# on top of the saddr-form loads: each GEMM load segment's two closing waits merged into one s_waitcnt vmcnt(8) lgkmcnt(0) (one instruction less between the last wait and the barrier), 36 segments
# baseline (speedup 1.0000x reference)
; #define PG8_STAGE(bufoff, gbase, voff) do { _Pragma("unroll") for (int _i = 0; _i < 2; ++_i) \
;         __builtin_amdgcn_global_load_lds((const unsigned*)((const char*)(gbase) + (voff)[_i]), (PG8_LAS unsigned*)(lds + (bufoff) + ldsw + _i * 8192), 16, 0, 0); } while (0)
; #define PG8_LDA(dst, b, h) do { _Pragma("unroll") for (int m = 0; m < 4; ++m) _Pragma("unroll") for (int k = 0; k < 2; ++k) dst[m][k] = *(const PG8_LAS bf16x8*)(lds + PG8_SA(b, h) + aoff + m * 2048 + k * 1024); } while (0)
; #define PG8_LDB(dst, b, h) do { _Pragma("unroll") for (int n = 0; n < 2; ++n) _Pragma("unroll") for (int k = 0; k < 2; ++k) dst[n][k] = *(const PG8_LAS bf16x8*)(lds + PG8_SB(b, h) + boff + n * 2048 + k * 1024); } while (0)
; #define PG8_MMA(ai, bj, At, Bt) do { __builtin_amdgcn_s_setprio(1); _Pragma("unroll") for (int m = 0; m < 4; ++m) _Pragma("unroll") for (int n = 0; n < 2; ++n) _Pragma("unroll") for (int k = 0; k < 2; ++k) \
;         acc[ai][bj][m][n] = __builtin_amdgcn_mfma_f32_16x16x32_bf16(Bt[n][k], At[m][k], acc[ai][bj][m][n], 0, 0, 0); __builtin_amdgcn_s_setprio(0); } while (0)
; #define PG8_WAIT_V(n) asm volatile("s_waitcnt vmcnt(" #n ")" ::: "memory")
; #define PG8_WAIT_L(n) asm volatile("s_waitcnt lgkmcnt(" #n ")" ::: "memory")
; template <class Epi, class Sched, bool ALIGN_EPI = false, bool SP2 = false>
; __device__ __forceinline__ void gemm_phase(PG8_LAS unsigned char* lds, const Gemm g, const Sched& S, const Epi& E) {
;     ...
;             const bool last = (t == nt - 2);
;             const char* a1 = cA + (size_t)(t + 1) * kstep;
;             const char* a2 = last ? nA : cA + (size_t)(t + 2) * kstep; const char* b2 = last ? nB : cB + (size_t)(t + 2) * kstep;
;             const char* a3 = a2 + kstep; const char* b3 = b2 + kstep;
;             if (last && has_next) S.a_ready(nxt);
;             if constexpr (SP2) {
;             PG8_LDB(B0, 0, 0); PG8_LDB(B1, 0, 1); PG8_SCHED; PG8_LDA(At, 0, 0); PG8_STAGE(PG8_SA(1, 1), a1 + hstep, voffA);
;             PG8_WAIT_V(8); PG8_WAIT_L(0); PG8_BAR; PG8_MMA(0, 0, At, B0); PG8_MMA(0, 1, At, B1); PG8_BAR; PG8_SCHED;
;             PG8_LDA(At, 0, 1); PG8_STAGE(PG8_SB(0, 0), b2, voffB); PG8_STAGE(PG8_SB(0, 1), b2 + hstep, voffB); PG8_STAGE(PG8_SA(0, 0), a2, voffA);
;             PG8_WAIT_V(8); PG8_WAIT_L(0); PG8_BAR; PG8_MMA(1, 0, At, B0); PG8_MMA(1, 1, At, B1); PG8_BAR; PG8_SCHED;
.LBB0_66:
	s_add_u32 s61, s90, 0xfffc0080
	s_addc_u32 s72, s91, -1
	s_add_i32 s73, 0, 0x10000
	s_cmp_eq_u32 s80, 12
	s_cselect_b32 s95, s47, s72
	s_cselect_b32 s94, vcc_lo, s61
	v_add_u32_e32 v147, s73, v139
	s_cselect_b32 s93, s45, s7
	s_cselect_b32 s92, vcc_hi, s4
	s_add_i32 s61, 0, 0x14000
	ds_read_b128 v[170:173], v147
	ds_read_b128 v[174:177], v147 offset:1024
	ds_read_b128 v[178:181], v147 offset:2048
	ds_read_b128 v[182:185], v147 offset:3072
	v_add_u32_e32 v147, s61, v139
	ds_read_b128 v[196:199], v147
	ds_read_b128 v[200:203], v147 offset:1024
	ds_read_b128 v[204:207], v147 offset:2048
	ds_read_b128 v[208:211], v147 offset:3072
	s_add_i32 m0, s8, 0xc000
	ds_read_b128 v[212:215], v143
	ds_read_b128 v[216:219], v143 offset:1024
	ds_read_b128 v[220:223], v143 offset:2048
	ds_read_b128 v[224:227], v143 offset:3072
	ds_read_b128 v[228:231], v143 offset:4096
	ds_read_b128 v[232:235], v143 offset:5120
	ds_read_b128 v[236:239], v143 offset:6144
	ds_read_b128 v[240:243], v143 offset:7168
	global_load_lds_dwordx4 v150, s[90:91]
	s_add_i32 m0, s8, 0xe000
	s_nop 0
	global_load_lds_dwordx4 v148, s[90:91]
	s_waitcnt vmcnt(8) lgkmcnt(0)
	s_barrier
	v_mfma_f32_16x16x32_bf16 v[126:129], v[170:173], v[212:215], v[126:129]
	v_mfma_f32_16x16x32_bf16 v[122:125], v[178:181], v[212:215], v[122:125]
	v_mfma_f32_16x16x32_bf16 v[110:113], v[170:173], v[220:223], v[110:113]
	v_mfma_f32_16x16x32_bf16 v[106:109], v[178:181], v[220:223], v[106:109]
	v_mfma_f32_16x16x32_bf16 v[94:97], v[170:173], v[228:231], v[94:97]
	v_mfma_f32_16x16x32_bf16 v[90:93], v[178:181], v[228:231], v[90:93]
	v_mfma_f32_16x16x32_bf16 v[78:81], v[170:173], v[236:239], v[78:81]
	v_mfma_f32_16x16x32_bf16 v[74:77], v[178:181], v[236:239], v[74:77]
	v_mfma_f32_16x16x32_bf16 v[126:129], v[174:177], v[216:219], v[126:129]
	v_mfma_f32_16x16x32_bf16 v[122:125], v[182:185], v[216:219], v[122:125]
	v_mfma_f32_16x16x32_bf16 v[110:113], v[174:177], v[224:227], v[110:113]
	v_mfma_f32_16x16x32_bf16 v[106:109], v[182:185], v[224:227], v[106:109]
	v_mfma_f32_16x16x32_bf16 v[94:97], v[174:177], v[232:235], v[94:97]
	v_mfma_f32_16x16x32_bf16 v[90:93], v[182:185], v[232:235], v[90:93]
	v_mfma_f32_16x16x32_bf16 v[78:81], v[174:177], v[240:243], v[78:81]
	v_mfma_f32_16x16x32_bf16 v[74:77], v[182:185], v[240:243], v[74:77]
	v_mfma_f32_16x16x32_bf16 v[118:121], v[196:199], v[212:215], v[118:121]
	v_mfma_f32_16x16x32_bf16 v[114:117], v[204:207], v[212:215], v[114:117]
	v_mfma_f32_16x16x32_bf16 v[102:105], v[196:199], v[220:223], v[102:105]
	v_mfma_f32_16x16x32_bf16 v[98:101], v[204:207], v[220:223], v[98:101]
	v_mfma_f32_16x16x32_bf16 v[86:89], v[196:199], v[228:231], v[86:89]
	v_mfma_f32_16x16x32_bf16 v[82:85], v[204:207], v[228:231], v[82:85]
	v_mfma_f32_16x16x32_bf16 v[70:73], v[196:199], v[236:239], v[70:73]
	v_mfma_f32_16x16x32_bf16 v[66:69], v[204:207], v[236:239], v[66:69]
	v_mfma_f32_16x16x32_bf16 v[118:121], v[200:203], v[216:219], v[118:121]
	v_mfma_f32_16x16x32_bf16 v[114:117], v[208:211], v[216:219], v[114:117]
	v_mfma_f32_16x16x32_bf16 v[102:105], v[200:203], v[224:227], v[102:105]
	v_mfma_f32_16x16x32_bf16 v[98:101], v[208:211], v[224:227], v[98:101]
	v_mfma_f32_16x16x32_bf16 v[86:89], v[200:203], v[232:235], v[86:89]
	v_mfma_f32_16x16x32_bf16 v[82:85], v[208:211], v[232:235], v[82:85]
	v_mfma_f32_16x16x32_bf16 v[70:73], v[200:203], v[240:243], v[70:73]
	v_mfma_f32_16x16x32_bf16 v[66:69], v[208:211], v[240:243], v[66:69]
	s_barrier
	s_add_i32 s72, s73, s5
	v_lshl_add_u64 v[160:161], s[92:93], 0, v[132:133]
	s_mov_b32 m0, s72
	ds_read_b128 v[212:215], v143 offset:16384
	ds_read_b128 v[216:219], v143 offset:17408
	ds_read_b128 v[220:223], v143 offset:18432
	ds_read_b128 v[224:227], v143 offset:19456
	ds_read_b128 v[228:231], v143 offset:20480
	ds_read_b128 v[232:235], v143 offset:21504
	ds_read_b128 v[236:239], v143 offset:22528
	ds_read_b128 v[240:243], v143 offset:23552
	global_load_lds_dwordx4 v[160:161], off
	s_add_i32 m0, s72, 0x2000
	s_add_u32 s76, s92, 0x40000
	v_lshl_add_u64 v[244:245], s[92:93], 0, v[136:137]
	s_addc_u32 s77, s93, 0
	s_add_i32 s61, s61, s5
	global_load_lds_dwordx4 v[244:245], off
	s_mov_b32 m0, s61
	v_lshl_add_u64 v[248:249], s[94:95], 0, v[134:135]
	global_load_lds_dwordx4 v132, s[76:77]
	s_add_i32 m0, s61, 0x2000
	s_nop 0
	global_load_lds_dwordx4 v136, s[76:77]
	v_lshl_add_u64 v[246:247], s[94:95], 0, v[130:131]
	s_mov_b32 m0, s8
	s_nop 0
	global_load_lds_dwordx4 v[246:247], off
	s_mov_b32 m0, s9
	s_nop 0
	global_load_lds_dwordx4 v[248:249], off
	s_waitcnt vmcnt(8) lgkmcnt(0)
	s_barrier
; #define PG8_STAGE(bufoff, gbase, voff) do { _Pragma("unroll") for (int _i = 0; _i < 2; ++_i) \
;         __builtin_amdgcn_global_load_lds((const unsigned*)((const char*)(gbase) + (voff)[_i]), (PG8_LAS unsigned*)(lds + (bufoff) + ldsw + _i * 8192), 16, 0, 0); } while (0)
; #define PG8_LDA(dst, b, h) do { _Pragma("unroll") for (int m = 0; m < 4; ++m) _Pragma("unroll") for (int k = 0; k < 2; ++k) dst[m][k] = *(const PG8_LAS bf16x8*)(lds + PG8_SA(b, h) + aoff + m * 2048 + k * 1024); } while (0)
; #define PG8_LDB(dst, b, h) do { _Pragma("unroll") for (int n = 0; n < 2; ++n) _Pragma("unroll") for (int k = 0; k < 2; ++k) dst[n][k] = *(const PG8_LAS bf16x8*)(lds + PG8_SB(b, h) + boff + n * 2048 + k * 1024); } while (0)
; #define PG8_MMA(ai, bj, At, Bt) do { __builtin_amdgcn_s_setprio(1); _Pragma("unroll") for (int m = 0; m < 4; ++m) _Pragma("unroll") for (int n = 0; n < 2; ++n) _Pragma("unroll") for (int k = 0; k < 2; ++k) \
;         acc[ai][bj][m][n] = __builtin_amdgcn_mfma_f32_16x16x32_bf16(Bt[n][k], At[m][k], acc[ai][bj][m][n], 0, 0, 0); __builtin_amdgcn_s_setprio(0); } while (0)
; #define PG8_WAIT_V(n) asm volatile("s_waitcnt vmcnt(" #n ")" ::: "memory")
; #define PG8_WAIT_L(n) asm volatile("s_waitcnt lgkmcnt(" #n ")" ::: "memory")
; #define PG8_BAR __builtin_amdgcn_s_barrier()
; #define PG8_SCHED __builtin_amdgcn_sched_barrier(0)
; template <class Epi, class Sched, bool ALIGN_EPI = false, bool SP2 = false>
; __device__ __forceinline__ void gemm_phase(PG8_LAS unsigned char* lds, const Gemm g, const Sched& S, const Epi& E) {
;     ...
;             PG8_WAIT_V(8); PG8_WAIT_L(0); PG8_BAR; PG8_MMA(1, 0, At, B0); PG8_MMA(1, 1, At, B1); PG8_BAR; PG8_SCHED;
;             PG8_LDB(B0, 1, 0); PG8_LDB(B1, 1, 1); PG8_SCHED; PG8_LDA(At, 1, 0); PG8_STAGE(PG8_SA(0, 1), a2 + hstep, voffA);
;             PG8_WAIT_V(8); PG8_WAIT_L(0); PG8_BAR; PG8_MMA(0, 0, At, B0); PG8_MMA(0, 1, At, B1); PG8_BAR; PG8_SCHED;
	v_mfma_f32_16x16x32_bf16 v[62:65], v[170:173], v[212:215], v[62:65]
	v_mfma_f32_16x16x32_bf16 v[58:61], v[178:181], v[212:215], v[58:61]
	v_mfma_f32_16x16x32_bf16 v[50:53], v[170:173], v[220:223], v[50:53]
	v_mfma_f32_16x16x32_bf16 v[42:45], v[178:181], v[220:223], v[42:45]
	v_mfma_f32_16x16x32_bf16 v[34:37], v[170:173], v[228:231], v[34:37]
	v_mfma_f32_16x16x32_bf16 v[24:27], v[178:181], v[228:231], v[24:27]
	v_mfma_f32_16x16x32_bf16 v[16:19], v[170:173], v[236:239], v[16:19]
	v_mfma_f32_16x16x32_bf16 v[8:11], v[178:181], v[236:239], v[8:11]
	v_mfma_f32_16x16x32_bf16 v[62:65], v[174:177], v[216:219], v[62:65]
	v_mfma_f32_16x16x32_bf16 v[58:61], v[182:185], v[216:219], v[58:61]
	v_mfma_f32_16x16x32_bf16 v[50:53], v[174:177], v[224:227], v[50:53]
	v_mfma_f32_16x16x32_bf16 v[42:45], v[182:185], v[224:227], v[42:45]
	v_mfma_f32_16x16x32_bf16 v[34:37], v[174:177], v[232:235], v[34:37]
	v_mfma_f32_16x16x32_bf16 v[24:27], v[182:185], v[232:235], v[24:27]
	v_mfma_f32_16x16x32_bf16 v[16:19], v[174:177], v[240:243], v[16:19]
	v_mfma_f32_16x16x32_bf16 v[8:11], v[182:185], v[240:243], v[8:11]
	v_mfma_f32_16x16x32_bf16 v[54:57], v[196:199], v[212:215], v[54:57]
	v_mfma_f32_16x16x32_bf16 v[46:49], v[204:207], v[212:215], v[46:49]
	v_mfma_f32_16x16x32_bf16 v[38:41], v[196:199], v[220:223], v[38:41]
	v_mfma_f32_16x16x32_bf16 v[28:31], v[204:207], v[220:223], v[28:31]
	v_mfma_f32_16x16x32_bf16 v[20:23], v[196:199], v[228:231], v[20:23]
	v_mfma_f32_16x16x32_bf16 v[12:15], v[204:207], v[228:231], v[12:15]
	v_mfma_f32_16x16x32_bf16 v[4:7], v[196:199], v[236:239], v[4:7]
	v_mfma_f32_16x16x32_bf16 v[0:3], v[204:207], v[236:239], v[0:3]
	v_mfma_f32_16x16x32_bf16 v[54:57], v[200:203], v[216:219], v[54:57]
	v_mfma_f32_16x16x32_bf16 v[46:49], v[208:211], v[216:219], v[46:49]
	v_mfma_f32_16x16x32_bf16 v[38:41], v[200:203], v[224:227], v[38:41]
	v_mfma_f32_16x16x32_bf16 v[28:31], v[208:211], v[224:227], v[28:31]
	v_mfma_f32_16x16x32_bf16 v[20:23], v[200:203], v[232:235], v[20:23]
	v_mfma_f32_16x16x32_bf16 v[12:15], v[208:211], v[232:235], v[12:15]
	v_mfma_f32_16x16x32_bf16 v[4:7], v[200:203], v[240:243], v[4:7]
	v_mfma_f32_16x16x32_bf16 v[0:3], v[208:211], v[240:243], v[0:3]
	s_barrier
	s_add_i32 s61, 0, 0x18000
	v_add_u32_e32 v147, s61, v139
	s_add_i32 s72, 0, 0x1c000
	ds_read_b128 v[170:173], v147
	ds_read_b128 v[174:177], v147 offset:1024
	ds_read_b128 v[178:181], v147 offset:2048
	ds_read_b128 v[182:185], v147 offset:3072
	v_add_u32_e32 v147, s72, v139
	ds_read_b128 v[196:199], v147
	ds_read_b128 v[200:203], v147 offset:1024
	ds_read_b128 v[204:207], v147 offset:2048
	ds_read_b128 v[208:211], v147 offset:3072
	s_add_u32 s76, s94, 0x40000
	s_addc_u32 s77, s95, 0
	s_mov_b32 m0, s89
	ds_read_b128 v[212:215], v143 offset:32768
	ds_read_b128 v[216:219], v143 offset:33792
	ds_read_b128 v[220:223], v143 offset:34816
	ds_read_b128 v[224:227], v143 offset:35840
	ds_read_b128 v[228:231], v143 offset:36864
	ds_read_b128 v[232:235], v143 offset:37888
	ds_read_b128 v[236:239], v143 offset:38912
	ds_read_b128 v[240:243], v143 offset:39936
	global_load_lds_dwordx4 v130, s[76:77]
	s_mov_b32 m0, s96
	s_nop 0
	global_load_lds_dwordx4 v134, s[76:77]
	s_waitcnt vmcnt(8) lgkmcnt(0)
	s_barrier
	v_mfma_f32_16x16x32_bf16 v[126:129], v[170:173], v[212:215], v[126:129]
	v_mfma_f32_16x16x32_bf16 v[122:125], v[178:181], v[212:215], v[122:125]
	v_mfma_f32_16x16x32_bf16 v[110:113], v[170:173], v[220:223], v[110:113]
	v_mfma_f32_16x16x32_bf16 v[106:109], v[178:181], v[220:223], v[106:109]
	v_mfma_f32_16x16x32_bf16 v[94:97], v[170:173], v[228:231], v[94:97]
	v_mfma_f32_16x16x32_bf16 v[90:93], v[178:181], v[228:231], v[90:93]
	v_mfma_f32_16x16x32_bf16 v[78:81], v[170:173], v[236:239], v[78:81]
	v_mfma_f32_16x16x32_bf16 v[74:77], v[178:181], v[236:239], v[74:77]
	v_mfma_f32_16x16x32_bf16 v[126:129], v[174:177], v[216:219], v[126:129]
	v_mfma_f32_16x16x32_bf16 v[122:125], v[182:185], v[216:219], v[122:125]
	v_mfma_f32_16x16x32_bf16 v[110:113], v[174:177], v[224:227], v[110:113]
	v_mfma_f32_16x16x32_bf16 v[106:109], v[182:185], v[224:227], v[106:109]
	v_mfma_f32_16x16x32_bf16 v[94:97], v[174:177], v[232:235], v[94:97]
	v_mfma_f32_16x16x32_bf16 v[90:93], v[182:185], v[232:235], v[90:93]
	v_mfma_f32_16x16x32_bf16 v[78:81], v[174:177], v[240:243], v[78:81]
	v_mfma_f32_16x16x32_bf16 v[74:77], v[182:185], v[240:243], v[74:77]
	v_mfma_f32_16x16x32_bf16 v[118:121], v[196:199], v[212:215], v[118:121]
	v_mfma_f32_16x16x32_bf16 v[114:117], v[204:207], v[212:215], v[114:117]
	v_mfma_f32_16x16x32_bf16 v[102:105], v[196:199], v[220:223], v[102:105]
	v_mfma_f32_16x16x32_bf16 v[98:101], v[204:207], v[220:223], v[98:101]
	v_mfma_f32_16x16x32_bf16 v[86:89], v[196:199], v[228:231], v[86:89]
	v_mfma_f32_16x16x32_bf16 v[82:85], v[204:207], v[228:231], v[82:85]
	v_mfma_f32_16x16x32_bf16 v[70:73], v[196:199], v[236:239], v[70:73]
	v_mfma_f32_16x16x32_bf16 v[66:69], v[204:207], v[236:239], v[66:69]
	v_mfma_f32_16x16x32_bf16 v[118:121], v[200:203], v[216:219], v[118:121]
	v_mfma_f32_16x16x32_bf16 v[114:117], v[208:211], v[216:219], v[114:117]
	v_mfma_f32_16x16x32_bf16 v[102:105], v[200:203], v[224:227], v[102:105]
	v_mfma_f32_16x16x32_bf16 v[98:101], v[208:211], v[224:227], v[98:101]
	v_mfma_f32_16x16x32_bf16 v[86:89], v[200:203], v[232:235], v[86:89]
	v_mfma_f32_16x16x32_bf16 v[82:85], v[208:211], v[232:235], v[82:85]
	v_mfma_f32_16x16x32_bf16 v[70:73], v[200:203], v[240:243], v[70:73]
	v_mfma_f32_16x16x32_bf16 v[66:69], v[208:211], v[240:243], v[66:69]
	s_barrier
; #define PG8_STAGE(bufoff, gbase, voff) do { _Pragma("unroll") for (int _i = 0; _i < 2; ++_i) \
;         __builtin_amdgcn_global_load_lds((const unsigned*)((const char*)(gbase) + (voff)[_i]), (PG8_LAS unsigned*)(lds + (bufoff) + ldsw + _i * 8192), 16, 0, 0); } while (0)
; #define PG8_LDA(dst, b, h) do { _Pragma("unroll") for (int m = 0; m < 4; ++m) _Pragma("unroll") for (int k = 0; k < 2; ++k) dst[m][k] = *(const PG8_LAS bf16x8*)(lds + PG8_SA(b, h) + aoff + m * 2048 + k * 1024); } while (0)
; #define PG8_MMA(ai, bj, At, Bt) do { __builtin_amdgcn_s_setprio(1); _Pragma("unroll") for (int m = 0; m < 4; ++m) _Pragma("unroll") for (int n = 0; n < 2; ++n) _Pragma("unroll") for (int k = 0; k < 2; ++k) \
;         acc[ai][bj][m][n] = __builtin_amdgcn_mfma_f32_16x16x32_bf16(Bt[n][k], At[m][k], acc[ai][bj][m][n], 0, 0, 0); __builtin_amdgcn_s_setprio(0); } while (0)
; #define PG8_WAIT_V(n) asm volatile("s_waitcnt vmcnt(" #n ")" ::: "memory")
; #define PG8_WAIT_L(n) asm volatile("s_waitcnt lgkmcnt(" #n ")" ::: "memory")
; #define PG8_BAR __builtin_amdgcn_s_barrier()
; #define PG8_SCHED __builtin_amdgcn_sched_barrier(0)
; template <class Epi, class Sched, bool ALIGN_EPI = false, bool SP2 = false>
; __device__ __forceinline__ void gemm_phase(PG8_LAS unsigned char* lds, const Gemm g, const Sched& S, const Epi& E) {
;     ...
;             PG8_LDA(At, 1, 1); PG8_STAGE(PG8_SB(1, 0), b3, voffB); PG8_STAGE(PG8_SB(1, 1), b3 + hstep, voffB); PG8_STAGE(PG8_SA(1, 0), a3, voffA);
;             PG8_WAIT_V(8); PG8_WAIT_L(0); PG8_BAR; PG8_MMA(1, 0, At, B0); PG8_MMA(1, 1, At, B1); PG8_BAR; PG8_SCHED;
;     ...
;         if constexpr (ALIGN_EPI) { if (wr == 0) PG8_BAR; }
	s_add_i32 s61, s61, s5
	v_lshl_add_u64 v[160:161], v[160:161], 0, s[34:35]
	s_mov_b32 m0, s61
	ds_read_b128 v[212:215], v143 offset:49152
	ds_read_b128 v[216:219], v143 offset:50176
	ds_read_b128 v[220:223], v143 offset:51200
	ds_read_b128 v[224:227], v143 offset:52224
	ds_read_b128 v[228:231], v143 offset:53248
	ds_read_b128 v[232:235], v143 offset:54272
	ds_read_b128 v[236:239], v143 offset:55296
	ds_read_b128 v[240:243], v143 offset:56320
	global_load_lds_dwordx4 v[160:161], off
	s_add_i32 m0, s61, 0x2000
	s_add_u32 s76, s92, 0x40080
	v_lshl_add_u64 v[160:161], v[244:245], 0, s[34:35]
	s_addc_u32 s77, s93, 0
	s_add_i32 s61, s72, s5
	global_load_lds_dwordx4 v[160:161], off
	s_mov_b32 m0, s61
	s_nop 0
	global_load_lds_dwordx4 v132, s[76:77]
	s_add_i32 m0, s61, 0x2000
	s_nop 0
	global_load_lds_dwordx4 v136, s[76:77]
	v_lshl_add_u64 v[160:161], v[246:247], 0, s[34:35]
	s_mov_b32 m0, s0
	s_nop 0
	global_load_lds_dwordx4 v[160:161], off
	v_lshl_add_u64 v[160:161], v[248:249], 0, s[34:35]
	s_mov_b32 m0, s97
	s_nop 0
	global_load_lds_dwordx4 v[160:161], off
	s_waitcnt vmcnt(8) lgkmcnt(0)
	s_barrier
	v_mfma_f32_16x16x32_bf16 v[62:65], v[170:173], v[212:215], v[62:65]
	v_mfma_f32_16x16x32_bf16 v[58:61], v[178:181], v[212:215], v[58:61]
	v_mfma_f32_16x16x32_bf16 v[50:53], v[170:173], v[220:223], v[50:53]
	v_mfma_f32_16x16x32_bf16 v[42:45], v[178:181], v[220:223], v[42:45]
	v_mfma_f32_16x16x32_bf16 v[34:37], v[170:173], v[228:231], v[34:37]
	v_mfma_f32_16x16x32_bf16 v[24:27], v[178:181], v[228:231], v[24:27]
	v_mfma_f32_16x16x32_bf16 v[16:19], v[170:173], v[236:239], v[16:19]
	v_mfma_f32_16x16x32_bf16 v[8:11], v[178:181], v[236:239], v[8:11]
	v_mfma_f32_16x16x32_bf16 v[62:65], v[174:177], v[216:219], v[62:65]
	v_mfma_f32_16x16x32_bf16 v[58:61], v[182:185], v[216:219], v[58:61]
	v_mfma_f32_16x16x32_bf16 v[50:53], v[174:177], v[224:227], v[50:53]
	v_mfma_f32_16x16x32_bf16 v[42:45], v[182:185], v[224:227], v[42:45]
	v_mfma_f32_16x16x32_bf16 v[34:37], v[174:177], v[232:235], v[34:37]
	v_mfma_f32_16x16x32_bf16 v[24:27], v[182:185], v[232:235], v[24:27]
	v_mfma_f32_16x16x32_bf16 v[16:19], v[174:177], v[240:243], v[16:19]
	v_mfma_f32_16x16x32_bf16 v[8:11], v[182:185], v[240:243], v[8:11]
	v_mfma_f32_16x16x32_bf16 v[54:57], v[196:199], v[212:215], v[54:57]
	v_mfma_f32_16x16x32_bf16 v[46:49], v[204:207], v[212:215], v[46:49]
	v_mfma_f32_16x16x32_bf16 v[38:41], v[196:199], v[220:223], v[38:41]
	v_mfma_f32_16x16x32_bf16 v[28:31], v[204:207], v[220:223], v[28:31]
	v_mfma_f32_16x16x32_bf16 v[20:23], v[196:199], v[228:231], v[20:23]
	v_mfma_f32_16x16x32_bf16 v[12:15], v[204:207], v[228:231], v[12:15]
	v_mfma_f32_16x16x32_bf16 v[4:7], v[196:199], v[236:239], v[4:7]
	v_mfma_f32_16x16x32_bf16 v[0:3], v[204:207], v[236:239], v[0:3]
	v_mfma_f32_16x16x32_bf16 v[54:57], v[200:203], v[216:219], v[54:57]
	v_mfma_f32_16x16x32_bf16 v[46:49], v[208:211], v[216:219], v[46:49]
	v_mfma_f32_16x16x32_bf16 v[38:41], v[200:203], v[224:227], v[38:41]
	v_mfma_f32_16x16x32_bf16 v[28:31], v[208:211], v[224:227], v[28:31]
	v_mfma_f32_16x16x32_bf16 v[20:23], v[200:203], v[232:235], v[20:23]
	v_mfma_f32_16x16x32_bf16 v[12:15], v[208:211], v[232:235], v[12:15]
	v_mfma_f32_16x16x32_bf16 v[4:7], v[200:203], v[240:243], v[4:7]
	v_mfma_f32_16x16x32_bf16 v[0:3], v[208:211], v[240:243], v[0:3]
	s_barrier
	s_add_i32 s80, s80, 2
	s_add_u32 s4, s4, 0x100
	s_addc_u32 s7, s7, 0
	s_add_u32 s90, s90, 0x100
	s_addc_u32 s91, s91, 0
	s_cmp_gt_u32 s80, 13
	s_cbranch_scc0 .LBB0_66
	s_and_b64 vcc, exec, s[38:39]
	s_cbranch_vccz .LBB0_69
	s_barrier

; #define PG8_STAGE(bufoff, gbase, voff) do { _Pragma("unroll") for (int _i = 0; _i < 2; ++_i) \
;         __builtin_amdgcn_global_load_lds((const unsigned*)((const char*)(gbase) + (voff)[_i]), (PG8_LAS unsigned*)(lds + (bufoff) + ldsw + _i * 8192), 16, 0, 0); } while (0)
; #define PG8_LDA(dst, b, h) do { _Pragma("unroll") for (int m = 0; m < 4; ++m) _Pragma("unroll") for (int k = 0; k < 2; ++k) dst[m][k] = *(const PG8_LAS bf16x8*)(lds + PG8_SA(b, h) + aoff + m * 2048 + k * 1024); } while (0)
; #define PG8_LDB(dst, b, h) do { _Pragma("unroll") for (int n = 0; n < 2; ++n) _Pragma("unroll") for (int k = 0; k < 2; ++k) dst[n][k] = *(const PG8_LAS bf16x8*)(lds + PG8_SB(b, h) + boff + n * 2048 + k * 1024); } while (0)
; #define PG8_MMA(ai, bj, At, Bt) do { __builtin_amdgcn_s_setprio(1); _Pragma("unroll") for (int m = 0; m < 4; ++m) _Pragma("unroll") for (int n = 0; n < 2; ++n) _Pragma("unroll") for (int k = 0; k < 2; ++k) \
;         acc[ai][bj][m][n] = __builtin_amdgcn_mfma_f32_16x16x32_bf16(Bt[n][k], At[m][k], acc[ai][bj][m][n], 0, 0, 0); __builtin_amdgcn_s_setprio(0); } while (0)
; #define PG8_WAIT_V(n) asm volatile("s_waitcnt vmcnt(" #n ")" ::: "memory")
; #define PG8_WAIT_L(n) asm volatile("s_waitcnt lgkmcnt(" #n ")" ::: "memory")
; template <class Epi, class Sched, bool ALIGN_EPI = false, bool SP2 = false>
; __device__ __forceinline__ void gemm_phase(PG8_LAS unsigned char* lds, const Gemm g, const Sched& S, const Epi& E) {
;     ...
;             const bool last = (t == nt - 2);
;             const char* a1 = cA + (size_t)(t + 1) * kstep;
;             const char* a2 = last ? nA : cA + (size_t)(t + 2) * kstep; const char* b2 = last ? nB : cB + (size_t)(t + 2) * kstep;
;             const char* a3 = a2 + kstep; const char* b3 = b2 + kstep;
;             if (last && has_next) S.a_ready(nxt);
;             if constexpr (SP2) {
;             PG8_LDB(B0, 0, 0); PG8_LDB(B1, 0, 1); PG8_SCHED; PG8_LDA(At, 0, 0); PG8_STAGE(PG8_SA(1, 1), a1 + hstep, voffA);
;             PG8_WAIT_V(8); PG8_WAIT_L(0); PG8_BAR; PG8_MMA(0, 0, At, B0); PG8_MMA(0, 1, At, B1); PG8_BAR; PG8_SCHED;
;             PG8_LDA(At, 0, 1); PG8_STAGE(PG8_SB(0, 0), b2, voffB); PG8_STAGE(PG8_SB(0, 1), b2 + hstep, voffB); PG8_STAGE(PG8_SA(0, 0), a2, voffA);
;             PG8_WAIT_V(8); PG8_WAIT_L(0); PG8_BAR; PG8_MMA(1, 0, At, B0); PG8_MMA(1, 1, At, B1); PG8_BAR; PG8_SCHED;
.LBB0_91:
	s_add_u32 s48, s46, 0xfffc0080
	s_addc_u32 s49, s47, -1
	s_add_i32 s61, 0, 0x10000
	s_cmp_eq_u32 s80, 12
	s_cselect_b32 s51, s89, s49
	s_cselect_b32 s50, vcc_lo, s48
	s_cselect_b32 s49, s87, s7
	s_cselect_b32 s48, vcc_hi, s5
	s_add_i32 s72, 0, 0x14000
	v_add_u32_e32 v110, s61, v170
	v_add_u32_e32 v173, s72, v170
	ds_read_b128 v[98:101], v110
	ds_read_b128 v[102:105], v110 offset:1024
	ds_read_b128 v[106:109], v110 offset:2048
	ds_read_b128 v[110:113], v110 offset:3072
	ds_read_b128 v[158:161], v173
	ds_read_b128 v[174:177], v173 offset:1024
	ds_read_b128 v[178:181], v173 offset:2048
	ds_read_b128 v[182:185], v173 offset:3072
	s_add_i32 m0, s9, 0xc000
	ds_read_b128 v[196:199], v172
	ds_read_b128 v[200:203], v172 offset:1024
	ds_read_b128 v[204:207], v172 offset:2048
	ds_read_b128 v[208:211], v172 offset:3072
	ds_read_b128 v[212:215], v172 offset:4096
	ds_read_b128 v[216:219], v172 offset:5120
	ds_read_b128 v[220:223], v172 offset:6144
	ds_read_b128 v[224:227], v172 offset:7168
	global_load_lds_dwordx4 v156, s[46:47]
	s_add_i32 m0, s9, 0xe000
	s_nop 0
	global_load_lds_dwordx4 v154, s[46:47]
	s_waitcnt vmcnt(8) lgkmcnt(0)
	s_barrier
	v_mfma_f32_16x16x32_bf16 v[142:145], v[98:101], v[196:199], v[142:145]
	v_mfma_f32_16x16x32_bf16 v[138:141], v[106:109], v[196:199], v[138:141]
	v_mfma_f32_16x16x32_bf16 v[126:129], v[98:101], v[204:207], v[126:129]
	v_mfma_f32_16x16x32_bf16 v[122:125], v[106:109], v[204:207], v[122:125]
	v_mfma_f32_16x16x32_bf16 v[94:97], v[98:101], v[212:215], v[94:97]
	v_mfma_f32_16x16x32_bf16 v[90:93], v[106:109], v[212:215], v[90:93]
	v_mfma_f32_16x16x32_bf16 v[78:81], v[98:101], v[220:223], v[78:81]
	v_mfma_f32_16x16x32_bf16 v[74:77], v[106:109], v[220:223], v[74:77]
	v_mfma_f32_16x16x32_bf16 v[142:145], v[102:105], v[200:203], v[142:145]
	v_mfma_f32_16x16x32_bf16 v[138:141], v[110:113], v[200:203], v[138:141]
	v_mfma_f32_16x16x32_bf16 v[126:129], v[102:105], v[208:211], v[126:129]
	v_mfma_f32_16x16x32_bf16 v[122:125], v[110:113], v[208:211], v[122:125]
	v_mfma_f32_16x16x32_bf16 v[94:97], v[102:105], v[216:219], v[94:97]
	v_mfma_f32_16x16x32_bf16 v[90:93], v[110:113], v[216:219], v[90:93]
	v_mfma_f32_16x16x32_bf16 v[78:81], v[102:105], v[224:227], v[78:81]
	v_mfma_f32_16x16x32_bf16 v[74:77], v[110:113], v[224:227], v[74:77]
	v_mfma_f32_16x16x32_bf16 v[134:137], v[158:161], v[196:199], v[134:137]
	v_mfma_f32_16x16x32_bf16 v[130:133], v[178:181], v[196:199], v[130:133]
	v_mfma_f32_16x16x32_bf16 v[118:121], v[158:161], v[204:207], v[118:121]
	v_mfma_f32_16x16x32_bf16 v[114:117], v[178:181], v[204:207], v[114:117]
	v_mfma_f32_16x16x32_bf16 v[86:89], v[158:161], v[212:215], v[86:89]
	v_mfma_f32_16x16x32_bf16 v[82:85], v[178:181], v[212:215], v[82:85]
	v_mfma_f32_16x16x32_bf16 v[70:73], v[158:161], v[220:223], v[70:73]
	v_mfma_f32_16x16x32_bf16 v[66:69], v[178:181], v[220:223], v[66:69]
	v_mfma_f32_16x16x32_bf16 v[134:137], v[174:177], v[200:203], v[134:137]
	v_mfma_f32_16x16x32_bf16 v[130:133], v[182:185], v[200:203], v[130:133]
	v_mfma_f32_16x16x32_bf16 v[118:121], v[174:177], v[208:211], v[118:121]
	v_mfma_f32_16x16x32_bf16 v[114:117], v[182:185], v[208:211], v[114:117]
	v_mfma_f32_16x16x32_bf16 v[86:89], v[174:177], v[216:219], v[86:89]
	v_mfma_f32_16x16x32_bf16 v[82:85], v[182:185], v[216:219], v[82:85]
	v_mfma_f32_16x16x32_bf16 v[70:73], v[174:177], v[224:227], v[70:73]
	v_mfma_f32_16x16x32_bf16 v[66:69], v[182:185], v[224:227], v[66:69]
	s_barrier
	s_add_i32 s61, s61, s8
	v_lshl_add_u64 v[228:229], s[48:49], 0, v[148:149]
	s_mov_b32 m0, s61
	ds_read_b128 v[196:199], v172 offset:16384
	ds_read_b128 v[200:203], v172 offset:17408
	ds_read_b128 v[204:207], v172 offset:18432
	ds_read_b128 v[208:211], v172 offset:19456
	ds_read_b128 v[212:215], v172 offset:20480
	ds_read_b128 v[216:219], v172 offset:21504
	ds_read_b128 v[220:223], v172 offset:22528
	ds_read_b128 v[224:227], v172 offset:23552
	global_load_lds_dwordx4 v[228:229], off
	s_add_i32 m0, s61, 0x2000
	s_add_u32 s76, s48, 0x40000
	v_lshl_add_u64 v[230:231], s[48:49], 0, v[152:153]
	s_addc_u32 s77, s49, 0
	s_add_i32 s61, s72, s8
	global_load_lds_dwordx4 v[230:231], off
	s_mov_b32 m0, s61
	v_lshl_add_u64 v[234:235], s[50:51], 0, v[150:151]
	global_load_lds_dwordx4 v148, s[76:77]
	s_add_i32 m0, s61, 0x2000
	s_nop 0
	global_load_lds_dwordx4 v152, s[76:77]
	v_lshl_add_u64 v[232:233], s[50:51], 0, v[146:147]
	s_mov_b32 m0, s9
	s_nop 0
	global_load_lds_dwordx4 v[232:233], off
	s_mov_b32 m0, s96
	s_nop 0
	global_load_lds_dwordx4 v[234:235], off
	s_waitcnt vmcnt(8) lgkmcnt(0)
	s_barrier
	v_mfma_f32_16x16x32_bf16 v[62:65], v[98:101], v[196:199], v[62:65]
	v_mfma_f32_16x16x32_bf16 v[58:61], v[106:109], v[196:199], v[58:61]
	v_mfma_f32_16x16x32_bf16 v[50:53], v[98:101], v[204:207], v[50:53]
	v_mfma_f32_16x16x32_bf16 v[42:45], v[106:109], v[204:207], v[42:45]
	v_mfma_f32_16x16x32_bf16 v[34:37], v[98:101], v[212:215], v[34:37]
	v_mfma_f32_16x16x32_bf16 v[24:27], v[106:109], v[212:215], v[24:27]
	v_mfma_f32_16x16x32_bf16 v[12:15], v[98:101], v[220:223], v[12:15]
	v_mfma_f32_16x16x32_bf16 v[8:11], v[106:109], v[220:223], v[8:11]
	v_mfma_f32_16x16x32_bf16 v[62:65], v[102:105], v[200:203], v[62:65]
	v_mfma_f32_16x16x32_bf16 v[58:61], v[110:113], v[200:203], v[58:61]
	v_mfma_f32_16x16x32_bf16 v[50:53], v[102:105], v[208:211], v[50:53]
	v_mfma_f32_16x16x32_bf16 v[42:45], v[110:113], v[208:211], v[42:45]
	v_mfma_f32_16x16x32_bf16 v[34:37], v[102:105], v[216:219], v[34:37]
	v_mfma_f32_16x16x32_bf16 v[24:27], v[110:113], v[216:219], v[24:27]
	v_mfma_f32_16x16x32_bf16 v[12:15], v[102:105], v[224:227], v[12:15]
	v_mfma_f32_16x16x32_bf16 v[8:11], v[110:113], v[224:227], v[8:11]
	v_mfma_f32_16x16x32_bf16 v[54:57], v[158:161], v[196:199], v[54:57]
	v_mfma_f32_16x16x32_bf16 v[46:49], v[178:181], v[196:199], v[46:49]
	v_mfma_f32_16x16x32_bf16 v[38:41], v[158:161], v[204:207], v[38:41]
	v_mfma_f32_16x16x32_bf16 v[28:31], v[178:181], v[204:207], v[28:31]
	v_mfma_f32_16x16x32_bf16 v[20:23], v[158:161], v[212:215], v[20:23]
	v_mfma_f32_16x16x32_bf16 v[16:19], v[178:181], v[212:215], v[16:19]
	v_mfma_f32_16x16x32_bf16 v[4:7], v[158:161], v[220:223], v[4:7]
	v_mfma_f32_16x16x32_bf16 v[0:3], v[178:181], v[220:223], v[0:3]
	v_mfma_f32_16x16x32_bf16 v[54:57], v[174:177], v[200:203], v[54:57]
	v_mfma_f32_16x16x32_bf16 v[46:49], v[182:185], v[200:203], v[46:49]
	v_mfma_f32_16x16x32_bf16 v[38:41], v[174:177], v[208:211], v[38:41]
	v_mfma_f32_16x16x32_bf16 v[28:31], v[182:185], v[208:211], v[28:31]
	v_mfma_f32_16x16x32_bf16 v[20:23], v[174:177], v[216:219], v[20:23]
	v_mfma_f32_16x16x32_bf16 v[16:19], v[182:185], v[216:219], v[16:19]
	v_mfma_f32_16x16x32_bf16 v[4:7], v[174:177], v[224:227], v[4:7]
	v_mfma_f32_16x16x32_bf16 v[0:3], v[182:185], v[224:227], v[0:3]
	s_barrier
; #define PG8_STAGE(bufoff, gbase, voff) do { _Pragma("unroll") for (int _i = 0; _i < 2; ++_i) \
;         __builtin_amdgcn_global_load_lds((const unsigned*)((const char*)(gbase) + (voff)[_i]), (PG8_LAS unsigned*)(lds + (bufoff) + ldsw + _i * 8192), 16, 0, 0); } while (0)
; #define PG8_LDA(dst, b, h) do { _Pragma("unroll") for (int m = 0; m < 4; ++m) _Pragma("unroll") for (int k = 0; k < 2; ++k) dst[m][k] = *(const PG8_LAS bf16x8*)(lds + PG8_SA(b, h) + aoff + m * 2048 + k * 1024); } while (0)
; #define PG8_LDB(dst, b, h) do { _Pragma("unroll") for (int n = 0; n < 2; ++n) _Pragma("unroll") for (int k = 0; k < 2; ++k) dst[n][k] = *(const PG8_LAS bf16x8*)(lds + PG8_SB(b, h) + boff + n * 2048 + k * 1024); } while (0)
; #define PG8_MMA(ai, bj, At, Bt) do { __builtin_amdgcn_s_setprio(1); _Pragma("unroll") for (int m = 0; m < 4; ++m) _Pragma("unroll") for (int n = 0; n < 2; ++n) _Pragma("unroll") for (int k = 0; k < 2; ++k) \
;         acc[ai][bj][m][n] = __builtin_amdgcn_mfma_f32_16x16x32_bf16(Bt[n][k], At[m][k], acc[ai][bj][m][n], 0, 0, 0); __builtin_amdgcn_s_setprio(0); } while (0)
; #define PG8_WAIT_V(n) asm volatile("s_waitcnt vmcnt(" #n ")" ::: "memory")
; #define PG8_WAIT_L(n) asm volatile("s_waitcnt lgkmcnt(" #n ")" ::: "memory")
; #define PG8_BAR __builtin_amdgcn_s_barrier()
; #define PG8_SCHED __builtin_amdgcn_sched_barrier(0)
; template <class Epi, class Sched, bool ALIGN_EPI = false, bool SP2 = false>
; __device__ __forceinline__ void gemm_phase(PG8_LAS unsigned char* lds, const Gemm g, const Sched& S, const Epi& E) {
;     ...
;             PG8_LDB(B0, 1, 0); PG8_LDB(B1, 1, 1); PG8_SCHED; PG8_LDA(At, 1, 0); PG8_STAGE(PG8_SA(0, 1), a2 + hstep, voffA);
;             PG8_WAIT_V(8); PG8_WAIT_L(0); PG8_BAR; PG8_MMA(0, 0, At, B0); PG8_MMA(0, 1, At, B1); PG8_BAR; PG8_SCHED;
;             PG8_LDA(At, 1, 1); PG8_STAGE(PG8_SB(1, 0), b3, voffB); PG8_STAGE(PG8_SB(1, 1), b3 + hstep, voffB); PG8_STAGE(PG8_SA(1, 0), a3, voffA);
;             PG8_WAIT_V(8); PG8_WAIT_L(0); PG8_BAR; PG8_MMA(1, 0, At, B0); PG8_MMA(1, 1, At, B1); PG8_BAR; PG8_SCHED;
	s_add_i32 s61, 0, 0x18000
	s_add_i32 s72, 0, 0x1c000
	v_add_u32_e32 v110, s61, v170
	v_add_u32_e32 v173, s72, v170
	ds_read_b128 v[98:101], v110
	ds_read_b128 v[102:105], v110 offset:1024
	ds_read_b128 v[106:109], v110 offset:2048
	ds_read_b128 v[110:113], v110 offset:3072
	ds_read_b128 v[158:161], v173
	ds_read_b128 v[174:177], v173 offset:1024
	ds_read_b128 v[178:181], v173 offset:2048
	ds_read_b128 v[182:185], v173 offset:3072
	s_add_u32 s50, s50, 0x40000
	s_addc_u32 s51, s51, 0
	s_mov_b32 m0, s97
	ds_read_b128 v[196:199], v172 offset:32768
	ds_read_b128 v[200:203], v172 offset:33792
	ds_read_b128 v[204:207], v172 offset:34816
	ds_read_b128 v[208:211], v172 offset:35840
	ds_read_b128 v[212:215], v172 offset:36864
	ds_read_b128 v[216:219], v172 offset:37888
	ds_read_b128 v[220:223], v172 offset:38912
	ds_read_b128 v[224:227], v172 offset:39936
	global_load_lds_dwordx4 v146, s[50:51]
	s_mov_b32 m0, s2
	s_nop 0
	global_load_lds_dwordx4 v150, s[50:51]
	s_waitcnt vmcnt(8) lgkmcnt(0)
	s_barrier
	v_mfma_f32_16x16x32_bf16 v[142:145], v[98:101], v[196:199], v[142:145]
	v_mfma_f32_16x16x32_bf16 v[138:141], v[106:109], v[196:199], v[138:141]
	v_mfma_f32_16x16x32_bf16 v[126:129], v[98:101], v[204:207], v[126:129]
	v_mfma_f32_16x16x32_bf16 v[122:125], v[106:109], v[204:207], v[122:125]
	v_mfma_f32_16x16x32_bf16 v[94:97], v[98:101], v[212:215], v[94:97]
	v_mfma_f32_16x16x32_bf16 v[90:93], v[106:109], v[212:215], v[90:93]
	v_mfma_f32_16x16x32_bf16 v[78:81], v[98:101], v[220:223], v[78:81]
	v_mfma_f32_16x16x32_bf16 v[74:77], v[106:109], v[220:223], v[74:77]
	v_mfma_f32_16x16x32_bf16 v[142:145], v[102:105], v[200:203], v[142:145]
	v_mfma_f32_16x16x32_bf16 v[138:141], v[110:113], v[200:203], v[138:141]
	v_mfma_f32_16x16x32_bf16 v[126:129], v[102:105], v[208:211], v[126:129]
	v_mfma_f32_16x16x32_bf16 v[122:125], v[110:113], v[208:211], v[122:125]
	v_mfma_f32_16x16x32_bf16 v[94:97], v[102:105], v[216:219], v[94:97]
	v_mfma_f32_16x16x32_bf16 v[90:93], v[110:113], v[216:219], v[90:93]
	v_mfma_f32_16x16x32_bf16 v[78:81], v[102:105], v[224:227], v[78:81]
	v_mfma_f32_16x16x32_bf16 v[74:77], v[110:113], v[224:227], v[74:77]
	v_mfma_f32_16x16x32_bf16 v[134:137], v[158:161], v[196:199], v[134:137]
	v_mfma_f32_16x16x32_bf16 v[130:133], v[178:181], v[196:199], v[130:133]
	v_mfma_f32_16x16x32_bf16 v[118:121], v[158:161], v[204:207], v[118:121]
	v_mfma_f32_16x16x32_bf16 v[114:117], v[178:181], v[204:207], v[114:117]
	v_mfma_f32_16x16x32_bf16 v[86:89], v[158:161], v[212:215], v[86:89]
	v_mfma_f32_16x16x32_bf16 v[82:85], v[178:181], v[212:215], v[82:85]
	v_mfma_f32_16x16x32_bf16 v[70:73], v[158:161], v[220:223], v[70:73]
	v_mfma_f32_16x16x32_bf16 v[66:69], v[178:181], v[220:223], v[66:69]
	v_mfma_f32_16x16x32_bf16 v[134:137], v[174:177], v[200:203], v[134:137]
	v_mfma_f32_16x16x32_bf16 v[130:133], v[182:185], v[200:203], v[130:133]
	v_mfma_f32_16x16x32_bf16 v[118:121], v[174:177], v[208:211], v[118:121]
	v_mfma_f32_16x16x32_bf16 v[114:117], v[182:185], v[208:211], v[114:117]
	v_mfma_f32_16x16x32_bf16 v[86:89], v[174:177], v[216:219], v[86:89]
	v_mfma_f32_16x16x32_bf16 v[82:85], v[182:185], v[216:219], v[82:85]
	v_mfma_f32_16x16x32_bf16 v[70:73], v[174:177], v[224:227], v[70:73]
	v_mfma_f32_16x16x32_bf16 v[66:69], v[182:185], v[224:227], v[66:69]
	s_barrier
	s_add_i32 s50, s61, s8
	v_lshl_add_u64 v[228:229], v[228:229], 0, s[34:35]
	s_mov_b32 m0, s50
	ds_read_b128 v[196:199], v172 offset:49152
	ds_read_b128 v[200:203], v172 offset:50176
	ds_read_b128 v[204:207], v172 offset:51200
	ds_read_b128 v[208:211], v172 offset:52224
	ds_read_b128 v[212:215], v172 offset:53248
	ds_read_b128 v[216:219], v172 offset:54272
	ds_read_b128 v[220:223], v172 offset:55296
	ds_read_b128 v[224:227], v172 offset:56320
	global_load_lds_dwordx4 v[228:229], off
	s_add_i32 m0, s50, 0x2000
	s_add_u32 s48, s48, 0x40080
	v_lshl_add_u64 v[228:229], v[230:231], 0, s[34:35]
	s_addc_u32 s49, s49, 0
	s_add_i32 s50, s72, s8
	global_load_lds_dwordx4 v[228:229], off
	s_mov_b32 m0, s50
	s_nop 0
	global_load_lds_dwordx4 v148, s[48:49]
	s_add_i32 m0, s50, 0x2000
	s_nop 0
	global_load_lds_dwordx4 v152, s[48:49]
	v_lshl_add_u64 v[228:229], v[232:233], 0, s[34:35]
	s_mov_b32 m0, s0
	s_nop 0
	global_load_lds_dwordx4 v[228:229], off
	v_lshl_add_u64 v[228:229], v[234:235], 0, s[34:35]
	s_mov_b32 m0, s3
	s_nop 0
	global_load_lds_dwordx4 v[228:229], off
	s_waitcnt vmcnt(8) lgkmcnt(0)
	s_barrier
	v_mfma_f32_16x16x32_bf16 v[62:65], v[98:101], v[196:199], v[62:65]
	v_mfma_f32_16x16x32_bf16 v[58:61], v[106:109], v[196:199], v[58:61]
	v_mfma_f32_16x16x32_bf16 v[50:53], v[98:101], v[204:207], v[50:53]
	v_mfma_f32_16x16x32_bf16 v[42:45], v[106:109], v[204:207], v[42:45]
	v_mfma_f32_16x16x32_bf16 v[34:37], v[98:101], v[212:215], v[34:37]
	v_mfma_f32_16x16x32_bf16 v[24:27], v[106:109], v[212:215], v[24:27]
	v_mfma_f32_16x16x32_bf16 v[12:15], v[98:101], v[220:223], v[12:15]
	v_mfma_f32_16x16x32_bf16 v[8:11], v[106:109], v[220:223], v[8:11]
	v_mfma_f32_16x16x32_bf16 v[62:65], v[102:105], v[200:203], v[62:65]
	v_mfma_f32_16x16x32_bf16 v[58:61], v[110:113], v[200:203], v[58:61]
	v_mfma_f32_16x16x32_bf16 v[50:53], v[102:105], v[208:211], v[50:53]
	v_mfma_f32_16x16x32_bf16 v[42:45], v[110:113], v[208:211], v[42:45]
	v_mfma_f32_16x16x32_bf16 v[34:37], v[102:105], v[216:219], v[34:37]
	v_mfma_f32_16x16x32_bf16 v[24:27], v[110:113], v[216:219], v[24:27]
	v_mfma_f32_16x16x32_bf16 v[12:15], v[102:105], v[224:227], v[12:15]
	v_mfma_f32_16x16x32_bf16 v[8:11], v[110:113], v[224:227], v[8:11]
	v_mfma_f32_16x16x32_bf16 v[54:57], v[158:161], v[196:199], v[54:57]
	v_mfma_f32_16x16x32_bf16 v[46:49], v[178:181], v[196:199], v[46:49]
	v_mfma_f32_16x16x32_bf16 v[38:41], v[158:161], v[204:207], v[38:41]
	v_mfma_f32_16x16x32_bf16 v[28:31], v[178:181], v[204:207], v[28:31]
	v_mfma_f32_16x16x32_bf16 v[20:23], v[158:161], v[212:215], v[20:23]
	v_mfma_f32_16x16x32_bf16 v[16:19], v[178:181], v[212:215], v[16:19]
	v_mfma_f32_16x16x32_bf16 v[4:7], v[158:161], v[220:223], v[4:7]
	v_mfma_f32_16x16x32_bf16 v[0:3], v[178:181], v[220:223], v[0:3]
	v_mfma_f32_16x16x32_bf16 v[54:57], v[174:177], v[200:203], v[54:57]
	v_mfma_f32_16x16x32_bf16 v[46:49], v[182:185], v[200:203], v[46:49]
	v_mfma_f32_16x16x32_bf16 v[38:41], v[174:177], v[208:211], v[38:41]
	v_mfma_f32_16x16x32_bf16 v[28:31], v[182:185], v[208:211], v[28:31]
	v_mfma_f32_16x16x32_bf16 v[20:23], v[174:177], v[216:219], v[20:23]
	v_mfma_f32_16x16x32_bf16 v[16:19], v[182:185], v[216:219], v[16:19]
	v_mfma_f32_16x16x32_bf16 v[4:7], v[174:177], v[224:227], v[4:7]
	v_mfma_f32_16x16x32_bf16 v[0:3], v[182:185], v[224:227], v[0:3]
	s_barrier
	s_add_i32 s80, s80, 2
	s_add_u32 s5, s5, 0x100
	s_addc_u32 s7, s7, 0
	s_add_u32 s46, s46, 0x100
	s_addc_u32 s47, s47, 0
	s_cmp_gt_u32 s80, 13
	s_cbranch_scc0 .LBB0_91
	s_and_b64 vcc, exec, s[38:39]
	s_cbranch_vccz .LBB0_94
	s_barrier

; #define PG8_STAGE(bufoff, gbase, voff) do { _Pragma("unroll") for (int _i = 0; _i < 2; ++_i) \
;         __builtin_amdgcn_global_load_lds((const unsigned*)((const char*)(gbase) + (voff)[_i]), (PG8_LAS unsigned*)(lds + (bufoff) + ldsw + _i * 8192), 16, 0, 0); } while (0)
; #define PG8_LDA(dst, b, h) do { _Pragma("unroll") for (int m = 0; m < 4; ++m) _Pragma("unroll") for (int k = 0; k < 2; ++k) dst[m][k] = *(const PG8_LAS bf16x8*)(lds + PG8_SA(b, h) + aoff + m * 2048 + k * 1024); } while (0)
; #define PG8_LDB(dst, b, h) do { _Pragma("unroll") for (int n = 0; n < 2; ++n) _Pragma("unroll") for (int k = 0; k < 2; ++k) dst[n][k] = *(const PG8_LAS bf16x8*)(lds + PG8_SB(b, h) + boff + n * 2048 + k * 1024); } while (0)
; #define PG8_MMA(ai, bj, At, Bt) do { __builtin_amdgcn_s_setprio(1); _Pragma("unroll") for (int m = 0; m < 4; ++m) _Pragma("unroll") for (int n = 0; n < 2; ++n) _Pragma("unroll") for (int k = 0; k < 2; ++k) \
;         acc[ai][bj][m][n] = __builtin_amdgcn_mfma_f32_16x16x32_bf16(Bt[n][k], At[m][k], acc[ai][bj][m][n], 0, 0, 0); __builtin_amdgcn_s_setprio(0); } while (0)
; #define PG8_WAIT_V(n) asm volatile("s_waitcnt vmcnt(" #n ")" ::: "memory")
; #define PG8_BAR __builtin_amdgcn_s_barrier()
; template <class Epi, class Sched, bool ALIGN_EPI = false, bool SP2 = false>
; __device__ __forceinline__ void gemm_phase(PG8_LAS unsigned char* lds, const Gemm g, const Sched& S, const Epi& E) {
;     ...
;         for (int t = 0; t < nt; t += 2) {
;             const bool last = (t == nt - 2);
;             const char* a1 = cA + (size_t)(t + 1) * kstep;
;             const char* a2 = last ? nA : cA + (size_t)(t + 2) * kstep; const char* b2 = last ? nB : cB + (size_t)(t + 2) * kstep;
;             const char* a3 = a2 + kstep; const char* b3 = b2 + kstep;
;             if (last && has_next) S.a_ready(nxt);
;             if constexpr (SP2) {
;             PG8_LDB(B0, 0, 0); PG8_LDB(B1, 0, 1); PG8_SCHED; PG8_LDA(At, 0, 0); PG8_STAGE(PG8_SA(1, 1), a1 + hstep, voffA);
;             PG8_WAIT_V(8); PG8_WAIT_L(0); PG8_BAR; PG8_MMA(0, 0, At, B0); PG8_MMA(0, 1, At, B1); PG8_BAR; PG8_SCHED;
;             PG8_LDA(At, 0, 1); PG8_STAGE(PG8_SB(0, 0), b2, voffB); PG8_STAGE(PG8_SB(0, 1), b2 + hstep, voffB); PG8_STAGE(PG8_SA(0, 0), a2, voffA);
;             PG8_WAIT_V(8); PG8_WAIT_L(0); PG8_BAR; PG8_MMA(1, 0, At, B0); PG8_MMA(1, 1, At, B1); PG8_BAR; PG8_SCHED;
.LBB0_118:
	s_add_u32 s48, s46, 0xfffc0080
	s_addc_u32 s49, s47, -1
	s_add_i32 s61, 0, 0x10000
	s_cmp_eq_u32 vcc_lo, 12
	s_cselect_b32 s51, s5, s49
	s_cselect_b32 s50, s7, s48
	v_add_u32_e32 v150, s61, v145
	s_cselect_b32 s49, s8, s91
	s_cselect_b32 s48, s45, s89
	s_add_i32 s72, 0, 0x14000
	ds_read_b128 v[174:177], v150
	ds_read_b128 v[178:181], v150 offset:1024
	ds_read_b128 v[182:185], v150 offset:2048
	ds_read_b128 v[196:199], v150 offset:3072
	v_add_u32_e32 v150, s72, v145
	ds_read_b128 v[200:203], v150
	ds_read_b128 v[204:207], v150 offset:1024
	ds_read_b128 v[208:211], v150 offset:2048
	ds_read_b128 v[212:215], v150 offset:3072
	s_add_i32 m0, s39, 0xc000
	ds_read_b128 v[216:219], v149
	ds_read_b128 v[220:223], v149 offset:1024
	ds_read_b128 v[224:227], v149 offset:2048
	ds_read_b128 v[228:231], v149 offset:3072
	ds_read_b128 v[232:235], v149 offset:4096
	ds_read_b128 v[236:239], v149 offset:5120
	ds_read_b128 v[240:243], v149 offset:6144
	ds_read_b128 v[244:247], v149 offset:7168
	global_load_lds_dwordx4 v142, s[46:47]
	s_add_i32 m0, s39, 0xe000
	s_nop 0
	global_load_lds_dwordx4 v140, s[46:47]
	s_waitcnt vmcnt(8) lgkmcnt(0)
	s_barrier
	v_mfma_f32_16x16x32_bf16 v[126:129], v[174:177], v[216:219], v[126:129]
	v_mfma_f32_16x16x32_bf16 v[122:125], v[182:185], v[216:219], v[122:125]
	v_mfma_f32_16x16x32_bf16 v[110:113], v[174:177], v[224:227], v[110:113]
	v_mfma_f32_16x16x32_bf16 v[106:109], v[182:185], v[224:227], v[106:109]
	v_mfma_f32_16x16x32_bf16 v[94:97], v[174:177], v[232:235], v[94:97]
	v_mfma_f32_16x16x32_bf16 v[90:93], v[182:185], v[232:235], v[90:93]
	v_mfma_f32_16x16x32_bf16 v[78:81], v[174:177], v[240:243], v[78:81]
	v_mfma_f32_16x16x32_bf16 v[74:77], v[182:185], v[240:243], v[74:77]
	v_mfma_f32_16x16x32_bf16 v[126:129], v[178:181], v[220:223], v[126:129]
	v_mfma_f32_16x16x32_bf16 v[122:125], v[196:199], v[220:223], v[122:125]
	v_mfma_f32_16x16x32_bf16 v[110:113], v[178:181], v[228:231], v[110:113]
	v_mfma_f32_16x16x32_bf16 v[106:109], v[196:199], v[228:231], v[106:109]
	v_mfma_f32_16x16x32_bf16 v[94:97], v[178:181], v[236:239], v[94:97]
	v_mfma_f32_16x16x32_bf16 v[90:93], v[196:199], v[236:239], v[90:93]
	v_mfma_f32_16x16x32_bf16 v[78:81], v[178:181], v[244:247], v[78:81]
	v_mfma_f32_16x16x32_bf16 v[74:77], v[196:199], v[244:247], v[74:77]
	v_mfma_f32_16x16x32_bf16 v[118:121], v[200:203], v[216:219], v[118:121]
	v_mfma_f32_16x16x32_bf16 v[114:117], v[208:211], v[216:219], v[114:117]
	v_mfma_f32_16x16x32_bf16 v[102:105], v[200:203], v[224:227], v[102:105]
	v_mfma_f32_16x16x32_bf16 v[98:101], v[208:211], v[224:227], v[98:101]
	v_mfma_f32_16x16x32_bf16 v[86:89], v[200:203], v[232:235], v[86:89]
	v_mfma_f32_16x16x32_bf16 v[82:85], v[208:211], v[232:235], v[82:85]
	v_mfma_f32_16x16x32_bf16 v[70:73], v[200:203], v[240:243], v[70:73]
	v_mfma_f32_16x16x32_bf16 v[66:69], v[208:211], v[240:243], v[66:69]
	v_mfma_f32_16x16x32_bf16 v[118:121], v[204:207], v[220:223], v[118:121]
	v_mfma_f32_16x16x32_bf16 v[114:117], v[212:215], v[220:223], v[114:117]
	v_mfma_f32_16x16x32_bf16 v[102:105], v[204:207], v[228:231], v[102:105]
	v_mfma_f32_16x16x32_bf16 v[98:101], v[212:215], v[228:231], v[98:101]
	v_mfma_f32_16x16x32_bf16 v[86:89], v[204:207], v[236:239], v[86:89]
	v_mfma_f32_16x16x32_bf16 v[82:85], v[212:215], v[236:239], v[82:85]
	v_mfma_f32_16x16x32_bf16 v[70:73], v[204:207], v[244:247], v[70:73]
	v_mfma_f32_16x16x32_bf16 v[66:69], v[212:215], v[244:247], v[66:69]
	s_barrier
	s_add_i32 s61, s61, s38
	v_lshl_add_u64 v[150:151], s[48:49], 0, v[132:133]
	s_mov_b32 m0, s61
	ds_read_b128 v[216:219], v149 offset:16384
	ds_read_b128 v[220:223], v149 offset:17408
	ds_read_b128 v[224:227], v149 offset:18432
	ds_read_b128 v[228:231], v149 offset:19456
	ds_read_b128 v[232:235], v149 offset:20480
	ds_read_b128 v[236:239], v149 offset:21504
	ds_read_b128 v[240:243], v149 offset:22528
	ds_read_b128 v[244:247], v149 offset:23552
	global_load_lds_dwordx4 v[150:151], off
	s_add_i32 m0, s61, 0x2000
	s_add_u32 s80, s48, 0x40000
	v_lshl_add_u64 v[160:161], s[48:49], 0, v[136:137]
	s_addc_u32 s81, s49, 0
	s_add_i32 s61, s72, s38
	global_load_lds_dwordx4 v[160:161], off
	s_mov_b32 m0, s61
	v_lshl_add_u64 v[248:249], s[50:51], 0, v[134:135]
	global_load_lds_dwordx4 v132, s[80:81]
	s_add_i32 m0, s61, 0x2000
	s_nop 0
	global_load_lds_dwordx4 v136, s[80:81]
	v_lshl_add_u64 v[170:171], s[50:51], 0, v[130:131]
	s_mov_b32 m0, s39
	s_nop 0
	global_load_lds_dwordx4 v[170:171], off
	s_mov_b32 m0, s2
	s_nop 0
	global_load_lds_dwordx4 v[248:249], off
	s_waitcnt vmcnt(8) lgkmcnt(0)
	s_barrier
; #define PG8_STAGE(bufoff, gbase, voff) do { _Pragma("unroll") for (int _i = 0; _i < 2; ++_i) \
;         __builtin_amdgcn_global_load_lds((const unsigned*)((const char*)(gbase) + (voff)[_i]), (PG8_LAS unsigned*)(lds + (bufoff) + ldsw + _i * 8192), 16, 0, 0); } while (0)
; #define PG8_LDA(dst, b, h) do { _Pragma("unroll") for (int m = 0; m < 4; ++m) _Pragma("unroll") for (int k = 0; k < 2; ++k) dst[m][k] = *(const PG8_LAS bf16x8*)(lds + PG8_SA(b, h) + aoff + m * 2048 + k * 1024); } while (0)
; #define PG8_LDB(dst, b, h) do { _Pragma("unroll") for (int n = 0; n < 2; ++n) _Pragma("unroll") for (int k = 0; k < 2; ++k) dst[n][k] = *(const PG8_LAS bf16x8*)(lds + PG8_SB(b, h) + boff + n * 2048 + k * 1024); } while (0)
; #define PG8_MMA(ai, bj, At, Bt) do { __builtin_amdgcn_s_setprio(1); _Pragma("unroll") for (int m = 0; m < 4; ++m) _Pragma("unroll") for (int n = 0; n < 2; ++n) _Pragma("unroll") for (int k = 0; k < 2; ++k) \
;         acc[ai][bj][m][n] = __builtin_amdgcn_mfma_f32_16x16x32_bf16(Bt[n][k], At[m][k], acc[ai][bj][m][n], 0, 0, 0); __builtin_amdgcn_s_setprio(0); } while (0)
; #define PG8_WAIT_V(n) asm volatile("s_waitcnt vmcnt(" #n ")" ::: "memory")
; #define PG8_WAIT_L(n) asm volatile("s_waitcnt lgkmcnt(" #n ")" ::: "memory")
; #define PG8_BAR __builtin_amdgcn_s_barrier()
; #define PG8_SCHED __builtin_amdgcn_sched_barrier(0)
; template <class Epi, class Sched, bool ALIGN_EPI = false, bool SP2 = false>
; __device__ __forceinline__ void gemm_phase(PG8_LAS unsigned char* lds, const Gemm g, const Sched& S, const Epi& E) {
;     ...
;             PG8_WAIT_V(8); PG8_WAIT_L(0); PG8_BAR; PG8_MMA(1, 0, At, B0); PG8_MMA(1, 1, At, B1); PG8_BAR; PG8_SCHED;
;             PG8_LDB(B0, 1, 0); PG8_LDB(B1, 1, 1); PG8_SCHED; PG8_LDA(At, 1, 0); PG8_STAGE(PG8_SA(0, 1), a2 + hstep, voffA);
;             PG8_WAIT_V(8); PG8_WAIT_L(0); PG8_BAR; PG8_MMA(0, 0, At, B0); PG8_MMA(0, 1, At, B1); PG8_BAR; PG8_SCHED;
	v_mfma_f32_16x16x32_bf16 v[62:65], v[174:177], v[216:219], v[62:65]
	v_mfma_f32_16x16x32_bf16 v[58:61], v[182:185], v[216:219], v[58:61]
	v_mfma_f32_16x16x32_bf16 v[46:49], v[174:177], v[224:227], v[46:49]
	v_mfma_f32_16x16x32_bf16 v[42:45], v[182:185], v[224:227], v[42:45]
	v_mfma_f32_16x16x32_bf16 v[28:31], v[174:177], v[232:235], v[28:31]
	v_mfma_f32_16x16x32_bf16 v[24:27], v[182:185], v[232:235], v[24:27]
	v_mfma_f32_16x16x32_bf16 v[12:15], v[174:177], v[240:243], v[12:15]
	v_mfma_f32_16x16x32_bf16 v[8:11], v[182:185], v[240:243], v[8:11]
	v_mfma_f32_16x16x32_bf16 v[62:65], v[178:181], v[220:223], v[62:65]
	v_mfma_f32_16x16x32_bf16 v[58:61], v[196:199], v[220:223], v[58:61]
	v_mfma_f32_16x16x32_bf16 v[46:49], v[178:181], v[228:231], v[46:49]
	v_mfma_f32_16x16x32_bf16 v[42:45], v[196:199], v[228:231], v[42:45]
	v_mfma_f32_16x16x32_bf16 v[28:31], v[178:181], v[236:239], v[28:31]
	v_mfma_f32_16x16x32_bf16 v[24:27], v[196:199], v[236:239], v[24:27]
	v_mfma_f32_16x16x32_bf16 v[12:15], v[178:181], v[244:247], v[12:15]
	v_mfma_f32_16x16x32_bf16 v[8:11], v[196:199], v[244:247], v[8:11]
	v_mfma_f32_16x16x32_bf16 v[54:57], v[200:203], v[216:219], v[54:57]
	v_mfma_f32_16x16x32_bf16 v[50:53], v[208:211], v[216:219], v[50:53]
	v_mfma_f32_16x16x32_bf16 v[38:41], v[200:203], v[224:227], v[38:41]
	v_mfma_f32_16x16x32_bf16 v[34:37], v[208:211], v[224:227], v[34:37]
	v_mfma_f32_16x16x32_bf16 v[20:23], v[200:203], v[232:235], v[20:23]
	v_mfma_f32_16x16x32_bf16 v[16:19], v[208:211], v[232:235], v[16:19]
	v_mfma_f32_16x16x32_bf16 v[4:7], v[200:203], v[240:243], v[4:7]
	v_mfma_f32_16x16x32_bf16 v[0:3], v[208:211], v[240:243], v[0:3]
	v_mfma_f32_16x16x32_bf16 v[54:57], v[204:207], v[220:223], v[54:57]
	v_mfma_f32_16x16x32_bf16 v[50:53], v[212:215], v[220:223], v[50:53]
	v_mfma_f32_16x16x32_bf16 v[38:41], v[204:207], v[228:231], v[38:41]
	v_mfma_f32_16x16x32_bf16 v[34:37], v[212:215], v[228:231], v[34:37]
	v_mfma_f32_16x16x32_bf16 v[20:23], v[204:207], v[236:239], v[20:23]
	v_mfma_f32_16x16x32_bf16 v[16:19], v[212:215], v[236:239], v[16:19]
	v_mfma_f32_16x16x32_bf16 v[4:7], v[204:207], v[244:247], v[4:7]
	v_mfma_f32_16x16x32_bf16 v[0:3], v[212:215], v[244:247], v[0:3]
	s_barrier
	s_add_i32 s61, 0, 0x18000
	v_add_u32_e32 v153, s61, v145
	s_add_i32 s72, 0, 0x1c000
	ds_read_b128 v[174:177], v153
	ds_read_b128 v[178:181], v153 offset:1024
	ds_read_b128 v[182:185], v153 offset:2048
	ds_read_b128 v[196:199], v153 offset:3072
	v_add_u32_e32 v153, s72, v145
	ds_read_b128 v[200:203], v153
	ds_read_b128 v[204:207], v153 offset:1024
	ds_read_b128 v[208:211], v153 offset:2048
	ds_read_b128 v[212:215], v153 offset:3072
	s_add_u32 s50, s50, 0x40000
	s_addc_u32 s51, s51, 0
	s_mov_b32 m0, s3
	ds_read_b128 v[216:219], v149 offset:32768
	ds_read_b128 v[220:223], v149 offset:33792
	ds_read_b128 v[224:227], v149 offset:34816
	ds_read_b128 v[228:231], v149 offset:35840
	ds_read_b128 v[232:235], v149 offset:36864
	ds_read_b128 v[236:239], v149 offset:37888
	ds_read_b128 v[240:243], v149 offset:38912
	ds_read_b128 v[244:247], v149 offset:39936
	global_load_lds_dwordx4 v130, s[50:51]
	s_mov_b32 m0, s87
	s_nop 0
	global_load_lds_dwordx4 v134, s[50:51]
	s_waitcnt vmcnt(8) lgkmcnt(0)
	s_barrier
	v_mfma_f32_16x16x32_bf16 v[126:129], v[174:177], v[216:219], v[126:129]
	v_mfma_f32_16x16x32_bf16 v[122:125], v[182:185], v[216:219], v[122:125]
	v_mfma_f32_16x16x32_bf16 v[110:113], v[174:177], v[224:227], v[110:113]
	v_mfma_f32_16x16x32_bf16 v[106:109], v[182:185], v[224:227], v[106:109]
	v_mfma_f32_16x16x32_bf16 v[94:97], v[174:177], v[232:235], v[94:97]
	v_mfma_f32_16x16x32_bf16 v[90:93], v[182:185], v[232:235], v[90:93]
	v_mfma_f32_16x16x32_bf16 v[78:81], v[174:177], v[240:243], v[78:81]
	v_mfma_f32_16x16x32_bf16 v[74:77], v[182:185], v[240:243], v[74:77]
	v_mfma_f32_16x16x32_bf16 v[126:129], v[178:181], v[220:223], v[126:129]
	v_mfma_f32_16x16x32_bf16 v[122:125], v[196:199], v[220:223], v[122:125]
	v_mfma_f32_16x16x32_bf16 v[110:113], v[178:181], v[228:231], v[110:113]
	v_mfma_f32_16x16x32_bf16 v[106:109], v[196:199], v[228:231], v[106:109]
	v_mfma_f32_16x16x32_bf16 v[94:97], v[178:181], v[236:239], v[94:97]
	v_mfma_f32_16x16x32_bf16 v[90:93], v[196:199], v[236:239], v[90:93]
	v_mfma_f32_16x16x32_bf16 v[78:81], v[178:181], v[244:247], v[78:81]
	v_mfma_f32_16x16x32_bf16 v[74:77], v[196:199], v[244:247], v[74:77]
	v_mfma_f32_16x16x32_bf16 v[118:121], v[200:203], v[216:219], v[118:121]
	v_mfma_f32_16x16x32_bf16 v[114:117], v[208:211], v[216:219], v[114:117]
	v_mfma_f32_16x16x32_bf16 v[102:105], v[200:203], v[224:227], v[102:105]
	v_mfma_f32_16x16x32_bf16 v[98:101], v[208:211], v[224:227], v[98:101]
	v_mfma_f32_16x16x32_bf16 v[86:89], v[200:203], v[232:235], v[86:89]
	v_mfma_f32_16x16x32_bf16 v[82:85], v[208:211], v[232:235], v[82:85]
	v_mfma_f32_16x16x32_bf16 v[70:73], v[200:203], v[240:243], v[70:73]
	v_mfma_f32_16x16x32_bf16 v[66:69], v[208:211], v[240:243], v[66:69]
	v_mfma_f32_16x16x32_bf16 v[118:121], v[204:207], v[220:223], v[118:121]
	v_mfma_f32_16x16x32_bf16 v[114:117], v[212:215], v[220:223], v[114:117]
	v_mfma_f32_16x16x32_bf16 v[102:105], v[204:207], v[228:231], v[102:105]
	v_mfma_f32_16x16x32_bf16 v[98:101], v[212:215], v[228:231], v[98:101]
	v_mfma_f32_16x16x32_bf16 v[86:89], v[204:207], v[236:239], v[86:89]
	v_mfma_f32_16x16x32_bf16 v[82:85], v[212:215], v[236:239], v[82:85]
	v_mfma_f32_16x16x32_bf16 v[70:73], v[204:207], v[244:247], v[70:73]
	v_mfma_f32_16x16x32_bf16 v[66:69], v[212:215], v[244:247], v[66:69]
	s_barrier
; #define PG8_STAGE(bufoff, gbase, voff) do { _Pragma("unroll") for (int _i = 0; _i < 2; ++_i) \
;         __builtin_amdgcn_global_load_lds((const unsigned*)((const char*)(gbase) + (voff)[_i]), (PG8_LAS unsigned*)(lds + (bufoff) + ldsw + _i * 8192), 16, 0, 0); } while (0)
; #define PG8_LDA(dst, b, h) do { _Pragma("unroll") for (int m = 0; m < 4; ++m) _Pragma("unroll") for (int k = 0; k < 2; ++k) dst[m][k] = *(const PG8_LAS bf16x8*)(lds + PG8_SA(b, h) + aoff + m * 2048 + k * 1024); } while (0)
; #define PG8_MMA(ai, bj, At, Bt) do { __builtin_amdgcn_s_setprio(1); _Pragma("unroll") for (int m = 0; m < 4; ++m) _Pragma("unroll") for (int n = 0; n < 2; ++n) _Pragma("unroll") for (int k = 0; k < 2; ++k) \
;         acc[ai][bj][m][n] = __builtin_amdgcn_mfma_f32_16x16x32_bf16(Bt[n][k], At[m][k], acc[ai][bj][m][n], 0, 0, 0); __builtin_amdgcn_s_setprio(0); } while (0)
; #define PG8_WAIT_V(n) asm volatile("s_waitcnt vmcnt(" #n ")" ::: "memory")
; #define PG8_WAIT_L(n) asm volatile("s_waitcnt lgkmcnt(" #n ")" ::: "memory")
; #define PG8_BAR __builtin_amdgcn_s_barrier()
; #define PG8_SCHED __builtin_amdgcn_sched_barrier(0)
; template <class Epi, class Sched, bool ALIGN_EPI = false, bool SP2 = false>
; __device__ __forceinline__ void gemm_phase(PG8_LAS unsigned char* lds, const Gemm g, const Sched& S, const Epi& E) {
;     ...
;             PG8_LDA(At, 1, 1); PG8_STAGE(PG8_SB(1, 0), b3, voffB); PG8_STAGE(PG8_SB(1, 1), b3 + hstep, voffB); PG8_STAGE(PG8_SA(1, 0), a3, voffA);
;             PG8_WAIT_V(8); PG8_WAIT_L(0); PG8_BAR; PG8_MMA(1, 0, At, B0); PG8_MMA(1, 1, At, B1); PG8_BAR; PG8_SCHED;
	s_add_i32 s50, s61, s38
	v_lshl_add_u64 v[150:151], v[150:151], 0, s[34:35]
	s_mov_b32 m0, s50
	ds_read_b128 v[216:219], v149 offset:49152
	ds_read_b128 v[220:223], v149 offset:50176
	ds_read_b128 v[224:227], v149 offset:51200
	ds_read_b128 v[228:231], v149 offset:52224
	ds_read_b128 v[232:235], v149 offset:53248
	ds_read_b128 v[236:239], v149 offset:54272
	ds_read_b128 v[240:243], v149 offset:55296
	ds_read_b128 v[244:247], v149 offset:56320
	global_load_lds_dwordx4 v[150:151], off
	s_add_i32 m0, s50, 0x2000
	s_add_u32 s48, s48, 0x40080
	v_lshl_add_u64 v[150:151], v[160:161], 0, s[34:35]
	s_addc_u32 s49, s49, 0
	s_add_i32 s50, s72, s38
	global_load_lds_dwordx4 v[150:151], off
	s_mov_b32 m0, s50
	s_nop 0
	global_load_lds_dwordx4 v132, s[48:49]
	s_add_i32 m0, s50, 0x2000
	s_nop 0
	global_load_lds_dwordx4 v136, s[48:49]
	v_lshl_add_u64 v[150:151], v[170:171], 0, s[34:35]
	s_mov_b32 m0, s0
	s_nop 0
	global_load_lds_dwordx4 v[150:151], off
	v_lshl_add_u64 v[150:151], v[248:249], 0, s[34:35]
	s_mov_b32 m0, s86
	s_nop 0
	global_load_lds_dwordx4 v[150:151], off
	s_waitcnt vmcnt(8) lgkmcnt(0)
	s_barrier
	v_mfma_f32_16x16x32_bf16 v[62:65], v[174:177], v[216:219], v[62:65]
	v_mfma_f32_16x16x32_bf16 v[58:61], v[182:185], v[216:219], v[58:61]
	v_mfma_f32_16x16x32_bf16 v[46:49], v[174:177], v[224:227], v[46:49]
	v_mfma_f32_16x16x32_bf16 v[42:45], v[182:185], v[224:227], v[42:45]
	v_mfma_f32_16x16x32_bf16 v[28:31], v[174:177], v[232:235], v[28:31]
	v_mfma_f32_16x16x32_bf16 v[24:27], v[182:185], v[232:235], v[24:27]
	v_mfma_f32_16x16x32_bf16 v[12:15], v[174:177], v[240:243], v[12:15]
	v_mfma_f32_16x16x32_bf16 v[8:11], v[182:185], v[240:243], v[8:11]
	v_mfma_f32_16x16x32_bf16 v[62:65], v[178:181], v[220:223], v[62:65]
	v_mfma_f32_16x16x32_bf16 v[58:61], v[196:199], v[220:223], v[58:61]
	v_mfma_f32_16x16x32_bf16 v[46:49], v[178:181], v[228:231], v[46:49]
	v_mfma_f32_16x16x32_bf16 v[42:45], v[196:199], v[228:231], v[42:45]
	v_mfma_f32_16x16x32_bf16 v[28:31], v[178:181], v[236:239], v[28:31]
	v_mfma_f32_16x16x32_bf16 v[24:27], v[196:199], v[236:239], v[24:27]
	v_mfma_f32_16x16x32_bf16 v[12:15], v[178:181], v[244:247], v[12:15]
	v_mfma_f32_16x16x32_bf16 v[8:11], v[196:199], v[244:247], v[8:11]
	v_mfma_f32_16x16x32_bf16 v[54:57], v[200:203], v[216:219], v[54:57]
	v_mfma_f32_16x16x32_bf16 v[50:53], v[208:211], v[216:219], v[50:53]
	v_mfma_f32_16x16x32_bf16 v[38:41], v[200:203], v[224:227], v[38:41]
	v_mfma_f32_16x16x32_bf16 v[34:37], v[208:211], v[224:227], v[34:37]
	v_mfma_f32_16x16x32_bf16 v[20:23], v[200:203], v[232:235], v[20:23]
	v_mfma_f32_16x16x32_bf16 v[16:19], v[208:211], v[232:235], v[16:19]
	v_mfma_f32_16x16x32_bf16 v[4:7], v[200:203], v[240:243], v[4:7]
	v_mfma_f32_16x16x32_bf16 v[0:3], v[208:211], v[240:243], v[0:3]
	v_mfma_f32_16x16x32_bf16 v[54:57], v[204:207], v[220:223], v[54:57]
	v_mfma_f32_16x16x32_bf16 v[50:53], v[212:215], v[220:223], v[50:53]
	v_mfma_f32_16x16x32_bf16 v[38:41], v[204:207], v[228:231], v[38:41]
	v_mfma_f32_16x16x32_bf16 v[34:37], v[212:215], v[228:231], v[34:37]
	v_mfma_f32_16x16x32_bf16 v[20:23], v[204:207], v[236:239], v[20:23]
	v_mfma_f32_16x16x32_bf16 v[16:19], v[212:215], v[236:239], v[16:19]
	v_mfma_f32_16x16x32_bf16 v[4:7], v[204:207], v[244:247], v[4:7]
	v_mfma_f32_16x16x32_bf16 v[0:3], v[212:215], v[244:247], v[0:3]
	s_barrier
	s_add_i32 vcc_lo, vcc_lo, 2
	s_add_u32 s89, s89, 0x100
	s_addc_u32 s91, s91, 0
	s_add_u32 s46, s46, 0x100
	s_addc_u32 s47, s47, 0
	s_cmp_gt_u32 vcc_lo, 13
	s_cbranch_scc0 .LBB0_118
	v_readlane_b32 s46, v254, 51
	v_readlane_b32 s47, v254, 52
	s_and_b64 vcc, exec, s[46:47]
	s_cbranch_vccz .LBB0_121
	s_barrier

; #define PG8_STAGE(bufoff, gbase, voff) do { _Pragma("unroll") for (int _i = 0; _i < 2; ++_i) \
;         __builtin_amdgcn_global_load_lds((const unsigned*)((const char*)(gbase) + (voff)[_i]), (PG8_LAS unsigned*)(lds + (bufoff) + ldsw + _i * 8192), 16, 0, 0); } while (0)
; #define PG8_LDA(dst, b, h) do { _Pragma("unroll") for (int m = 0; m < 4; ++m) _Pragma("unroll") for (int k = 0; k < 2; ++k) dst[m][k] = *(const PG8_LAS bf16x8*)(lds + PG8_SA(b, h) + aoff + m * 2048 + k * 1024); } while (0)
; #define PG8_LDB(dst, b, h) do { _Pragma("unroll") for (int n = 0; n < 2; ++n) _Pragma("unroll") for (int k = 0; k < 2; ++k) dst[n][k] = *(const PG8_LAS bf16x8*)(lds + PG8_SB(b, h) + boff + n * 2048 + k * 1024); } while (0)
; #define PG8_MMA(ai, bj, At, Bt) do { __builtin_amdgcn_s_setprio(1); _Pragma("unroll") for (int m = 0; m < 4; ++m) _Pragma("unroll") for (int n = 0; n < 2; ++n) _Pragma("unroll") for (int k = 0; k < 2; ++k) \
;         acc[ai][bj][m][n] = __builtin_amdgcn_mfma_f32_16x16x32_bf16(Bt[n][k], At[m][k], acc[ai][bj][m][n], 0, 0, 0); __builtin_amdgcn_s_setprio(0); } while (0)
; #define PG8_WAIT_V(n) asm volatile("s_waitcnt vmcnt(" #n ")" ::: "memory")
; #define PG8_BAR __builtin_amdgcn_s_barrier()
; template <class Epi, class Sched, bool ALIGN_EPI = false, bool SP2 = false>
; __device__ __forceinline__ void gemm_phase(PG8_LAS unsigned char* lds, const Gemm g, const Sched& S, const Epi& E) {
;     ...
;         for (int t = 0; t < nt; t += 2) {
;             const bool last = (t == nt - 2);
;             const char* a1 = cA + (size_t)(t + 1) * kstep;
;             const char* a2 = last ? nA : cA + (size_t)(t + 2) * kstep; const char* b2 = last ? nB : cB + (size_t)(t + 2) * kstep;
;             const char* a3 = a2 + kstep; const char* b3 = b2 + kstep;
;             if (last && has_next) S.a_ready(nxt);
;             if constexpr (SP2) {
;             PG8_LDB(B0, 0, 0); PG8_LDB(B1, 0, 1); PG8_SCHED; PG8_LDA(At, 0, 0); PG8_STAGE(PG8_SA(1, 1), a1 + hstep, voffA);
;             PG8_WAIT_V(8); PG8_WAIT_L(0); PG8_BAR; PG8_MMA(0, 0, At, B0); PG8_MMA(0, 1, At, B1); PG8_BAR; PG8_SCHED;
;             PG8_LDA(At, 0, 1); PG8_STAGE(PG8_SB(0, 0), b2, voffB); PG8_STAGE(PG8_SB(0, 1), b2 + hstep, voffB); PG8_STAGE(PG8_SA(0, 0), a2, voffA);
;             PG8_WAIT_V(8); PG8_WAIT_L(0); PG8_BAR; PG8_MMA(1, 0, At, B0); PG8_MMA(1, 1, At, B1); PG8_BAR; PG8_SCHED;
.LBB0_145:
	s_add_u32 s48, s46, 0xfffc0080
	s_addc_u32 s49, s47, -1
	s_add_i32 s61, 0, 0x10000
	s_cmp_eq_u32 s80, 12
	s_cselect_b32 s51, s3, s49
	s_cselect_b32 s50, s45, s48
	s_cselect_b32 s49, s89, s7
	s_cselect_b32 s48, vcc_lo, vcc_hi
	s_add_i32 s72, 0, 0x14000
	v_add_u32_e32 v70, s61, v176
	v_add_u32_e32 v174, s72, v176
	ds_read_b128 v[50:53], v70
	ds_read_b128 v[54:57], v70 offset:1024
	ds_read_b128 v[66:69], v70 offset:2048
	ds_read_b128 v[70:73], v70 offset:3072
	ds_read_b128 v[158:161], v174
	ds_read_b128 v[170:173], v174 offset:1024
	ds_read_b128 v[180:183], v174 offset:2048
	ds_read_b128 v[196:199], v174 offset:3072
	s_add_i32 m0, s5, 0xc000
	ds_read_b128 v[200:203], v178
	ds_read_b128 v[204:207], v178 offset:1024
	ds_read_b128 v[208:211], v178 offset:2048
	ds_read_b128 v[212:215], v178 offset:3072
	ds_read_b128 v[216:219], v178 offset:4096
	ds_read_b128 v[220:223], v178 offset:5120
	ds_read_b128 v[224:227], v178 offset:6144
	ds_read_b128 v[228:231], v178 offset:7168
	global_load_lds_dwordx4 v156, s[46:47]
	s_add_i32 m0, s5, 0xe000
	s_nop 0
	global_load_lds_dwordx4 v154, s[46:47]
	s_waitcnt vmcnt(8) lgkmcnt(0)
	s_barrier
	v_mfma_f32_16x16x32_bf16 v[142:145], v[50:53], v[200:203], v[142:145]
	v_mfma_f32_16x16x32_bf16 v[138:141], v[66:69], v[200:203], v[138:141]
	v_mfma_f32_16x16x32_bf16 v[126:129], v[50:53], v[208:211], v[126:129]
	v_mfma_f32_16x16x32_bf16 v[122:125], v[66:69], v[208:211], v[122:125]
	v_mfma_f32_16x16x32_bf16 v[110:113], v[50:53], v[216:219], v[110:113]
	v_mfma_f32_16x16x32_bf16 v[106:109], v[66:69], v[216:219], v[106:109]
	v_mfma_f32_16x16x32_bf16 v[94:97], v[50:53], v[224:227], v[94:97]
	v_mfma_f32_16x16x32_bf16 v[90:93], v[66:69], v[224:227], v[90:93]
	v_mfma_f32_16x16x32_bf16 v[142:145], v[54:57], v[204:207], v[142:145]
	v_mfma_f32_16x16x32_bf16 v[138:141], v[70:73], v[204:207], v[138:141]
	v_mfma_f32_16x16x32_bf16 v[126:129], v[54:57], v[212:215], v[126:129]
	v_mfma_f32_16x16x32_bf16 v[122:125], v[70:73], v[212:215], v[122:125]
	v_mfma_f32_16x16x32_bf16 v[110:113], v[54:57], v[220:223], v[110:113]
	v_mfma_f32_16x16x32_bf16 v[106:109], v[70:73], v[220:223], v[106:109]
	v_mfma_f32_16x16x32_bf16 v[94:97], v[54:57], v[228:231], v[94:97]
	v_mfma_f32_16x16x32_bf16 v[90:93], v[70:73], v[228:231], v[90:93]
	v_mfma_f32_16x16x32_bf16 v[134:137], v[158:161], v[200:203], v[134:137]
	v_mfma_f32_16x16x32_bf16 v[130:133], v[180:183], v[200:203], v[130:133]
	v_mfma_f32_16x16x32_bf16 v[118:121], v[158:161], v[208:211], v[118:121]
	v_mfma_f32_16x16x32_bf16 v[114:117], v[180:183], v[208:211], v[114:117]
	v_mfma_f32_16x16x32_bf16 v[102:105], v[158:161], v[216:219], v[102:105]
	v_mfma_f32_16x16x32_bf16 v[98:101], v[180:183], v[216:219], v[98:101]
	v_mfma_f32_16x16x32_bf16 v[86:89], v[158:161], v[224:227], v[86:89]
	v_mfma_f32_16x16x32_bf16 v[82:85], v[180:183], v[224:227], v[82:85]
	v_mfma_f32_16x16x32_bf16 v[134:137], v[170:173], v[204:207], v[134:137]
	v_mfma_f32_16x16x32_bf16 v[130:133], v[196:199], v[204:207], v[130:133]
	v_mfma_f32_16x16x32_bf16 v[118:121], v[170:173], v[212:215], v[118:121]
	v_mfma_f32_16x16x32_bf16 v[114:117], v[196:199], v[212:215], v[114:117]
	v_mfma_f32_16x16x32_bf16 v[102:105], v[170:173], v[220:223], v[102:105]
	v_mfma_f32_16x16x32_bf16 v[98:101], v[196:199], v[220:223], v[98:101]
	v_mfma_f32_16x16x32_bf16 v[86:89], v[170:173], v[228:231], v[86:89]
	v_mfma_f32_16x16x32_bf16 v[82:85], v[196:199], v[228:231], v[82:85]
	s_barrier
	s_add_i32 s61, s61, s4
	v_lshl_add_u64 v[174:175], s[48:49], 0, v[148:149]
	s_mov_b32 m0, s61
	ds_read_b128 v[200:203], v178 offset:16384
	ds_read_b128 v[204:207], v178 offset:17408
	ds_read_b128 v[208:211], v178 offset:18432
	ds_read_b128 v[212:215], v178 offset:19456
	ds_read_b128 v[216:219], v178 offset:20480
	ds_read_b128 v[220:223], v178 offset:21504
	ds_read_b128 v[224:227], v178 offset:22528
	ds_read_b128 v[228:231], v178 offset:23552
	global_load_lds_dwordx4 v[174:175], off
	s_add_i32 m0, s61, 0x2000
	s_add_u32 s76, s48, 0x40000
	v_lshl_add_u64 v[184:185], s[48:49], 0, v[152:153]
	s_addc_u32 s77, s49, 0
	s_add_i32 s61, s72, s4
	global_load_lds_dwordx4 v[184:185], off
	s_mov_b32 m0, s61
	v_lshl_add_u64 v[234:235], s[50:51], 0, v[150:151]
	global_load_lds_dwordx4 v148, s[76:77]
	s_add_i32 m0, s61, 0x2000
	s_nop 0
	global_load_lds_dwordx4 v152, s[76:77]
	v_lshl_add_u64 v[232:233], s[50:51], 0, v[146:147]
	s_mov_b32 m0, s5
	s_nop 0
	global_load_lds_dwordx4 v[232:233], off
	s_mov_b32 m0, s91
	s_nop 0
	global_load_lds_dwordx4 v[234:235], off
	s_waitcnt vmcnt(8) lgkmcnt(0)
	s_barrier
	v_mfma_f32_16x16x32_bf16 v[78:81], v[50:53], v[200:203], v[78:81]
	v_mfma_f32_16x16x32_bf16 v[74:77], v[66:69], v[200:203], v[74:77]
	v_mfma_f32_16x16x32_bf16 v[46:49], v[50:53], v[208:211], v[46:49]
	v_mfma_f32_16x16x32_bf16 v[42:45], v[66:69], v[208:211], v[42:45]
	v_mfma_f32_16x16x32_bf16 v[28:31], v[50:53], v[216:219], v[28:31]
	v_mfma_f32_16x16x32_bf16 v[24:27], v[66:69], v[216:219], v[24:27]
	v_mfma_f32_16x16x32_bf16 v[12:15], v[50:53], v[224:227], v[12:15]
	v_mfma_f32_16x16x32_bf16 v[8:11], v[66:69], v[224:227], v[8:11]
	v_mfma_f32_16x16x32_bf16 v[78:81], v[54:57], v[204:207], v[78:81]
	v_mfma_f32_16x16x32_bf16 v[74:77], v[70:73], v[204:207], v[74:77]
	v_mfma_f32_16x16x32_bf16 v[46:49], v[54:57], v[212:215], v[46:49]
	v_mfma_f32_16x16x32_bf16 v[42:45], v[70:73], v[212:215], v[42:45]
	v_mfma_f32_16x16x32_bf16 v[28:31], v[54:57], v[220:223], v[28:31]
	v_mfma_f32_16x16x32_bf16 v[24:27], v[70:73], v[220:223], v[24:27]
	v_mfma_f32_16x16x32_bf16 v[12:15], v[54:57], v[228:231], v[12:15]
	v_mfma_f32_16x16x32_bf16 v[8:11], v[70:73], v[228:231], v[8:11]
	v_mfma_f32_16x16x32_bf16 v[38:41], v[158:161], v[208:211], v[38:41]
	v_mfma_f32_16x16x32_bf16 v[34:37], v[180:183], v[208:211], v[34:37]
	v_mfma_f32_16x16x32_bf16 v[20:23], v[158:161], v[216:219], v[20:23]
	v_mfma_f32_16x16x32_bf16 v[16:19], v[180:183], v[216:219], v[16:19]
	v_mfma_f32_16x16x32_bf16 v[4:7], v[158:161], v[224:227], v[4:7]
	v_mfma_f32_16x16x32_bf16 v[0:3], v[180:183], v[224:227], v[0:3]
	v_mfma_f32_16x16x32_bf16 v[50:53], v[158:161], v[200:203], v[62:65]
	v_mfma_f32_16x16x32_bf16 v[54:57], v[180:183], v[200:203], v[58:61]
	v_mfma_f32_16x16x32_bf16 v[38:41], v[170:173], v[212:215], v[38:41]
	v_mfma_f32_16x16x32_bf16 v[34:37], v[196:199], v[212:215], v[34:37]
	v_mfma_f32_16x16x32_bf16 v[20:23], v[170:173], v[220:223], v[20:23]
	v_mfma_f32_16x16x32_bf16 v[16:19], v[196:199], v[220:223], v[16:19]
	v_mfma_f32_16x16x32_bf16 v[4:7], v[170:173], v[228:231], v[4:7]
	v_mfma_f32_16x16x32_bf16 v[0:3], v[196:199], v[228:231], v[0:3]
	v_mfma_f32_16x16x32_bf16 v[50:53], v[170:173], v[204:207], v[50:53]
	v_mfma_f32_16x16x32_bf16 v[54:57], v[196:199], v[204:207], v[54:57]
	s_barrier
; #define PG8_STAGE(bufoff, gbase, voff) do { _Pragma("unroll") for (int _i = 0; _i < 2; ++_i) \
;         __builtin_amdgcn_global_load_lds((const unsigned*)((const char*)(gbase) + (voff)[_i]), (PG8_LAS unsigned*)(lds + (bufoff) + ldsw + _i * 8192), 16, 0, 0); } while (0)
; #define PG8_LDA(dst, b, h) do { _Pragma("unroll") for (int m = 0; m < 4; ++m) _Pragma("unroll") for (int k = 0; k < 2; ++k) dst[m][k] = *(const PG8_LAS bf16x8*)(lds + PG8_SA(b, h) + aoff + m * 2048 + k * 1024); } while (0)
; #define PG8_LDB(dst, b, h) do { _Pragma("unroll") for (int n = 0; n < 2; ++n) _Pragma("unroll") for (int k = 0; k < 2; ++k) dst[n][k] = *(const PG8_LAS bf16x8*)(lds + PG8_SB(b, h) + boff + n * 2048 + k * 1024); } while (0)
; #define PG8_MMA(ai, bj, At, Bt) do { __builtin_amdgcn_s_setprio(1); _Pragma("unroll") for (int m = 0; m < 4; ++m) _Pragma("unroll") for (int n = 0; n < 2; ++n) _Pragma("unroll") for (int k = 0; k < 2; ++k) \
;         acc[ai][bj][m][n] = __builtin_amdgcn_mfma_f32_16x16x32_bf16(Bt[n][k], At[m][k], acc[ai][bj][m][n], 0, 0, 0); __builtin_amdgcn_s_setprio(0); } while (0)
; #define PG8_WAIT_V(n) asm volatile("s_waitcnt vmcnt(" #n ")" ::: "memory")
; #define PG8_WAIT_L(n) asm volatile("s_waitcnt lgkmcnt(" #n ")" ::: "memory")
; #define PG8_BAR __builtin_amdgcn_s_barrier()
; #define PG8_SCHED __builtin_amdgcn_sched_barrier(0)
; template <class Epi, class Sched, bool ALIGN_EPI = false, bool SP2 = false>
; __device__ __forceinline__ void gemm_phase(PG8_LAS unsigned char* lds, const Gemm g, const Sched& S, const Epi& E) {
;     ...
;             PG8_LDB(B0, 1, 0); PG8_LDB(B1, 1, 1); PG8_SCHED; PG8_LDA(At, 1, 0); PG8_STAGE(PG8_SA(0, 1), a2 + hstep, voffA);
;             PG8_WAIT_V(8); PG8_WAIT_L(0); PG8_BAR; PG8_MMA(0, 0, At, B0); PG8_MMA(0, 1, At, B1); PG8_BAR; PG8_SCHED;
;             PG8_LDA(At, 1, 1); PG8_STAGE(PG8_SB(1, 0), b3, voffB); PG8_STAGE(PG8_SB(1, 1), b3 + hstep, voffB); PG8_STAGE(PG8_SA(1, 0), a3, voffA);
;             PG8_WAIT_V(8); PG8_WAIT_L(0); PG8_BAR; PG8_MMA(1, 0, At, B0); PG8_MMA(1, 1, At, B1); PG8_BAR; PG8_SCHED;
	s_add_i32 s61, 0, 0x18000
	s_add_i32 s72, 0, 0x1c000
	v_add_u32_e32 v70, s61, v176
	v_add_u32_e32 v179, s72, v176
	ds_read_b128 v[58:61], v70
	ds_read_b128 v[62:65], v70 offset:1024
	ds_read_b128 v[66:69], v70 offset:2048
	ds_read_b128 v[70:73], v70 offset:3072
	ds_read_b128 v[158:161], v179
	ds_read_b128 v[170:173], v179 offset:1024
	ds_read_b128 v[180:183], v179 offset:2048
	ds_read_b128 v[196:199], v179 offset:3072
	s_add_u32 s50, s50, 0x40000
	s_addc_u32 s51, s51, 0
	s_mov_b32 m0, s8
	ds_read_b128 v[200:203], v178 offset:32768
	ds_read_b128 v[204:207], v178 offset:33792
	ds_read_b128 v[208:211], v178 offset:34816
	ds_read_b128 v[212:215], v178 offset:35840
	ds_read_b128 v[216:219], v178 offset:36864
	ds_read_b128 v[220:223], v178 offset:37888
	ds_read_b128 v[224:227], v178 offset:38912
	ds_read_b128 v[228:231], v178 offset:39936
	global_load_lds_dwordx4 v146, s[50:51]
	s_mov_b32 m0, s0
	s_nop 0
	global_load_lds_dwordx4 v150, s[50:51]
	s_waitcnt vmcnt(8) lgkmcnt(0)
	s_barrier
	v_mfma_f32_16x16x32_bf16 v[142:145], v[58:61], v[200:203], v[142:145]
	v_mfma_f32_16x16x32_bf16 v[138:141], v[66:69], v[200:203], v[138:141]
	v_mfma_f32_16x16x32_bf16 v[126:129], v[58:61], v[208:211], v[126:129]
	v_mfma_f32_16x16x32_bf16 v[122:125], v[66:69], v[208:211], v[122:125]
	v_mfma_f32_16x16x32_bf16 v[110:113], v[58:61], v[216:219], v[110:113]
	v_mfma_f32_16x16x32_bf16 v[106:109], v[66:69], v[216:219], v[106:109]
	v_mfma_f32_16x16x32_bf16 v[94:97], v[58:61], v[224:227], v[94:97]
	v_mfma_f32_16x16x32_bf16 v[90:93], v[66:69], v[224:227], v[90:93]
	v_mfma_f32_16x16x32_bf16 v[142:145], v[62:65], v[204:207], v[142:145]
	v_mfma_f32_16x16x32_bf16 v[138:141], v[70:73], v[204:207], v[138:141]
	v_mfma_f32_16x16x32_bf16 v[126:129], v[62:65], v[212:215], v[126:129]
	v_mfma_f32_16x16x32_bf16 v[122:125], v[70:73], v[212:215], v[122:125]
	v_mfma_f32_16x16x32_bf16 v[110:113], v[62:65], v[220:223], v[110:113]
	v_mfma_f32_16x16x32_bf16 v[106:109], v[70:73], v[220:223], v[106:109]
	v_mfma_f32_16x16x32_bf16 v[94:97], v[62:65], v[228:231], v[94:97]
	v_mfma_f32_16x16x32_bf16 v[90:93], v[70:73], v[228:231], v[90:93]
	v_mfma_f32_16x16x32_bf16 v[134:137], v[158:161], v[200:203], v[134:137]
	v_mfma_f32_16x16x32_bf16 v[130:133], v[180:183], v[200:203], v[130:133]
	v_mfma_f32_16x16x32_bf16 v[118:121], v[158:161], v[208:211], v[118:121]
	v_mfma_f32_16x16x32_bf16 v[114:117], v[180:183], v[208:211], v[114:117]
	v_mfma_f32_16x16x32_bf16 v[102:105], v[158:161], v[216:219], v[102:105]
	v_mfma_f32_16x16x32_bf16 v[98:101], v[180:183], v[216:219], v[98:101]
	v_mfma_f32_16x16x32_bf16 v[86:89], v[158:161], v[224:227], v[86:89]
	v_mfma_f32_16x16x32_bf16 v[82:85], v[180:183], v[224:227], v[82:85]
	v_mfma_f32_16x16x32_bf16 v[134:137], v[170:173], v[204:207], v[134:137]
	v_mfma_f32_16x16x32_bf16 v[130:133], v[196:199], v[204:207], v[130:133]
	v_mfma_f32_16x16x32_bf16 v[118:121], v[170:173], v[212:215], v[118:121]
	v_mfma_f32_16x16x32_bf16 v[114:117], v[196:199], v[212:215], v[114:117]
	v_mfma_f32_16x16x32_bf16 v[102:105], v[170:173], v[220:223], v[102:105]
	v_mfma_f32_16x16x32_bf16 v[98:101], v[196:199], v[220:223], v[98:101]
	v_mfma_f32_16x16x32_bf16 v[86:89], v[170:173], v[228:231], v[86:89]
	v_mfma_f32_16x16x32_bf16 v[82:85], v[196:199], v[228:231], v[82:85]
	s_barrier
	s_add_i32 s50, s61, s4
	v_lshl_add_u64 v[174:175], v[174:175], 0, s[34:35]
	s_mov_b32 m0, s50
	ds_read_b128 v[200:203], v178 offset:49152
	ds_read_b128 v[204:207], v178 offset:50176
	ds_read_b128 v[208:211], v178 offset:51200
	ds_read_b128 v[212:215], v178 offset:52224
	ds_read_b128 v[216:219], v178 offset:53248
	ds_read_b128 v[220:223], v178 offset:54272
	ds_read_b128 v[224:227], v178 offset:55296
	ds_read_b128 v[228:231], v178 offset:56320
	global_load_lds_dwordx4 v[174:175], off
	s_add_i32 m0, s50, 0x2000
	s_add_u32 s48, s48, 0x40080
	v_lshl_add_u64 v[174:175], v[184:185], 0, s[34:35]
	s_addc_u32 s49, s49, 0
	s_add_i32 s50, s72, s4
	global_load_lds_dwordx4 v[174:175], off
	s_mov_b32 m0, s50
	s_nop 0
	global_load_lds_dwordx4 v148, s[48:49]
	s_add_i32 m0, s50, 0x2000
	s_nop 0
	global_load_lds_dwordx4 v152, s[48:49]
	v_lshl_add_u64 v[174:175], v[232:233], 0, s[34:35]
	s_mov_b32 m0, s9
	s_nop 0
	global_load_lds_dwordx4 v[174:175], off
	v_lshl_add_u64 v[174:175], v[234:235], 0, s[34:35]
	s_mov_b32 m0, s86
	s_nop 0
	global_load_lds_dwordx4 v[174:175], off
	s_waitcnt vmcnt(8) lgkmcnt(0)
	s_barrier
	v_mfma_f32_16x16x32_bf16 v[78:81], v[58:61], v[200:203], v[78:81]
	v_mfma_f32_16x16x32_bf16 v[74:77], v[66:69], v[200:203], v[74:77]
	v_mfma_f32_16x16x32_bf16 v[46:49], v[58:61], v[208:211], v[46:49]
	v_mfma_f32_16x16x32_bf16 v[42:45], v[66:69], v[208:211], v[42:45]
	v_mfma_f32_16x16x32_bf16 v[28:31], v[58:61], v[216:219], v[28:31]
	v_mfma_f32_16x16x32_bf16 v[24:27], v[66:69], v[216:219], v[24:27]
	v_mfma_f32_16x16x32_bf16 v[12:15], v[58:61], v[224:227], v[12:15]
	v_mfma_f32_16x16x32_bf16 v[8:11], v[66:69], v[224:227], v[8:11]
	v_mfma_f32_16x16x32_bf16 v[78:81], v[62:65], v[204:207], v[78:81]
	v_mfma_f32_16x16x32_bf16 v[74:77], v[70:73], v[204:207], v[74:77]
	v_mfma_f32_16x16x32_bf16 v[46:49], v[62:65], v[212:215], v[46:49]
	v_mfma_f32_16x16x32_bf16 v[42:45], v[70:73], v[212:215], v[42:45]
	v_mfma_f32_16x16x32_bf16 v[28:31], v[62:65], v[220:223], v[28:31]
	v_mfma_f32_16x16x32_bf16 v[24:27], v[70:73], v[220:223], v[24:27]
	v_mfma_f32_16x16x32_bf16 v[12:15], v[62:65], v[228:231], v[12:15]
	v_mfma_f32_16x16x32_bf16 v[8:11], v[70:73], v[228:231], v[8:11]
	v_mfma_f32_16x16x32_bf16 v[50:53], v[158:161], v[200:203], v[50:53]
	v_mfma_f32_16x16x32_bf16 v[62:65], v[170:173], v[204:207], v[50:53]
	v_mfma_f32_16x16x32_bf16 v[50:53], v[180:183], v[200:203], v[54:57]
	v_mfma_f32_16x16x32_bf16 v[38:41], v[158:161], v[208:211], v[38:41]
	v_mfma_f32_16x16x32_bf16 v[34:37], v[180:183], v[208:211], v[34:37]
	v_mfma_f32_16x16x32_bf16 v[20:23], v[158:161], v[216:219], v[20:23]
	v_mfma_f32_16x16x32_bf16 v[16:19], v[180:183], v[216:219], v[16:19]
	v_mfma_f32_16x16x32_bf16 v[4:7], v[158:161], v[224:227], v[4:7]
	v_mfma_f32_16x16x32_bf16 v[0:3], v[180:183], v[224:227], v[0:3]
	v_mfma_f32_16x16x32_bf16 v[58:61], v[196:199], v[204:207], v[50:53]
	v_mfma_f32_16x16x32_bf16 v[38:41], v[170:173], v[212:215], v[38:41]
	v_mfma_f32_16x16x32_bf16 v[34:37], v[196:199], v[212:215], v[34:37]
	v_mfma_f32_16x16x32_bf16 v[20:23], v[170:173], v[220:223], v[20:23]
	v_mfma_f32_16x16x32_bf16 v[16:19], v[196:199], v[220:223], v[16:19]
	v_mfma_f32_16x16x32_bf16 v[4:7], v[170:173], v[228:231], v[4:7]
	v_mfma_f32_16x16x32_bf16 v[0:3], v[196:199], v[228:231], v[0:3]
	s_barrier
	s_add_i32 s80, s80, 2
	s_add_u32 vcc_hi, vcc_hi, 0x100
	s_addc_u32 s7, s7, 0
	s_add_u32 s46, s46, 0x100
	s_addc_u32 s47, s47, 0
	s_cmp_gt_u32 s80, 13
	s_cbranch_scc0 .LBB0_145
	v_readlane_b32 s46, v254, 51
	v_readlane_b32 s47, v254, 52
	s_and_b64 vcc, exec, s[46:47]
	s_cbranch_vccz .LBB0_148
	s_barrier

; #define PG8_STAGE(bufoff, gbase, voff) do { _Pragma("unroll") for (int _i = 0; _i < 2; ++_i) \
;         __builtin_amdgcn_global_load_lds((const unsigned*)((const char*)(gbase) + (voff)[_i]), (PG8_LAS unsigned*)(lds + (bufoff) + ldsw + _i * 8192), 16, 0, 0); } while (0)
; #define PG8_LDA(dst, b, h) do { _Pragma("unroll") for (int m = 0; m < 4; ++m) _Pragma("unroll") for (int k = 0; k < 2; ++k) dst[m][k] = *(const PG8_LAS bf16x8*)(lds + PG8_SA(b, h) + aoff + m * 2048 + k * 1024); } while (0)
; #define PG8_LDB(dst, b, h) do { _Pragma("unroll") for (int n = 0; n < 2; ++n) _Pragma("unroll") for (int k = 0; k < 2; ++k) dst[n][k] = *(const PG8_LAS bf16x8*)(lds + PG8_SB(b, h) + boff + n * 2048 + k * 1024); } while (0)
; #define PG8_MMA(ai, bj, At, Bt) do { __builtin_amdgcn_s_setprio(1); _Pragma("unroll") for (int m = 0; m < 4; ++m) _Pragma("unroll") for (int n = 0; n < 2; ++n) _Pragma("unroll") for (int k = 0; k < 2; ++k) \
;         acc[ai][bj][m][n] = __builtin_amdgcn_mfma_f32_16x16x32_bf16(Bt[n][k], At[m][k], acc[ai][bj][m][n], 0, 0, 0); __builtin_amdgcn_s_setprio(0); } while (0)
; #define PG8_WAIT_V(n) asm volatile("s_waitcnt vmcnt(" #n ")" ::: "memory")
; #define PG8_BAR __builtin_amdgcn_s_barrier()
; template <class Epi, class Sched, bool ALIGN_EPI = false, bool SP2 = false>
; __device__ __forceinline__ void gemm_phase(PG8_LAS unsigned char* lds, const Gemm g, const Sched& S, const Epi& E) {
;     ...
;         for (int t = 0; t < nt; t += 2) {
;             const bool last = (t == nt - 2);
;             const char* a1 = cA + (size_t)(t + 1) * kstep;
;             const char* a2 = last ? nA : cA + (size_t)(t + 2) * kstep; const char* b2 = last ? nB : cB + (size_t)(t + 2) * kstep;
;             const char* a3 = a2 + kstep; const char* b3 = b2 + kstep;
;             if (last && has_next) S.a_ready(nxt);
;             if constexpr (SP2) {
;             PG8_LDB(B0, 0, 0); PG8_LDB(B1, 0, 1); PG8_SCHED; PG8_LDA(At, 0, 0); PG8_STAGE(PG8_SA(1, 1), a1 + hstep, voffA);
;             PG8_WAIT_V(8); PG8_WAIT_L(0); PG8_BAR; PG8_MMA(0, 0, At, B0); PG8_MMA(0, 1, At, B1); PG8_BAR; PG8_SCHED;
;             PG8_LDA(At, 0, 1); PG8_STAGE(PG8_SB(0, 0), b2, voffB); PG8_STAGE(PG8_SB(0, 1), b2 + hstep, voffB); PG8_STAGE(PG8_SA(0, 0), a2, voffA);
;             PG8_WAIT_V(8); PG8_WAIT_L(0); PG8_BAR; PG8_MMA(1, 0, At, B0); PG8_MMA(1, 1, At, B1); PG8_BAR; PG8_SCHED;
.LBB0_369:
	s_add_i32 s92, s46, 2
	s_add_u32 s61, s44, 0x80
	s_addc_u32 s47, s45, 0
	s_add_i32 s72, 0, 0x10000
	s_cmp_eq_u32 s87, s46
	s_cselect_b32 s47, s43, s47
	s_cselect_b32 s46, s42, s61
	v_add_u32_e32 v149, s72, v146
	s_cselect_b32 s95, s77, s91
	s_cselect_b32 s94, s76, s90
	s_add_i32 s61, 0, 0x14000
	ds_read_b128 v[142:145], v149
	ds_read_b128 v[150:153], v149 offset:1024
	ds_read_b128 v[154:157], v149 offset:2048
	ds_read_b128 v[158:161], v149 offset:3072
	v_add_u32_e32 v149, s61, v146
	ds_read_b128 v[170:173], v149
	ds_read_b128 v[174:177], v149 offset:1024
	ds_read_b128 v[178:181], v149 offset:2048
	ds_read_b128 v[182:185], v149 offset:3072
	s_add_i32 m0, s51, 0xc000
	ds_read_b128 v[196:199], v148
	ds_read_b128 v[200:203], v148 offset:1024
	ds_read_b128 v[204:207], v148 offset:2048
	ds_read_b128 v[208:211], v148 offset:3072
	ds_read_b128 v[212:215], v148 offset:4096
	ds_read_b128 v[216:219], v148 offset:5120
	ds_read_b128 v[220:223], v148 offset:6144
	ds_read_b128 v[224:227], v148 offset:7168
	global_load_lds_dwordx4 v140, s[44:45]
	s_add_i32 m0, s51, 0xe000
	s_nop 0
	global_load_lds_dwordx4 v138, s[44:45]
	s_waitcnt vmcnt(8) lgkmcnt(0)
	s_barrier
	v_mfma_f32_16x16x32_bf16 v[126:129], v[142:145], v[196:199], v[126:129]
	v_mfma_f32_16x16x32_bf16 v[122:125], v[154:157], v[196:199], v[122:125]
	v_mfma_f32_16x16x32_bf16 v[110:113], v[142:145], v[204:207], v[110:113]
	v_mfma_f32_16x16x32_bf16 v[106:109], v[154:157], v[204:207], v[106:109]
	v_mfma_f32_16x16x32_bf16 v[94:97], v[142:145], v[212:215], v[94:97]
	v_mfma_f32_16x16x32_bf16 v[90:93], v[154:157], v[212:215], v[90:93]
	v_mfma_f32_16x16x32_bf16 v[78:81], v[142:145], v[220:223], v[78:81]
	v_mfma_f32_16x16x32_bf16 v[74:77], v[154:157], v[220:223], v[74:77]
	v_mfma_f32_16x16x32_bf16 v[126:129], v[150:153], v[200:203], v[126:129]
	v_mfma_f32_16x16x32_bf16 v[122:125], v[158:161], v[200:203], v[122:125]
	v_mfma_f32_16x16x32_bf16 v[110:113], v[150:153], v[208:211], v[110:113]
	v_mfma_f32_16x16x32_bf16 v[106:109], v[158:161], v[208:211], v[106:109]
	v_mfma_f32_16x16x32_bf16 v[94:97], v[150:153], v[216:219], v[94:97]
	v_mfma_f32_16x16x32_bf16 v[90:93], v[158:161], v[216:219], v[90:93]
	v_mfma_f32_16x16x32_bf16 v[78:81], v[150:153], v[224:227], v[78:81]
	v_mfma_f32_16x16x32_bf16 v[74:77], v[158:161], v[224:227], v[74:77]
	v_mfma_f32_16x16x32_bf16 v[118:121], v[170:173], v[196:199], v[118:121]
	v_mfma_f32_16x16x32_bf16 v[114:117], v[178:181], v[196:199], v[114:117]
	v_mfma_f32_16x16x32_bf16 v[102:105], v[170:173], v[204:207], v[102:105]
	v_mfma_f32_16x16x32_bf16 v[98:101], v[178:181], v[204:207], v[98:101]
	v_mfma_f32_16x16x32_bf16 v[86:89], v[170:173], v[212:215], v[86:89]
	v_mfma_f32_16x16x32_bf16 v[82:85], v[178:181], v[212:215], v[82:85]
	v_mfma_f32_16x16x32_bf16 v[70:73], v[170:173], v[220:223], v[70:73]
	v_mfma_f32_16x16x32_bf16 v[66:69], v[178:181], v[220:223], v[66:69]
	v_mfma_f32_16x16x32_bf16 v[118:121], v[174:177], v[200:203], v[118:121]
	v_mfma_f32_16x16x32_bf16 v[114:117], v[182:185], v[200:203], v[114:117]
	v_mfma_f32_16x16x32_bf16 v[102:105], v[174:177], v[208:211], v[102:105]
	v_mfma_f32_16x16x32_bf16 v[98:101], v[182:185], v[208:211], v[98:101]
	v_mfma_f32_16x16x32_bf16 v[86:89], v[174:177], v[216:219], v[86:89]
	v_mfma_f32_16x16x32_bf16 v[82:85], v[182:185], v[216:219], v[82:85]
	v_mfma_f32_16x16x32_bf16 v[70:73], v[174:177], v[224:227], v[70:73]
	v_mfma_f32_16x16x32_bf16 v[66:69], v[182:185], v[224:227], v[66:69]
	s_barrier
	s_add_i32 s72, s72, s50
	v_lshl_add_u64 v[228:229], s[94:95], 0, v[132:133]
	s_mov_b32 m0, s72
	ds_read_b128 v[196:199], v148 offset:16384
	ds_read_b128 v[200:203], v148 offset:17408
	ds_read_b128 v[204:207], v148 offset:18432
	ds_read_b128 v[208:211], v148 offset:19456
	ds_read_b128 v[212:215], v148 offset:20480
	ds_read_b128 v[216:219], v148 offset:21504
	ds_read_b128 v[220:223], v148 offset:22528
	ds_read_b128 v[224:227], v148 offset:23552
	global_load_lds_dwordx4 v[228:229], off
	s_add_i32 m0, s72, 0x2000
	v_lshl_add_u64 v[230:231], s[94:95], 0, v[136:137]
	s_add_u32 s94, s94, s8
	s_addc_u32 s95, s95, 0
	s_add_i32 s61, s61, s50
	global_load_lds_dwordx4 v[230:231], off
	v_lshl_add_u64 v[232:233], s[94:95], 0, v[132:133]
	s_mov_b32 m0, s61
	v_lshl_add_u64 v[234:235], s[94:95], 0, v[136:137]
	global_load_lds_dwordx4 v[232:233], off
	s_add_i32 m0, s61, 0x2000
	v_lshl_add_u64 v[236:237], s[46:47], 0, v[130:131]
	global_load_lds_dwordx4 v[234:235], off
	s_mov_b32 m0, s51
	v_lshl_add_u64 v[238:239], s[46:47], 0, v[134:135]
	global_load_lds_dwordx4 v[236:237], off
	s_mov_b32 m0, s78
	s_nop 0
	global_load_lds_dwordx4 v[238:239], off
	s_waitcnt vmcnt(8) lgkmcnt(0)
	s_barrier
; #define PG8_STAGE(bufoff, gbase, voff) do { _Pragma("unroll") for (int _i = 0; _i < 2; ++_i) \
;         __builtin_amdgcn_global_load_lds((const unsigned*)((const char*)(gbase) + (voff)[_i]), (PG8_LAS unsigned*)(lds + (bufoff) + ldsw + _i * 8192), 16, 0, 0); } while (0)
; #define PG8_LDA(dst, b, h) do { _Pragma("unroll") for (int m = 0; m < 4; ++m) _Pragma("unroll") for (int k = 0; k < 2; ++k) dst[m][k] = *(const PG8_LAS bf16x8*)(lds + PG8_SA(b, h) + aoff + m * 2048 + k * 1024); } while (0)
; #define PG8_LDB(dst, b, h) do { _Pragma("unroll") for (int n = 0; n < 2; ++n) _Pragma("unroll") for (int k = 0; k < 2; ++k) dst[n][k] = *(const PG8_LAS bf16x8*)(lds + PG8_SB(b, h) + boff + n * 2048 + k * 1024); } while (0)
; #define PG8_MMA(ai, bj, At, Bt) do { __builtin_amdgcn_s_setprio(1); _Pragma("unroll") for (int m = 0; m < 4; ++m) _Pragma("unroll") for (int n = 0; n < 2; ++n) _Pragma("unroll") for (int k = 0; k < 2; ++k) \
;         acc[ai][bj][m][n] = __builtin_amdgcn_mfma_f32_16x16x32_bf16(Bt[n][k], At[m][k], acc[ai][bj][m][n], 0, 0, 0); __builtin_amdgcn_s_setprio(0); } while (0)
; #define PG8_WAIT_V(n) asm volatile("s_waitcnt vmcnt(" #n ")" ::: "memory")
; #define PG8_WAIT_L(n) asm volatile("s_waitcnt lgkmcnt(" #n ")" ::: "memory")
; #define PG8_BAR __builtin_amdgcn_s_barrier()
; #define PG8_SCHED __builtin_amdgcn_sched_barrier(0)
; template <class Epi, class Sched, bool ALIGN_EPI = false, bool SP2 = false>
; __device__ __forceinline__ void gemm_phase(PG8_LAS unsigned char* lds, const Gemm g, const Sched& S, const Epi& E) {
;     ...
;             PG8_WAIT_V(8); PG8_WAIT_L(0); PG8_BAR; PG8_MMA(1, 0, At, B0); PG8_MMA(1, 1, At, B1); PG8_BAR; PG8_SCHED;
;             PG8_LDB(B0, 1, 0); PG8_LDB(B1, 1, 1); PG8_SCHED; PG8_LDA(At, 1, 0); PG8_STAGE(PG8_SA(0, 1), a2 + hstep, voffA);
;             PG8_WAIT_V(8); PG8_WAIT_L(0); PG8_BAR; PG8_MMA(0, 0, At, B0); PG8_MMA(0, 1, At, B1); PG8_BAR; PG8_SCHED;
	v_mfma_f32_16x16x32_bf16 v[62:65], v[142:145], v[196:199], v[62:65]
	v_mfma_f32_16x16x32_bf16 v[58:61], v[154:157], v[196:199], v[58:61]
	v_mfma_f32_16x16x32_bf16 v[46:49], v[142:145], v[204:207], v[46:49]
	v_mfma_f32_16x16x32_bf16 v[42:45], v[154:157], v[204:207], v[42:45]
	v_mfma_f32_16x16x32_bf16 v[28:31], v[142:145], v[212:215], v[28:31]
	v_mfma_f32_16x16x32_bf16 v[24:27], v[154:157], v[212:215], v[24:27]
	v_mfma_f32_16x16x32_bf16 v[12:15], v[142:145], v[220:223], v[12:15]
	v_mfma_f32_16x16x32_bf16 v[8:11], v[154:157], v[220:223], v[8:11]
	v_mfma_f32_16x16x32_bf16 v[62:65], v[150:153], v[200:203], v[62:65]
	v_mfma_f32_16x16x32_bf16 v[58:61], v[158:161], v[200:203], v[58:61]
	v_mfma_f32_16x16x32_bf16 v[46:49], v[150:153], v[208:211], v[46:49]
	v_mfma_f32_16x16x32_bf16 v[42:45], v[158:161], v[208:211], v[42:45]
	v_mfma_f32_16x16x32_bf16 v[28:31], v[150:153], v[216:219], v[28:31]
	v_mfma_f32_16x16x32_bf16 v[24:27], v[158:161], v[216:219], v[24:27]
	v_mfma_f32_16x16x32_bf16 v[12:15], v[150:153], v[224:227], v[12:15]
	v_mfma_f32_16x16x32_bf16 v[8:11], v[158:161], v[224:227], v[8:11]
	v_mfma_f32_16x16x32_bf16 v[54:57], v[170:173], v[196:199], v[54:57]
	v_mfma_f32_16x16x32_bf16 v[50:53], v[178:181], v[196:199], v[50:53]
	v_mfma_f32_16x16x32_bf16 v[38:41], v[170:173], v[204:207], v[38:41]
	v_mfma_f32_16x16x32_bf16 v[34:37], v[178:181], v[204:207], v[34:37]
	v_mfma_f32_16x16x32_bf16 v[20:23], v[170:173], v[212:215], v[20:23]
	v_mfma_f32_16x16x32_bf16 v[16:19], v[178:181], v[212:215], v[16:19]
	v_mfma_f32_16x16x32_bf16 v[4:7], v[170:173], v[220:223], v[4:7]
	v_mfma_f32_16x16x32_bf16 v[0:3], v[178:181], v[220:223], v[0:3]
	v_mfma_f32_16x16x32_bf16 v[54:57], v[174:177], v[200:203], v[54:57]
	v_mfma_f32_16x16x32_bf16 v[50:53], v[182:185], v[200:203], v[50:53]
	v_mfma_f32_16x16x32_bf16 v[38:41], v[174:177], v[208:211], v[38:41]
	v_mfma_f32_16x16x32_bf16 v[34:37], v[182:185], v[208:211], v[34:37]
	v_mfma_f32_16x16x32_bf16 v[20:23], v[174:177], v[216:219], v[20:23]
	v_mfma_f32_16x16x32_bf16 v[16:19], v[182:185], v[216:219], v[16:19]
	v_mfma_f32_16x16x32_bf16 v[4:7], v[174:177], v[224:227], v[4:7]
	v_mfma_f32_16x16x32_bf16 v[0:3], v[182:185], v[224:227], v[0:3]
	s_barrier
	s_add_i32 s61, 0, 0x18000
	v_add_u32_e32 v149, s61, v146
	s_add_i32 s72, 0, 0x1c000
	ds_read_b128 v[142:145], v149
	ds_read_b128 v[150:153], v149 offset:1024
	ds_read_b128 v[154:157], v149 offset:2048
	ds_read_b128 v[158:161], v149 offset:3072
	v_add_u32_e32 v149, s72, v146
	ds_read_b128 v[170:173], v149
	ds_read_b128 v[174:177], v149 offset:1024
	ds_read_b128 v[178:181], v149 offset:2048
	ds_read_b128 v[182:185], v149 offset:3072
	s_add_u32 s46, s46, s8
	s_addc_u32 s47, s47, 0
	s_mov_b32 m0, s79
	ds_read_b128 v[196:199], v148 offset:32768
	ds_read_b128 v[200:203], v148 offset:33792
	ds_read_b128 v[204:207], v148 offset:34816
	ds_read_b128 v[208:211], v148 offset:35840
	ds_read_b128 v[212:215], v148 offset:36864
	ds_read_b128 v[216:219], v148 offset:37888
	ds_read_b128 v[220:223], v148 offset:38912
	ds_read_b128 v[224:227], v148 offset:39936
	global_load_lds_dwordx4 v130, s[46:47]
	s_mov_b32 m0, s80
	s_nop 0
	global_load_lds_dwordx4 v134, s[46:47]
	s_waitcnt vmcnt(8) lgkmcnt(0)
	s_barrier
	v_mfma_f32_16x16x32_bf16 v[126:129], v[142:145], v[196:199], v[126:129]
	v_mfma_f32_16x16x32_bf16 v[122:125], v[154:157], v[196:199], v[122:125]
	v_mfma_f32_16x16x32_bf16 v[110:113], v[142:145], v[204:207], v[110:113]
	v_mfma_f32_16x16x32_bf16 v[106:109], v[154:157], v[204:207], v[106:109]
	v_mfma_f32_16x16x32_bf16 v[94:97], v[142:145], v[212:215], v[94:97]
	v_mfma_f32_16x16x32_bf16 v[90:93], v[154:157], v[212:215], v[90:93]
	v_mfma_f32_16x16x32_bf16 v[78:81], v[142:145], v[220:223], v[78:81]
	v_mfma_f32_16x16x32_bf16 v[74:77], v[154:157], v[220:223], v[74:77]
	v_mfma_f32_16x16x32_bf16 v[126:129], v[150:153], v[200:203], v[126:129]
	v_mfma_f32_16x16x32_bf16 v[122:125], v[158:161], v[200:203], v[122:125]
	v_mfma_f32_16x16x32_bf16 v[110:113], v[150:153], v[208:211], v[110:113]
	v_mfma_f32_16x16x32_bf16 v[106:109], v[158:161], v[208:211], v[106:109]
	v_mfma_f32_16x16x32_bf16 v[94:97], v[150:153], v[216:219], v[94:97]
	v_mfma_f32_16x16x32_bf16 v[90:93], v[158:161], v[216:219], v[90:93]
	v_mfma_f32_16x16x32_bf16 v[78:81], v[150:153], v[224:227], v[78:81]
	v_mfma_f32_16x16x32_bf16 v[74:77], v[158:161], v[224:227], v[74:77]
	v_mfma_f32_16x16x32_bf16 v[118:121], v[170:173], v[196:199], v[118:121]
	v_mfma_f32_16x16x32_bf16 v[114:117], v[178:181], v[196:199], v[114:117]
	v_mfma_f32_16x16x32_bf16 v[102:105], v[170:173], v[204:207], v[102:105]
	v_mfma_f32_16x16x32_bf16 v[98:101], v[178:181], v[204:207], v[98:101]
	v_mfma_f32_16x16x32_bf16 v[86:89], v[170:173], v[212:215], v[86:89]
	v_mfma_f32_16x16x32_bf16 v[82:85], v[178:181], v[212:215], v[82:85]
	v_mfma_f32_16x16x32_bf16 v[70:73], v[170:173], v[220:223], v[70:73]
	v_mfma_f32_16x16x32_bf16 v[66:69], v[178:181], v[220:223], v[66:69]
	v_mfma_f32_16x16x32_bf16 v[118:121], v[174:177], v[200:203], v[118:121]
	v_mfma_f32_16x16x32_bf16 v[114:117], v[182:185], v[200:203], v[114:117]
	v_mfma_f32_16x16x32_bf16 v[102:105], v[174:177], v[208:211], v[102:105]
	v_mfma_f32_16x16x32_bf16 v[98:101], v[182:185], v[208:211], v[98:101]
	v_mfma_f32_16x16x32_bf16 v[86:89], v[174:177], v[216:219], v[86:89]
	v_mfma_f32_16x16x32_bf16 v[82:85], v[182:185], v[216:219], v[82:85]
	v_mfma_f32_16x16x32_bf16 v[70:73], v[174:177], v[224:227], v[70:73]
	v_mfma_f32_16x16x32_bf16 v[66:69], v[182:185], v[224:227], v[66:69]
	s_barrier
; #define PG8_STAGE(bufoff, gbase, voff) do { _Pragma("unroll") for (int _i = 0; _i < 2; ++_i) \
;         __builtin_amdgcn_global_load_lds((const unsigned*)((const char*)(gbase) + (voff)[_i]), (PG8_LAS unsigned*)(lds + (bufoff) + ldsw + _i * 8192), 16, 0, 0); } while (0)
; #define PG8_LDA(dst, b, h) do { _Pragma("unroll") for (int m = 0; m < 4; ++m) _Pragma("unroll") for (int k = 0; k < 2; ++k) dst[m][k] = *(const PG8_LAS bf16x8*)(lds + PG8_SA(b, h) + aoff + m * 2048 + k * 1024); } while (0)
; #define PG8_MMA(ai, bj, At, Bt) do { __builtin_amdgcn_s_setprio(1); _Pragma("unroll") for (int m = 0; m < 4; ++m) _Pragma("unroll") for (int n = 0; n < 2; ++n) _Pragma("unroll") for (int k = 0; k < 2; ++k) \
;         acc[ai][bj][m][n] = __builtin_amdgcn_mfma_f32_16x16x32_bf16(Bt[n][k], At[m][k], acc[ai][bj][m][n], 0, 0, 0); __builtin_amdgcn_s_setprio(0); } while (0)
; #define PG8_WAIT_V(n) asm volatile("s_waitcnt vmcnt(" #n ")" ::: "memory")
; #define PG8_WAIT_L(n) asm volatile("s_waitcnt lgkmcnt(" #n ")" ::: "memory")
; #define PG8_BAR __builtin_amdgcn_s_barrier()
; #define PG8_SCHED __builtin_amdgcn_sched_barrier(0)
; template <class Epi, class Sched, bool ALIGN_EPI = false, bool SP2 = false>
; __device__ __forceinline__ void gemm_phase(PG8_LAS unsigned char* lds, const Gemm g, const Sched& S, const Epi& E) {
;     ...
;             PG8_LDA(At, 1, 1); PG8_STAGE(PG8_SB(1, 0), b3, voffB); PG8_STAGE(PG8_SB(1, 1), b3 + hstep, voffB); PG8_STAGE(PG8_SA(1, 0), a3, voffA);
;             PG8_WAIT_V(8); PG8_WAIT_L(0); PG8_BAR; PG8_MMA(1, 0, At, B0); PG8_MMA(1, 1, At, B1); PG8_BAR; PG8_SCHED;
	s_add_i32 s46, s61, s50
	v_lshl_add_u64 v[228:229], v[228:229], 0, s[34:35]
	s_mov_b32 m0, s46
	ds_read_b128 v[196:199], v148 offset:49152
	ds_read_b128 v[200:203], v148 offset:50176
	ds_read_b128 v[204:207], v148 offset:51200
	ds_read_b128 v[208:211], v148 offset:52224
	ds_read_b128 v[212:215], v148 offset:53248
	ds_read_b128 v[216:219], v148 offset:54272
	ds_read_b128 v[220:223], v148 offset:55296
	ds_read_b128 v[224:227], v148 offset:56320
	global_load_lds_dwordx4 v[228:229], off
	v_lshl_add_u64 v[228:229], v[230:231], 0, s[34:35]
	s_add_i32 m0, s46, 0x2000
	s_add_i32 s46, s72, s50
	global_load_lds_dwordx4 v[228:229], off
	v_lshl_add_u64 v[228:229], v[232:233], 0, s[34:35]
	s_mov_b32 m0, s46
	s_nop 0
	global_load_lds_dwordx4 v[228:229], off
	v_lshl_add_u64 v[228:229], v[234:235], 0, s[34:35]
	s_add_i32 m0, s46, 0x2000
	s_nop 0
	global_load_lds_dwordx4 v[228:229], off
	v_lshl_add_u64 v[228:229], v[236:237], 0, s[34:35]
	s_mov_b32 m0, s85
	s_nop 0
	global_load_lds_dwordx4 v[228:229], off
	v_lshl_add_u64 v[228:229], v[238:239], 0, s[34:35]
	s_mov_b32 m0, s86
	s_nop 0
	global_load_lds_dwordx4 v[228:229], off
	s_waitcnt vmcnt(8) lgkmcnt(0)
	s_barrier
	v_mfma_f32_16x16x32_bf16 v[62:65], v[142:145], v[196:199], v[62:65]
	v_mfma_f32_16x16x32_bf16 v[58:61], v[154:157], v[196:199], v[58:61]
	v_mfma_f32_16x16x32_bf16 v[46:49], v[142:145], v[204:207], v[46:49]
	v_mfma_f32_16x16x32_bf16 v[42:45], v[154:157], v[204:207], v[42:45]
	v_mfma_f32_16x16x32_bf16 v[28:31], v[142:145], v[212:215], v[28:31]
	v_mfma_f32_16x16x32_bf16 v[24:27], v[154:157], v[212:215], v[24:27]
	v_mfma_f32_16x16x32_bf16 v[12:15], v[142:145], v[220:223], v[12:15]
	v_mfma_f32_16x16x32_bf16 v[8:11], v[154:157], v[220:223], v[8:11]
	v_mfma_f32_16x16x32_bf16 v[62:65], v[150:153], v[200:203], v[62:65]
	v_mfma_f32_16x16x32_bf16 v[58:61], v[158:161], v[200:203], v[58:61]
	v_mfma_f32_16x16x32_bf16 v[46:49], v[150:153], v[208:211], v[46:49]
	v_mfma_f32_16x16x32_bf16 v[42:45], v[158:161], v[208:211], v[42:45]
	v_mfma_f32_16x16x32_bf16 v[28:31], v[150:153], v[216:219], v[28:31]
	v_mfma_f32_16x16x32_bf16 v[24:27], v[158:161], v[216:219], v[24:27]
	v_mfma_f32_16x16x32_bf16 v[12:15], v[150:153], v[224:227], v[12:15]
	v_mfma_f32_16x16x32_bf16 v[8:11], v[158:161], v[224:227], v[8:11]
	v_mfma_f32_16x16x32_bf16 v[54:57], v[170:173], v[196:199], v[54:57]
	v_mfma_f32_16x16x32_bf16 v[50:53], v[178:181], v[196:199], v[50:53]
	v_mfma_f32_16x16x32_bf16 v[38:41], v[170:173], v[204:207], v[38:41]
	v_mfma_f32_16x16x32_bf16 v[34:37], v[178:181], v[204:207], v[34:37]
	v_mfma_f32_16x16x32_bf16 v[20:23], v[170:173], v[212:215], v[20:23]
	v_mfma_f32_16x16x32_bf16 v[16:19], v[178:181], v[212:215], v[16:19]
	v_mfma_f32_16x16x32_bf16 v[4:7], v[170:173], v[220:223], v[4:7]
	v_mfma_f32_16x16x32_bf16 v[0:3], v[178:181], v[220:223], v[0:3]
	v_mfma_f32_16x16x32_bf16 v[54:57], v[174:177], v[200:203], v[54:57]
	v_mfma_f32_16x16x32_bf16 v[50:53], v[182:185], v[200:203], v[50:53]
	v_mfma_f32_16x16x32_bf16 v[38:41], v[174:177], v[208:211], v[38:41]
	v_mfma_f32_16x16x32_bf16 v[34:37], v[182:185], v[208:211], v[34:37]
	v_mfma_f32_16x16x32_bf16 v[20:23], v[174:177], v[216:219], v[20:23]
	v_mfma_f32_16x16x32_bf16 v[16:19], v[182:185], v[216:219], v[16:19]
	v_mfma_f32_16x16x32_bf16 v[4:7], v[174:177], v[224:227], v[4:7]
	v_mfma_f32_16x16x32_bf16 v[0:3], v[182:185], v[224:227], v[0:3]
	s_barrier
	s_add_u32 s90, s90, 0x100
	s_addc_u32 s91, s91, 0
	s_add_u32 s44, s44, 0x100
	s_addc_u32 s45, s45, 0
	s_cmp_ge_u32 s92, s82
	s_mov_b32 s46, s92
	s_cbranch_scc0 .LBB0_369
	s_and_b64 vcc, exec, s[40:41]
	s_cbranch_vccz .LBB0_372
	s_barrier

; #define PG8_STAGE(bufoff, gbase, voff) do { _Pragma("unroll") for (int _i = 0; _i < 2; ++_i) \
;         __builtin_amdgcn_global_load_lds((const unsigned*)((const char*)(gbase) + (voff)[_i]), (PG8_LAS unsigned*)(lds + (bufoff) + ldsw + _i * 8192), 16, 0, 0); } while (0)
; #define PG8_LDA(dst, b, h) do { _Pragma("unroll") for (int m = 0; m < 4; ++m) _Pragma("unroll") for (int k = 0; k < 2; ++k) dst[m][k] = *(const PG8_LAS bf16x8*)(lds + PG8_SA(b, h) + aoff + m * 2048 + k * 1024); } while (0)
; #define PG8_LDB(dst, b, h) do { _Pragma("unroll") for (int n = 0; n < 2; ++n) _Pragma("unroll") for (int k = 0; k < 2; ++k) dst[n][k] = *(const PG8_LAS bf16x8*)(lds + PG8_SB(b, h) + boff + n * 2048 + k * 1024); } while (0)
; #define PG8_MMA(ai, bj, At, Bt) do { __builtin_amdgcn_s_setprio(1); _Pragma("unroll") for (int m = 0; m < 4; ++m) _Pragma("unroll") for (int n = 0; n < 2; ++n) _Pragma("unroll") for (int k = 0; k < 2; ++k) \
;         acc[ai][bj][m][n] = __builtin_amdgcn_mfma_f32_16x16x32_bf16(Bt[n][k], At[m][k], acc[ai][bj][m][n], 0, 0, 0); __builtin_amdgcn_s_setprio(0); } while (0)
; #define PG8_WAIT_V(n) asm volatile("s_waitcnt vmcnt(" #n ")" ::: "memory")
; #define PG8_BAR __builtin_amdgcn_s_barrier()
; template <class Epi, class Sched, bool ALIGN_EPI = false, bool SP2 = false>
; __device__ __forceinline__ void gemm_phase(PG8_LAS unsigned char* lds, const Gemm g, const Sched& S, const Epi& E) {
;     ...
;         for (int t = 0; t < nt; t += 2) {
;             const bool last = (t == nt - 2);
;             const char* a1 = cA + (size_t)(t + 1) * kstep;
;             const char* a2 = last ? nA : cA + (size_t)(t + 2) * kstep; const char* b2 = last ? nB : cB + (size_t)(t + 2) * kstep;
;             const char* a3 = a2 + kstep; const char* b3 = b2 + kstep;
;             if (last && has_next) S.a_ready(nxt);
;             if constexpr (SP2) {
;             PG8_LDB(B0, 0, 0); PG8_LDB(B1, 0, 1); PG8_SCHED; PG8_LDA(At, 0, 0); PG8_STAGE(PG8_SA(1, 1), a1 + hstep, voffA);
;             PG8_WAIT_V(8); PG8_WAIT_L(0); PG8_BAR; PG8_MMA(0, 0, At, B0); PG8_MMA(0, 1, At, B1); PG8_BAR; PG8_SCHED;
;             PG8_LDA(At, 0, 1); PG8_STAGE(PG8_SB(0, 0), b2, voffB); PG8_STAGE(PG8_SB(0, 1), b2 + hstep, voffB); PG8_STAGE(PG8_SA(0, 0), a2, voffA);
;             PG8_WAIT_V(8); PG8_WAIT_L(0); PG8_BAR; PG8_MMA(1, 0, At, B0); PG8_MMA(1, 1, At, B1); PG8_BAR; PG8_SCHED;
.LBB0_411:
	s_add_i32 vcc_lo, s46, 2
	s_add_u32 s38, s44, 0x80
	s_addc_u32 s39, s45, 0
	s_add_i32 vcc_hi, 0, 0x10000
	s_cmp_eq_u32 s92, s46
	s_cselect_b32 s47, s79, s39
	s_cselect_b32 s46, s78, s38
	v_add_u32_e32 v149, vcc_hi, v146
	s_cselect_b32 s39, s81, s49
	s_cselect_b32 s38, s80, s48
	s_add_i32 s61, 0, 0x14000
	ds_read_b128 v[142:145], v149
	ds_read_b128 v[150:153], v149 offset:1024
	ds_read_b128 v[154:157], v149 offset:2048
	ds_read_b128 v[158:161], v149 offset:3072
	v_add_u32_e32 v149, s61, v146
	ds_read_b128 v[170:173], v149
	ds_read_b128 v[174:177], v149 offset:1024
	ds_read_b128 v[178:181], v149 offset:2048
	ds_read_b128 v[182:185], v149 offset:3072
	s_add_i32 m0, s82, 0xc000
	ds_read_b128 v[196:199], v148
	ds_read_b128 v[200:203], v148 offset:1024
	ds_read_b128 v[204:207], v148 offset:2048
	ds_read_b128 v[208:211], v148 offset:3072
	ds_read_b128 v[212:215], v148 offset:4096
	ds_read_b128 v[216:219], v148 offset:5120
	ds_read_b128 v[220:223], v148 offset:6144
	ds_read_b128 v[224:227], v148 offset:7168
	global_load_lds_dwordx4 v140, s[44:45]
	s_add_i32 m0, s82, 0xe000
	s_nop 0
	global_load_lds_dwordx4 v138, s[44:45]
	s_waitcnt vmcnt(8) lgkmcnt(0)
	s_barrier
	v_mfma_f32_16x16x32_bf16 v[126:129], v[142:145], v[196:199], v[126:129]
	v_mfma_f32_16x16x32_bf16 v[122:125], v[154:157], v[196:199], v[122:125]
	v_mfma_f32_16x16x32_bf16 v[110:113], v[142:145], v[204:207], v[110:113]
	v_mfma_f32_16x16x32_bf16 v[106:109], v[154:157], v[204:207], v[106:109]
	v_mfma_f32_16x16x32_bf16 v[94:97], v[142:145], v[212:215], v[94:97]
	v_mfma_f32_16x16x32_bf16 v[90:93], v[154:157], v[212:215], v[90:93]
	v_mfma_f32_16x16x32_bf16 v[78:81], v[142:145], v[220:223], v[78:81]
	v_mfma_f32_16x16x32_bf16 v[74:77], v[154:157], v[220:223], v[74:77]
	v_mfma_f32_16x16x32_bf16 v[126:129], v[150:153], v[200:203], v[126:129]
	v_mfma_f32_16x16x32_bf16 v[122:125], v[158:161], v[200:203], v[122:125]
	v_mfma_f32_16x16x32_bf16 v[110:113], v[150:153], v[208:211], v[110:113]
	v_mfma_f32_16x16x32_bf16 v[106:109], v[158:161], v[208:211], v[106:109]
	v_mfma_f32_16x16x32_bf16 v[94:97], v[150:153], v[216:219], v[94:97]
	v_mfma_f32_16x16x32_bf16 v[90:93], v[158:161], v[216:219], v[90:93]
	v_mfma_f32_16x16x32_bf16 v[78:81], v[150:153], v[224:227], v[78:81]
	v_mfma_f32_16x16x32_bf16 v[74:77], v[158:161], v[224:227], v[74:77]
	v_mfma_f32_16x16x32_bf16 v[118:121], v[170:173], v[196:199], v[118:121]
	v_mfma_f32_16x16x32_bf16 v[114:117], v[178:181], v[196:199], v[114:117]
	v_mfma_f32_16x16x32_bf16 v[102:105], v[170:173], v[204:207], v[102:105]
	v_mfma_f32_16x16x32_bf16 v[98:101], v[178:181], v[204:207], v[98:101]
	v_mfma_f32_16x16x32_bf16 v[86:89], v[170:173], v[212:215], v[86:89]
	v_mfma_f32_16x16x32_bf16 v[82:85], v[178:181], v[212:215], v[82:85]
	v_mfma_f32_16x16x32_bf16 v[70:73], v[170:173], v[220:223], v[70:73]
	v_mfma_f32_16x16x32_bf16 v[66:69], v[178:181], v[220:223], v[66:69]
	v_mfma_f32_16x16x32_bf16 v[118:121], v[174:177], v[200:203], v[118:121]
	v_mfma_f32_16x16x32_bf16 v[114:117], v[182:185], v[200:203], v[114:117]
	v_mfma_f32_16x16x32_bf16 v[102:105], v[174:177], v[208:211], v[102:105]
	v_mfma_f32_16x16x32_bf16 v[98:101], v[182:185], v[208:211], v[98:101]
	v_mfma_f32_16x16x32_bf16 v[86:89], v[174:177], v[216:219], v[86:89]
	v_mfma_f32_16x16x32_bf16 v[82:85], v[182:185], v[216:219], v[82:85]
	v_mfma_f32_16x16x32_bf16 v[70:73], v[174:177], v[224:227], v[70:73]
	v_mfma_f32_16x16x32_bf16 v[66:69], v[182:185], v[224:227], v[66:69]
	s_barrier
	s_add_i32 vcc_hi, vcc_hi, s51
	v_lshl_add_u64 v[228:229], s[38:39], 0, v[132:133]
	s_mov_b32 m0, vcc_hi
	ds_read_b128 v[196:199], v148 offset:16384
	ds_read_b128 v[200:203], v148 offset:17408
	ds_read_b128 v[204:207], v148 offset:18432
	ds_read_b128 v[208:211], v148 offset:19456
	ds_read_b128 v[212:215], v148 offset:20480
	ds_read_b128 v[216:219], v148 offset:21504
	ds_read_b128 v[220:223], v148 offset:22528
	ds_read_b128 v[224:227], v148 offset:23552
	global_load_lds_dwordx4 v[228:229], off
	s_add_i32 m0, vcc_hi, 0x2000
	v_lshl_add_u64 v[230:231], s[38:39], 0, v[136:137]
	s_add_u32 s38, s38, s8
	s_addc_u32 s39, s39, 0
	s_add_i32 s61, s61, s51
	global_load_lds_dwordx4 v[230:231], off
	v_lshl_add_u64 v[232:233], s[38:39], 0, v[132:133]
	s_mov_b32 m0, s61
	v_lshl_add_u64 v[234:235], s[38:39], 0, v[136:137]
	global_load_lds_dwordx4 v[232:233], off
	s_add_i32 m0, s61, 0x2000
	v_lshl_add_u64 v[236:237], s[46:47], 0, v[130:131]
	global_load_lds_dwordx4 v[234:235], off
	s_mov_b32 m0, s82
	v_lshl_add_u64 v[238:239], s[46:47], 0, v[134:135]
	global_load_lds_dwordx4 v[236:237], off
	s_mov_b32 m0, s83
	s_nop 0
	global_load_lds_dwordx4 v[238:239], off
	s_waitcnt vmcnt(8) lgkmcnt(0)
	s_barrier
; #define PG8_STAGE(bufoff, gbase, voff) do { _Pragma("unroll") for (int _i = 0; _i < 2; ++_i) \
;         __builtin_amdgcn_global_load_lds((const unsigned*)((const char*)(gbase) + (voff)[_i]), (PG8_LAS unsigned*)(lds + (bufoff) + ldsw + _i * 8192), 16, 0, 0); } while (0)
; #define PG8_LDA(dst, b, h) do { _Pragma("unroll") for (int m = 0; m < 4; ++m) _Pragma("unroll") for (int k = 0; k < 2; ++k) dst[m][k] = *(const PG8_LAS bf16x8*)(lds + PG8_SA(b, h) + aoff + m * 2048 + k * 1024); } while (0)
; #define PG8_LDB(dst, b, h) do { _Pragma("unroll") for (int n = 0; n < 2; ++n) _Pragma("unroll") for (int k = 0; k < 2; ++k) dst[n][k] = *(const PG8_LAS bf16x8*)(lds + PG8_SB(b, h) + boff + n * 2048 + k * 1024); } while (0)
; #define PG8_MMA(ai, bj, At, Bt) do { __builtin_amdgcn_s_setprio(1); _Pragma("unroll") for (int m = 0; m < 4; ++m) _Pragma("unroll") for (int n = 0; n < 2; ++n) _Pragma("unroll") for (int k = 0; k < 2; ++k) \
;         acc[ai][bj][m][n] = __builtin_amdgcn_mfma_f32_16x16x32_bf16(Bt[n][k], At[m][k], acc[ai][bj][m][n], 0, 0, 0); __builtin_amdgcn_s_setprio(0); } while (0)
; #define PG8_WAIT_V(n) asm volatile("s_waitcnt vmcnt(" #n ")" ::: "memory")
; #define PG8_WAIT_L(n) asm volatile("s_waitcnt lgkmcnt(" #n ")" ::: "memory")
; #define PG8_BAR __builtin_amdgcn_s_barrier()
; #define PG8_SCHED __builtin_amdgcn_sched_barrier(0)
; template <class Epi, class Sched, bool ALIGN_EPI = false, bool SP2 = false>
; __device__ __forceinline__ void gemm_phase(PG8_LAS unsigned char* lds, const Gemm g, const Sched& S, const Epi& E) {
;     ...
;             PG8_WAIT_V(8); PG8_WAIT_L(0); PG8_BAR; PG8_MMA(1, 0, At, B0); PG8_MMA(1, 1, At, B1); PG8_BAR; PG8_SCHED;
;             PG8_LDB(B0, 1, 0); PG8_LDB(B1, 1, 1); PG8_SCHED; PG8_LDA(At, 1, 0); PG8_STAGE(PG8_SA(0, 1), a2 + hstep, voffA);
;             PG8_WAIT_V(8); PG8_WAIT_L(0); PG8_BAR; PG8_MMA(0, 0, At, B0); PG8_MMA(0, 1, At, B1); PG8_BAR; PG8_SCHED;
	v_mfma_f32_16x16x32_bf16 v[62:65], v[142:145], v[196:199], v[62:65]
	v_mfma_f32_16x16x32_bf16 v[58:61], v[154:157], v[196:199], v[58:61]
	v_mfma_f32_16x16x32_bf16 v[46:49], v[142:145], v[204:207], v[46:49]
	v_mfma_f32_16x16x32_bf16 v[42:45], v[154:157], v[204:207], v[42:45]
	v_mfma_f32_16x16x32_bf16 v[28:31], v[142:145], v[212:215], v[28:31]
	v_mfma_f32_16x16x32_bf16 v[24:27], v[154:157], v[212:215], v[24:27]
	v_mfma_f32_16x16x32_bf16 v[12:15], v[142:145], v[220:223], v[12:15]
	v_mfma_f32_16x16x32_bf16 v[8:11], v[154:157], v[220:223], v[8:11]
	v_mfma_f32_16x16x32_bf16 v[62:65], v[150:153], v[200:203], v[62:65]
	v_mfma_f32_16x16x32_bf16 v[58:61], v[158:161], v[200:203], v[58:61]
	v_mfma_f32_16x16x32_bf16 v[46:49], v[150:153], v[208:211], v[46:49]
	v_mfma_f32_16x16x32_bf16 v[42:45], v[158:161], v[208:211], v[42:45]
	v_mfma_f32_16x16x32_bf16 v[28:31], v[150:153], v[216:219], v[28:31]
	v_mfma_f32_16x16x32_bf16 v[24:27], v[158:161], v[216:219], v[24:27]
	v_mfma_f32_16x16x32_bf16 v[12:15], v[150:153], v[224:227], v[12:15]
	v_mfma_f32_16x16x32_bf16 v[8:11], v[158:161], v[224:227], v[8:11]
	v_mfma_f32_16x16x32_bf16 v[54:57], v[170:173], v[196:199], v[54:57]
	v_mfma_f32_16x16x32_bf16 v[50:53], v[178:181], v[196:199], v[50:53]
	v_mfma_f32_16x16x32_bf16 v[38:41], v[170:173], v[204:207], v[38:41]
	v_mfma_f32_16x16x32_bf16 v[34:37], v[178:181], v[204:207], v[34:37]
	v_mfma_f32_16x16x32_bf16 v[20:23], v[170:173], v[212:215], v[20:23]
	v_mfma_f32_16x16x32_bf16 v[16:19], v[178:181], v[212:215], v[16:19]
	v_mfma_f32_16x16x32_bf16 v[4:7], v[170:173], v[220:223], v[4:7]
	v_mfma_f32_16x16x32_bf16 v[0:3], v[178:181], v[220:223], v[0:3]
	v_mfma_f32_16x16x32_bf16 v[54:57], v[174:177], v[200:203], v[54:57]
	v_mfma_f32_16x16x32_bf16 v[50:53], v[182:185], v[200:203], v[50:53]
	v_mfma_f32_16x16x32_bf16 v[38:41], v[174:177], v[208:211], v[38:41]
	v_mfma_f32_16x16x32_bf16 v[34:37], v[182:185], v[208:211], v[34:37]
	v_mfma_f32_16x16x32_bf16 v[20:23], v[174:177], v[216:219], v[20:23]
	v_mfma_f32_16x16x32_bf16 v[16:19], v[182:185], v[216:219], v[16:19]
	v_mfma_f32_16x16x32_bf16 v[4:7], v[174:177], v[224:227], v[4:7]
	v_mfma_f32_16x16x32_bf16 v[0:3], v[182:185], v[224:227], v[0:3]
	s_barrier
	s_add_i32 s61, 0, 0x18000
	v_add_u32_e32 v149, s61, v146
	s_add_i32 vcc_hi, 0, 0x1c000
	ds_read_b128 v[142:145], v149
	ds_read_b128 v[150:153], v149 offset:1024
	ds_read_b128 v[154:157], v149 offset:2048
	ds_read_b128 v[158:161], v149 offset:3072
	v_add_u32_e32 v149, vcc_hi, v146
	ds_read_b128 v[170:173], v149
	ds_read_b128 v[174:177], v149 offset:1024
	ds_read_b128 v[178:181], v149 offset:2048
	ds_read_b128 v[182:185], v149 offset:3072
	s_add_u32 s38, s46, s8
	s_addc_u32 s39, s47, 0
	s_mov_b32 m0, s87
	ds_read_b128 v[196:199], v148 offset:32768
	ds_read_b128 v[200:203], v148 offset:33792
	ds_read_b128 v[204:207], v148 offset:34816
	ds_read_b128 v[208:211], v148 offset:35840
	ds_read_b128 v[212:215], v148 offset:36864
	ds_read_b128 v[216:219], v148 offset:37888
	ds_read_b128 v[220:223], v148 offset:38912
	ds_read_b128 v[224:227], v148 offset:39936
	global_load_lds_dwordx4 v130, s[38:39]
	s_mov_b32 m0, s88
	s_nop 0
	global_load_lds_dwordx4 v134, s[38:39]
	s_waitcnt vmcnt(8) lgkmcnt(0)
	s_barrier
	v_mfma_f32_16x16x32_bf16 v[126:129], v[142:145], v[196:199], v[126:129]
	v_mfma_f32_16x16x32_bf16 v[122:125], v[154:157], v[196:199], v[122:125]
	v_mfma_f32_16x16x32_bf16 v[110:113], v[142:145], v[204:207], v[110:113]
	v_mfma_f32_16x16x32_bf16 v[106:109], v[154:157], v[204:207], v[106:109]
	v_mfma_f32_16x16x32_bf16 v[94:97], v[142:145], v[212:215], v[94:97]
	v_mfma_f32_16x16x32_bf16 v[90:93], v[154:157], v[212:215], v[90:93]
	v_mfma_f32_16x16x32_bf16 v[78:81], v[142:145], v[220:223], v[78:81]
	v_mfma_f32_16x16x32_bf16 v[74:77], v[154:157], v[220:223], v[74:77]
	v_mfma_f32_16x16x32_bf16 v[126:129], v[150:153], v[200:203], v[126:129]
	v_mfma_f32_16x16x32_bf16 v[122:125], v[158:161], v[200:203], v[122:125]
	v_mfma_f32_16x16x32_bf16 v[110:113], v[150:153], v[208:211], v[110:113]
	v_mfma_f32_16x16x32_bf16 v[106:109], v[158:161], v[208:211], v[106:109]
	v_mfma_f32_16x16x32_bf16 v[94:97], v[150:153], v[216:219], v[94:97]
	v_mfma_f32_16x16x32_bf16 v[90:93], v[158:161], v[216:219], v[90:93]
	v_mfma_f32_16x16x32_bf16 v[78:81], v[150:153], v[224:227], v[78:81]
	v_mfma_f32_16x16x32_bf16 v[74:77], v[158:161], v[224:227], v[74:77]
	v_mfma_f32_16x16x32_bf16 v[118:121], v[170:173], v[196:199], v[118:121]
	v_mfma_f32_16x16x32_bf16 v[114:117], v[178:181], v[196:199], v[114:117]
	v_mfma_f32_16x16x32_bf16 v[102:105], v[170:173], v[204:207], v[102:105]
	v_mfma_f32_16x16x32_bf16 v[98:101], v[178:181], v[204:207], v[98:101]
	v_mfma_f32_16x16x32_bf16 v[86:89], v[170:173], v[212:215], v[86:89]
	v_mfma_f32_16x16x32_bf16 v[82:85], v[178:181], v[212:215], v[82:85]
	v_mfma_f32_16x16x32_bf16 v[70:73], v[170:173], v[220:223], v[70:73]
	v_mfma_f32_16x16x32_bf16 v[66:69], v[178:181], v[220:223], v[66:69]
	v_mfma_f32_16x16x32_bf16 v[118:121], v[174:177], v[200:203], v[118:121]
	v_mfma_f32_16x16x32_bf16 v[114:117], v[182:185], v[200:203], v[114:117]
	v_mfma_f32_16x16x32_bf16 v[102:105], v[174:177], v[208:211], v[102:105]
	v_mfma_f32_16x16x32_bf16 v[98:101], v[182:185], v[208:211], v[98:101]
	v_mfma_f32_16x16x32_bf16 v[86:89], v[174:177], v[216:219], v[86:89]
	v_mfma_f32_16x16x32_bf16 v[82:85], v[182:185], v[216:219], v[82:85]
	v_mfma_f32_16x16x32_bf16 v[70:73], v[174:177], v[224:227], v[70:73]
	v_mfma_f32_16x16x32_bf16 v[66:69], v[182:185], v[224:227], v[66:69]
	s_barrier
; #define PG8_STAGE(bufoff, gbase, voff) do { _Pragma("unroll") for (int _i = 0; _i < 2; ++_i) \
;         __builtin_amdgcn_global_load_lds((const unsigned*)((const char*)(gbase) + (voff)[_i]), (PG8_LAS unsigned*)(lds + (bufoff) + ldsw + _i * 8192), 16, 0, 0); } while (0)
; #define PG8_LDA(dst, b, h) do { _Pragma("unroll") for (int m = 0; m < 4; ++m) _Pragma("unroll") for (int k = 0; k < 2; ++k) dst[m][k] = *(const PG8_LAS bf16x8*)(lds + PG8_SA(b, h) + aoff + m * 2048 + k * 1024); } while (0)
; #define PG8_MMA(ai, bj, At, Bt) do { __builtin_amdgcn_s_setprio(1); _Pragma("unroll") for (int m = 0; m < 4; ++m) _Pragma("unroll") for (int n = 0; n < 2; ++n) _Pragma("unroll") for (int k = 0; k < 2; ++k) \
;         acc[ai][bj][m][n] = __builtin_amdgcn_mfma_f32_16x16x32_bf16(Bt[n][k], At[m][k], acc[ai][bj][m][n], 0, 0, 0); __builtin_amdgcn_s_setprio(0); } while (0)
; #define PG8_WAIT_V(n) asm volatile("s_waitcnt vmcnt(" #n ")" ::: "memory")
; #define PG8_WAIT_L(n) asm volatile("s_waitcnt lgkmcnt(" #n ")" ::: "memory")
; #define PG8_BAR __builtin_amdgcn_s_barrier()
; #define PG8_SCHED __builtin_amdgcn_sched_barrier(0)
; template <class Epi, class Sched, bool ALIGN_EPI = false, bool SP2 = false>
; __device__ __forceinline__ void gemm_phase(PG8_LAS unsigned char* lds, const Gemm g, const Sched& S, const Epi& E) {
;     ...
;             PG8_LDA(At, 1, 1); PG8_STAGE(PG8_SB(1, 0), b3, voffB); PG8_STAGE(PG8_SB(1, 1), b3 + hstep, voffB); PG8_STAGE(PG8_SA(1, 0), a3, voffA);
;             PG8_WAIT_V(8); PG8_WAIT_L(0); PG8_BAR; PG8_MMA(1, 0, At, B0); PG8_MMA(1, 1, At, B1); PG8_BAR; PG8_SCHED;
	s_add_i32 s38, s61, s51
	v_lshl_add_u64 v[228:229], v[228:229], 0, s[34:35]
	s_mov_b32 m0, s38
	ds_read_b128 v[196:199], v148 offset:49152
	ds_read_b128 v[200:203], v148 offset:50176
	ds_read_b128 v[204:207], v148 offset:51200
	ds_read_b128 v[208:211], v148 offset:52224
	ds_read_b128 v[212:215], v148 offset:53248
	ds_read_b128 v[216:219], v148 offset:54272
	ds_read_b128 v[220:223], v148 offset:55296
	ds_read_b128 v[224:227], v148 offset:56320
	global_load_lds_dwordx4 v[228:229], off
	v_lshl_add_u64 v[228:229], v[230:231], 0, s[34:35]
	s_add_i32 m0, s38, 0x2000
	s_add_i32 s38, vcc_hi, s51
	global_load_lds_dwordx4 v[228:229], off
	v_lshl_add_u64 v[228:229], v[232:233], 0, s[34:35]
	s_mov_b32 m0, s38
	s_nop 0
	global_load_lds_dwordx4 v[228:229], off
	v_lshl_add_u64 v[228:229], v[234:235], 0, s[34:35]
	s_add_i32 m0, s38, 0x2000
	s_nop 0
	global_load_lds_dwordx4 v[228:229], off
	v_lshl_add_u64 v[228:229], v[236:237], 0, s[34:35]
	s_mov_b32 m0, s90
	s_nop 0
	global_load_lds_dwordx4 v[228:229], off
	v_lshl_add_u64 v[228:229], v[238:239], 0, s[34:35]
	s_mov_b32 m0, s91
	s_nop 0
	global_load_lds_dwordx4 v[228:229], off
	s_waitcnt vmcnt(8) lgkmcnt(0)
	s_barrier
	v_mfma_f32_16x16x32_bf16 v[62:65], v[142:145], v[196:199], v[62:65]
	v_mfma_f32_16x16x32_bf16 v[58:61], v[154:157], v[196:199], v[58:61]
	v_mfma_f32_16x16x32_bf16 v[46:49], v[142:145], v[204:207], v[46:49]
	v_mfma_f32_16x16x32_bf16 v[42:45], v[154:157], v[204:207], v[42:45]
	v_mfma_f32_16x16x32_bf16 v[28:31], v[142:145], v[212:215], v[28:31]
	v_mfma_f32_16x16x32_bf16 v[24:27], v[154:157], v[212:215], v[24:27]
	v_mfma_f32_16x16x32_bf16 v[12:15], v[142:145], v[220:223], v[12:15]
	v_mfma_f32_16x16x32_bf16 v[8:11], v[154:157], v[220:223], v[8:11]
	v_mfma_f32_16x16x32_bf16 v[62:65], v[150:153], v[200:203], v[62:65]
	v_mfma_f32_16x16x32_bf16 v[58:61], v[158:161], v[200:203], v[58:61]
	v_mfma_f32_16x16x32_bf16 v[46:49], v[150:153], v[208:211], v[46:49]
	v_mfma_f32_16x16x32_bf16 v[42:45], v[158:161], v[208:211], v[42:45]
	v_mfma_f32_16x16x32_bf16 v[28:31], v[150:153], v[216:219], v[28:31]
	v_mfma_f32_16x16x32_bf16 v[24:27], v[158:161], v[216:219], v[24:27]
	v_mfma_f32_16x16x32_bf16 v[12:15], v[150:153], v[224:227], v[12:15]
	v_mfma_f32_16x16x32_bf16 v[8:11], v[158:161], v[224:227], v[8:11]
	v_mfma_f32_16x16x32_bf16 v[54:57], v[170:173], v[196:199], v[54:57]
	v_mfma_f32_16x16x32_bf16 v[50:53], v[178:181], v[196:199], v[50:53]
	v_mfma_f32_16x16x32_bf16 v[38:41], v[170:173], v[204:207], v[38:41]
	v_mfma_f32_16x16x32_bf16 v[34:37], v[178:181], v[204:207], v[34:37]
	v_mfma_f32_16x16x32_bf16 v[20:23], v[170:173], v[212:215], v[20:23]
	v_mfma_f32_16x16x32_bf16 v[16:19], v[178:181], v[212:215], v[16:19]
	v_mfma_f32_16x16x32_bf16 v[4:7], v[170:173], v[220:223], v[4:7]
	v_mfma_f32_16x16x32_bf16 v[0:3], v[178:181], v[220:223], v[0:3]
	v_mfma_f32_16x16x32_bf16 v[54:57], v[174:177], v[200:203], v[54:57]
	v_mfma_f32_16x16x32_bf16 v[50:53], v[182:185], v[200:203], v[50:53]
	v_mfma_f32_16x16x32_bf16 v[38:41], v[174:177], v[208:211], v[38:41]
	v_mfma_f32_16x16x32_bf16 v[34:37], v[182:185], v[208:211], v[34:37]
	v_mfma_f32_16x16x32_bf16 v[20:23], v[174:177], v[216:219], v[20:23]
	v_mfma_f32_16x16x32_bf16 v[16:19], v[182:185], v[216:219], v[16:19]
	v_mfma_f32_16x16x32_bf16 v[4:7], v[174:177], v[224:227], v[4:7]
	v_mfma_f32_16x16x32_bf16 v[0:3], v[182:185], v[224:227], v[0:3]
	s_barrier
	s_add_u32 s48, s48, 0x100
	s_addc_u32 s49, s49, 0
	s_add_u32 s44, s44, 0x100
	s_addc_u32 s45, s45, 0
	s_cmp_ge_u32 vcc_lo, s85
	s_mov_b32 s46, vcc_lo
	s_cbranch_scc0 .LBB0_411
	s_and_b64 vcc, exec, s[42:43]
	s_cbranch_vccz .LBB0_414
	s_barrier

; #define PG8_STAGE(bufoff, gbase, voff) do { _Pragma("unroll") for (int _i = 0; _i < 2; ++_i) \
;         __builtin_amdgcn_global_load_lds((const unsigned*)((const char*)(gbase) + (voff)[_i]), (PG8_LAS unsigned*)(lds + (bufoff) + ldsw + _i * 8192), 16, 0, 0); } while (0)
; #define PG8_LDA(dst, b, h) do { _Pragma("unroll") for (int m = 0; m < 4; ++m) _Pragma("unroll") for (int k = 0; k < 2; ++k) dst[m][k] = *(const PG8_LAS bf16x8*)(lds + PG8_SA(b, h) + aoff + m * 2048 + k * 1024); } while (0)
; #define PG8_LDB(dst, b, h) do { _Pragma("unroll") for (int n = 0; n < 2; ++n) _Pragma("unroll") for (int k = 0; k < 2; ++k) dst[n][k] = *(const PG8_LAS bf16x8*)(lds + PG8_SB(b, h) + boff + n * 2048 + k * 1024); } while (0)
; #define PG8_MMA(ai, bj, At, Bt) do { __builtin_amdgcn_s_setprio(1); _Pragma("unroll") for (int m = 0; m < 4; ++m) _Pragma("unroll") for (int n = 0; n < 2; ++n) _Pragma("unroll") for (int k = 0; k < 2; ++k) \
;         acc[ai][bj][m][n] = __builtin_amdgcn_mfma_f32_16x16x32_bf16(Bt[n][k], At[m][k], acc[ai][bj][m][n], 0, 0, 0); __builtin_amdgcn_s_setprio(0); } while (0)
; #define PG8_WAIT_V(n) asm volatile("s_waitcnt vmcnt(" #n ")" ::: "memory")
; #define PG8_BAR __builtin_amdgcn_s_barrier()
; template <class Epi, class Sched, bool ALIGN_EPI = false, bool SP2 = false>
; __device__ __forceinline__ void gemm_phase(PG8_LAS unsigned char* lds, const Gemm g, const Sched& S, const Epi& E) {
;     ...
;         for (int t = 0; t < nt; t += 2) {
;             const bool last = (t == nt - 2);
;             const char* a1 = cA + (size_t)(t + 1) * kstep;
;             const char* a2 = last ? nA : cA + (size_t)(t + 2) * kstep; const char* b2 = last ? nB : cB + (size_t)(t + 2) * kstep;
;             const char* a3 = a2 + kstep; const char* b3 = b2 + kstep;
;             if (last && has_next) S.a_ready(nxt);
;             if constexpr (SP2) {
;             PG8_LDB(B0, 0, 0); PG8_LDB(B1, 0, 1); PG8_SCHED; PG8_LDA(At, 0, 0); PG8_STAGE(PG8_SA(1, 1), a1 + hstep, voffA);
;             PG8_WAIT_V(8); PG8_WAIT_L(0); PG8_BAR; PG8_MMA(0, 0, At, B0); PG8_MMA(0, 1, At, B1); PG8_BAR; PG8_SCHED;
;             PG8_LDA(At, 0, 1); PG8_STAGE(PG8_SB(0, 0), b2, voffB); PG8_STAGE(PG8_SB(0, 1), b2 + hstep, voffB); PG8_STAGE(PG8_SA(0, 0), a2, voffA);
;             PG8_WAIT_V(8); PG8_WAIT_L(0); PG8_BAR; PG8_MMA(1, 0, At, B0); PG8_MMA(1, 1, At, B1); PG8_BAR; PG8_SCHED;
.LBB0_444:
	s_add_u32 s38, s48, 0xfffc0080
	s_addc_u32 s39, s49, -1
	s_add_i32 s61, 0, 0x10000
	s_cmp_eq_u32 vcc_hi, 12
	s_cselect_b32 s83, s43, s39
	s_cselect_b32 s82, s45, s38
	v_add_u32_e32 v151, s61, v145
	s_cselect_b32 s51, s41, vcc_lo
	s_cselect_b32 s50, s96, s97
	s_add_i32 s72, 0, 0x14000
	ds_read_b128 v[170:173], v151
	ds_read_b128 v[174:177], v151 offset:1024
	ds_read_b128 v[178:181], v151 offset:2048
	ds_read_b128 v[182:185], v151 offset:3072
	v_add_u32_e32 v151, s72, v145
	ds_read_b128 v[196:199], v151
	ds_read_b128 v[200:203], v151 offset:1024
	ds_read_b128 v[204:207], v151 offset:2048
	ds_read_b128 v[208:211], v151 offset:3072
	s_add_i32 m0, s47, 0xc000
	ds_read_b128 v[212:215], v149
	ds_read_b128 v[216:219], v149 offset:1024
	ds_read_b128 v[220:223], v149 offset:2048
	ds_read_b128 v[224:227], v149 offset:3072
	ds_read_b128 v[228:231], v149 offset:4096
	ds_read_b128 v[232:235], v149 offset:5120
	ds_read_b128 v[236:239], v149 offset:6144
	ds_read_b128 v[240:243], v149 offset:7168
	global_load_lds_dwordx4 v142, s[48:49]
	s_add_i32 m0, s47, 0xe000
	s_nop 0
	global_load_lds_dwordx4 v140, s[48:49]
	s_waitcnt vmcnt(8) lgkmcnt(0)
	s_barrier
	v_mfma_f32_16x16x32_bf16 v[126:129], v[170:173], v[212:215], v[126:129]
	v_mfma_f32_16x16x32_bf16 v[122:125], v[178:181], v[212:215], v[122:125]
	v_mfma_f32_16x16x32_bf16 v[110:113], v[170:173], v[220:223], v[110:113]
	v_mfma_f32_16x16x32_bf16 v[106:109], v[178:181], v[220:223], v[106:109]
	v_mfma_f32_16x16x32_bf16 v[94:97], v[170:173], v[228:231], v[94:97]
	v_mfma_f32_16x16x32_bf16 v[90:93], v[178:181], v[228:231], v[90:93]
	v_mfma_f32_16x16x32_bf16 v[78:81], v[170:173], v[236:239], v[78:81]
	v_mfma_f32_16x16x32_bf16 v[74:77], v[178:181], v[236:239], v[74:77]
	v_mfma_f32_16x16x32_bf16 v[126:129], v[174:177], v[216:219], v[126:129]
	v_mfma_f32_16x16x32_bf16 v[122:125], v[182:185], v[216:219], v[122:125]
	v_mfma_f32_16x16x32_bf16 v[110:113], v[174:177], v[224:227], v[110:113]
	v_mfma_f32_16x16x32_bf16 v[106:109], v[182:185], v[224:227], v[106:109]
	v_mfma_f32_16x16x32_bf16 v[94:97], v[174:177], v[232:235], v[94:97]
	v_mfma_f32_16x16x32_bf16 v[90:93], v[182:185], v[232:235], v[90:93]
	v_mfma_f32_16x16x32_bf16 v[78:81], v[174:177], v[240:243], v[78:81]
	v_mfma_f32_16x16x32_bf16 v[74:77], v[182:185], v[240:243], v[74:77]
	v_mfma_f32_16x16x32_bf16 v[118:121], v[196:199], v[212:215], v[118:121]
	v_mfma_f32_16x16x32_bf16 v[114:117], v[204:207], v[212:215], v[114:117]
	v_mfma_f32_16x16x32_bf16 v[102:105], v[196:199], v[220:223], v[102:105]
	v_mfma_f32_16x16x32_bf16 v[98:101], v[204:207], v[220:223], v[98:101]
	v_mfma_f32_16x16x32_bf16 v[86:89], v[196:199], v[228:231], v[86:89]
	v_mfma_f32_16x16x32_bf16 v[82:85], v[204:207], v[228:231], v[82:85]
	v_mfma_f32_16x16x32_bf16 v[70:73], v[196:199], v[236:239], v[70:73]
	v_mfma_f32_16x16x32_bf16 v[66:69], v[204:207], v[236:239], v[66:69]
	v_mfma_f32_16x16x32_bf16 v[118:121], v[200:203], v[216:219], v[118:121]
	v_mfma_f32_16x16x32_bf16 v[114:117], v[208:211], v[216:219], v[114:117]
	v_mfma_f32_16x16x32_bf16 v[102:105], v[200:203], v[224:227], v[102:105]
	v_mfma_f32_16x16x32_bf16 v[98:101], v[208:211], v[224:227], v[98:101]
	v_mfma_f32_16x16x32_bf16 v[86:89], v[200:203], v[232:235], v[86:89]
	v_mfma_f32_16x16x32_bf16 v[82:85], v[208:211], v[232:235], v[82:85]
	v_mfma_f32_16x16x32_bf16 v[70:73], v[200:203], v[240:243], v[70:73]
	v_mfma_f32_16x16x32_bf16 v[66:69], v[208:211], v[240:243], v[66:69]
	s_barrier
	s_add_i32 s38, s61, s89
	v_lshl_add_u64 v[160:161], s[50:51], 0, v[134:135]
	s_mov_b32 m0, s38
	ds_read_b128 v[212:215], v149 offset:16384
	ds_read_b128 v[216:219], v149 offset:17408
	ds_read_b128 v[220:223], v149 offset:18432
	ds_read_b128 v[224:227], v149 offset:19456
	ds_read_b128 v[228:231], v149 offset:20480
	ds_read_b128 v[232:235], v149 offset:21504
	ds_read_b128 v[236:239], v149 offset:22528
	ds_read_b128 v[240:243], v149 offset:23552
	global_load_lds_dwordx4 v[160:161], off
	s_add_i32 m0, s38, 0x2000
	s_add_u32 s38, s50, 0x40000
	v_lshl_add_u64 v[244:245], s[50:51], 0, v[130:131]
	s_addc_u32 s39, s51, 0
	s_add_i32 s61, s72, s89
	global_load_lds_dwordx4 v[244:245], off
	s_mov_b32 m0, s61
	v_lshl_add_u64 v[248:249], s[82:83], 0, v[132:133]
	global_load_lds_dwordx4 v134, s[38:39]
	s_add_i32 m0, s61, 0x2000
	s_nop 0
	global_load_lds_dwordx4 v130, s[38:39]
	v_lshl_add_u64 v[246:247], s[82:83], 0, v[136:137]
	s_mov_b32 m0, s47
	s_nop 0
	global_load_lds_dwordx4 v[246:247], off
	s_mov_b32 m0, s90
	s_nop 0
	global_load_lds_dwordx4 v[248:249], off
	s_waitcnt vmcnt(8) lgkmcnt(0)
	s_barrier
; #define PG8_STAGE(bufoff, gbase, voff) do { _Pragma("unroll") for (int _i = 0; _i < 2; ++_i) \
;         __builtin_amdgcn_global_load_lds((const unsigned*)((const char*)(gbase) + (voff)[_i]), (PG8_LAS unsigned*)(lds + (bufoff) + ldsw + _i * 8192), 16, 0, 0); } while (0)
; #define PG8_LDA(dst, b, h) do { _Pragma("unroll") for (int m = 0; m < 4; ++m) _Pragma("unroll") for (int k = 0; k < 2; ++k) dst[m][k] = *(const PG8_LAS bf16x8*)(lds + PG8_SA(b, h) + aoff + m * 2048 + k * 1024); } while (0)
; #define PG8_LDB(dst, b, h) do { _Pragma("unroll") for (int n = 0; n < 2; ++n) _Pragma("unroll") for (int k = 0; k < 2; ++k) dst[n][k] = *(const PG8_LAS bf16x8*)(lds + PG8_SB(b, h) + boff + n * 2048 + k * 1024); } while (0)
; #define PG8_MMA(ai, bj, At, Bt) do { __builtin_amdgcn_s_setprio(1); _Pragma("unroll") for (int m = 0; m < 4; ++m) _Pragma("unroll") for (int n = 0; n < 2; ++n) _Pragma("unroll") for (int k = 0; k < 2; ++k) \
;         acc[ai][bj][m][n] = __builtin_amdgcn_mfma_f32_16x16x32_bf16(Bt[n][k], At[m][k], acc[ai][bj][m][n], 0, 0, 0); __builtin_amdgcn_s_setprio(0); } while (0)
; #define PG8_WAIT_V(n) asm volatile("s_waitcnt vmcnt(" #n ")" ::: "memory")
; #define PG8_WAIT_L(n) asm volatile("s_waitcnt lgkmcnt(" #n ")" ::: "memory")
; #define PG8_BAR __builtin_amdgcn_s_barrier()
; #define PG8_SCHED __builtin_amdgcn_sched_barrier(0)
; template <class Epi, class Sched, bool ALIGN_EPI = false, bool SP2 = false>
; __device__ __forceinline__ void gemm_phase(PG8_LAS unsigned char* lds, const Gemm g, const Sched& S, const Epi& E) {
;     ...
;             PG8_WAIT_V(8); PG8_WAIT_L(0); PG8_BAR; PG8_MMA(1, 0, At, B0); PG8_MMA(1, 1, At, B1); PG8_BAR; PG8_SCHED;
;             PG8_LDB(B0, 1, 0); PG8_LDB(B1, 1, 1); PG8_SCHED; PG8_LDA(At, 1, 0); PG8_STAGE(PG8_SA(0, 1), a2 + hstep, voffA);
;             PG8_WAIT_V(8); PG8_WAIT_L(0); PG8_BAR; PG8_MMA(0, 0, At, B0); PG8_MMA(0, 1, At, B1); PG8_BAR; PG8_SCHED;
	v_mfma_f32_16x16x32_bf16 v[62:65], v[170:173], v[212:215], v[62:65]
	v_mfma_f32_16x16x32_bf16 v[58:61], v[178:181], v[212:215], v[58:61]
	v_mfma_f32_16x16x32_bf16 v[46:49], v[170:173], v[220:223], v[46:49]
	v_mfma_f32_16x16x32_bf16 v[42:45], v[178:181], v[220:223], v[42:45]
	v_mfma_f32_16x16x32_bf16 v[28:31], v[170:173], v[228:231], v[28:31]
	v_mfma_f32_16x16x32_bf16 v[24:27], v[178:181], v[228:231], v[24:27]
	v_mfma_f32_16x16x32_bf16 v[12:15], v[170:173], v[236:239], v[12:15]
	v_mfma_f32_16x16x32_bf16 v[8:11], v[178:181], v[236:239], v[8:11]
	v_mfma_f32_16x16x32_bf16 v[62:65], v[174:177], v[216:219], v[62:65]
	v_mfma_f32_16x16x32_bf16 v[58:61], v[182:185], v[216:219], v[58:61]
	v_mfma_f32_16x16x32_bf16 v[46:49], v[174:177], v[224:227], v[46:49]
	v_mfma_f32_16x16x32_bf16 v[42:45], v[182:185], v[224:227], v[42:45]
	v_mfma_f32_16x16x32_bf16 v[28:31], v[174:177], v[232:235], v[28:31]
	v_mfma_f32_16x16x32_bf16 v[24:27], v[182:185], v[232:235], v[24:27]
	v_mfma_f32_16x16x32_bf16 v[12:15], v[174:177], v[240:243], v[12:15]
	v_mfma_f32_16x16x32_bf16 v[8:11], v[182:185], v[240:243], v[8:11]
	v_mfma_f32_16x16x32_bf16 v[54:57], v[196:199], v[212:215], v[54:57]
	v_mfma_f32_16x16x32_bf16 v[50:53], v[204:207], v[212:215], v[50:53]
	v_mfma_f32_16x16x32_bf16 v[38:41], v[196:199], v[220:223], v[38:41]
	v_mfma_f32_16x16x32_bf16 v[34:37], v[204:207], v[220:223], v[34:37]
	v_mfma_f32_16x16x32_bf16 v[20:23], v[196:199], v[228:231], v[20:23]
	v_mfma_f32_16x16x32_bf16 v[16:19], v[204:207], v[228:231], v[16:19]
	v_mfma_f32_16x16x32_bf16 v[4:7], v[196:199], v[236:239], v[4:7]
	v_mfma_f32_16x16x32_bf16 v[0:3], v[204:207], v[236:239], v[0:3]
	v_mfma_f32_16x16x32_bf16 v[54:57], v[200:203], v[216:219], v[54:57]
	v_mfma_f32_16x16x32_bf16 v[50:53], v[208:211], v[216:219], v[50:53]
	v_mfma_f32_16x16x32_bf16 v[38:41], v[200:203], v[224:227], v[38:41]
	v_mfma_f32_16x16x32_bf16 v[34:37], v[208:211], v[224:227], v[34:37]
	v_mfma_f32_16x16x32_bf16 v[20:23], v[200:203], v[232:235], v[20:23]
	v_mfma_f32_16x16x32_bf16 v[16:19], v[208:211], v[232:235], v[16:19]
	v_mfma_f32_16x16x32_bf16 v[4:7], v[200:203], v[240:243], v[4:7]
	v_mfma_f32_16x16x32_bf16 v[0:3], v[208:211], v[240:243], v[0:3]
	s_barrier
	s_add_i32 s61, 0, 0x18000
	v_add_u32_e32 v151, s61, v145
	s_add_i32 s72, 0, 0x1c000
	ds_read_b128 v[170:173], v151
	ds_read_b128 v[174:177], v151 offset:1024
	ds_read_b128 v[178:181], v151 offset:2048
	ds_read_b128 v[182:185], v151 offset:3072
	v_add_u32_e32 v151, s72, v145
	ds_read_b128 v[196:199], v151
	ds_read_b128 v[200:203], v151 offset:1024
	ds_read_b128 v[204:207], v151 offset:2048
	ds_read_b128 v[208:211], v151 offset:3072
	s_add_u32 s38, s82, 0x40000
	s_addc_u32 s39, s83, 0
	s_mov_b32 m0, s91
	ds_read_b128 v[212:215], v149 offset:32768
	ds_read_b128 v[216:219], v149 offset:33792
	ds_read_b128 v[220:223], v149 offset:34816
	ds_read_b128 v[224:227], v149 offset:35840
	ds_read_b128 v[228:231], v149 offset:36864
	ds_read_b128 v[232:235], v149 offset:37888
	ds_read_b128 v[236:239], v149 offset:38912
	ds_read_b128 v[240:243], v149 offset:39936
	global_load_lds_dwordx4 v136, s[38:39]
	s_mov_b32 m0, s92
	s_nop 0
	global_load_lds_dwordx4 v132, s[38:39]
	s_waitcnt vmcnt(8) lgkmcnt(0)
	s_barrier
	v_mfma_f32_16x16x32_bf16 v[126:129], v[170:173], v[212:215], v[126:129]
	v_mfma_f32_16x16x32_bf16 v[122:125], v[178:181], v[212:215], v[122:125]
	v_mfma_f32_16x16x32_bf16 v[110:113], v[170:173], v[220:223], v[110:113]
	v_mfma_f32_16x16x32_bf16 v[106:109], v[178:181], v[220:223], v[106:109]
	v_mfma_f32_16x16x32_bf16 v[94:97], v[170:173], v[228:231], v[94:97]
	v_mfma_f32_16x16x32_bf16 v[90:93], v[178:181], v[228:231], v[90:93]
	v_mfma_f32_16x16x32_bf16 v[78:81], v[170:173], v[236:239], v[78:81]
	v_mfma_f32_16x16x32_bf16 v[74:77], v[178:181], v[236:239], v[74:77]
	v_mfma_f32_16x16x32_bf16 v[126:129], v[174:177], v[216:219], v[126:129]
	v_mfma_f32_16x16x32_bf16 v[122:125], v[182:185], v[216:219], v[122:125]
	v_mfma_f32_16x16x32_bf16 v[110:113], v[174:177], v[224:227], v[110:113]
	v_mfma_f32_16x16x32_bf16 v[106:109], v[182:185], v[224:227], v[106:109]
	v_mfma_f32_16x16x32_bf16 v[94:97], v[174:177], v[232:235], v[94:97]
	v_mfma_f32_16x16x32_bf16 v[90:93], v[182:185], v[232:235], v[90:93]
	v_mfma_f32_16x16x32_bf16 v[78:81], v[174:177], v[240:243], v[78:81]
	v_mfma_f32_16x16x32_bf16 v[74:77], v[182:185], v[240:243], v[74:77]
	v_mfma_f32_16x16x32_bf16 v[118:121], v[196:199], v[212:215], v[118:121]
	v_mfma_f32_16x16x32_bf16 v[114:117], v[204:207], v[212:215], v[114:117]
	v_mfma_f32_16x16x32_bf16 v[102:105], v[196:199], v[220:223], v[102:105]
	v_mfma_f32_16x16x32_bf16 v[98:101], v[204:207], v[220:223], v[98:101]
	v_mfma_f32_16x16x32_bf16 v[86:89], v[196:199], v[228:231], v[86:89]
	v_mfma_f32_16x16x32_bf16 v[82:85], v[204:207], v[228:231], v[82:85]
	v_mfma_f32_16x16x32_bf16 v[70:73], v[196:199], v[236:239], v[70:73]
	v_mfma_f32_16x16x32_bf16 v[66:69], v[204:207], v[236:239], v[66:69]
	v_mfma_f32_16x16x32_bf16 v[118:121], v[200:203], v[216:219], v[118:121]
	v_mfma_f32_16x16x32_bf16 v[114:117], v[208:211], v[216:219], v[114:117]
	v_mfma_f32_16x16x32_bf16 v[102:105], v[200:203], v[224:227], v[102:105]
	v_mfma_f32_16x16x32_bf16 v[98:101], v[208:211], v[224:227], v[98:101]
	v_mfma_f32_16x16x32_bf16 v[86:89], v[200:203], v[232:235], v[86:89]
	v_mfma_f32_16x16x32_bf16 v[82:85], v[208:211], v[232:235], v[82:85]
	v_mfma_f32_16x16x32_bf16 v[70:73], v[200:203], v[240:243], v[70:73]
	v_mfma_f32_16x16x32_bf16 v[66:69], v[208:211], v[240:243], v[66:69]
	s_barrier
; #define PG8_STAGE(bufoff, gbase, voff) do { _Pragma("unroll") for (int _i = 0; _i < 2; ++_i) \
;         __builtin_amdgcn_global_load_lds((const unsigned*)((const char*)(gbase) + (voff)[_i]), (PG8_LAS unsigned*)(lds + (bufoff) + ldsw + _i * 8192), 16, 0, 0); } while (0)
; #define PG8_LDA(dst, b, h) do { _Pragma("unroll") for (int m = 0; m < 4; ++m) _Pragma("unroll") for (int k = 0; k < 2; ++k) dst[m][k] = *(const PG8_LAS bf16x8*)(lds + PG8_SA(b, h) + aoff + m * 2048 + k * 1024); } while (0)
; #define PG8_MMA(ai, bj, At, Bt) do { __builtin_amdgcn_s_setprio(1); _Pragma("unroll") for (int m = 0; m < 4; ++m) _Pragma("unroll") for (int n = 0; n < 2; ++n) _Pragma("unroll") for (int k = 0; k < 2; ++k) \
;         acc[ai][bj][m][n] = __builtin_amdgcn_mfma_f32_16x16x32_bf16(Bt[n][k], At[m][k], acc[ai][bj][m][n], 0, 0, 0); __builtin_amdgcn_s_setprio(0); } while (0)
; #define PG8_WAIT_V(n) asm volatile("s_waitcnt vmcnt(" #n ")" ::: "memory")
; #define PG8_WAIT_L(n) asm volatile("s_waitcnt lgkmcnt(" #n ")" ::: "memory")
; #define PG8_BAR __builtin_amdgcn_s_barrier()
; #define PG8_SCHED __builtin_amdgcn_sched_barrier(0)
; template <class Epi, class Sched, bool ALIGN_EPI = false, bool SP2 = false>
; __device__ __forceinline__ void gemm_phase(PG8_LAS unsigned char* lds, const Gemm g, const Sched& S, const Epi& E) {
;     ...
;             PG8_LDA(At, 1, 1); PG8_STAGE(PG8_SB(1, 0), b3, voffB); PG8_STAGE(PG8_SB(1, 1), b3 + hstep, voffB); PG8_STAGE(PG8_SA(1, 0), a3, voffA);
;             PG8_WAIT_V(8); PG8_WAIT_L(0); PG8_BAR; PG8_MMA(1, 0, At, B0); PG8_MMA(1, 1, At, B1); PG8_BAR; PG8_SCHED;
	s_add_i32 s38, s61, s89
	v_lshl_add_u64 v[160:161], v[160:161], 0, s[34:35]
	s_mov_b32 m0, s38
	ds_read_b128 v[212:215], v149 offset:49152
	ds_read_b128 v[216:219], v149 offset:50176
	ds_read_b128 v[220:223], v149 offset:51200
	ds_read_b128 v[224:227], v149 offset:52224
	ds_read_b128 v[228:231], v149 offset:53248
	ds_read_b128 v[232:235], v149 offset:54272
	ds_read_b128 v[236:239], v149 offset:55296
	ds_read_b128 v[240:243], v149 offset:56320
	global_load_lds_dwordx4 v[160:161], off
	s_add_i32 m0, s38, 0x2000
	s_add_u32 s38, s50, 0x40080
	v_lshl_add_u64 v[160:161], v[244:245], 0, s[34:35]
	s_addc_u32 s39, s51, 0
	s_add_i32 s50, s72, s89
	global_load_lds_dwordx4 v[160:161], off
	s_mov_b32 m0, s50
	s_nop 0
	global_load_lds_dwordx4 v134, s[38:39]
	s_add_i32 m0, s50, 0x2000
	s_nop 0
	global_load_lds_dwordx4 v130, s[38:39]
	v_lshl_add_u64 v[160:161], v[246:247], 0, s[34:35]
	s_mov_b32 m0, s93
	s_nop 0
	global_load_lds_dwordx4 v[160:161], off
	v_lshl_add_u64 v[160:161], v[248:249], 0, s[34:35]
	s_mov_b32 m0, s94
	s_nop 0
	global_load_lds_dwordx4 v[160:161], off
	s_waitcnt vmcnt(8) lgkmcnt(0)
	s_barrier
	v_mfma_f32_16x16x32_bf16 v[62:65], v[170:173], v[212:215], v[62:65]
	v_mfma_f32_16x16x32_bf16 v[58:61], v[178:181], v[212:215], v[58:61]
	v_mfma_f32_16x16x32_bf16 v[46:49], v[170:173], v[220:223], v[46:49]
	v_mfma_f32_16x16x32_bf16 v[42:45], v[178:181], v[220:223], v[42:45]
	v_mfma_f32_16x16x32_bf16 v[28:31], v[170:173], v[228:231], v[28:31]
	v_mfma_f32_16x16x32_bf16 v[24:27], v[178:181], v[228:231], v[24:27]
	v_mfma_f32_16x16x32_bf16 v[12:15], v[170:173], v[236:239], v[12:15]
	v_mfma_f32_16x16x32_bf16 v[8:11], v[178:181], v[236:239], v[8:11]
	v_mfma_f32_16x16x32_bf16 v[62:65], v[174:177], v[216:219], v[62:65]
	v_mfma_f32_16x16x32_bf16 v[58:61], v[182:185], v[216:219], v[58:61]
	v_mfma_f32_16x16x32_bf16 v[46:49], v[174:177], v[224:227], v[46:49]
	v_mfma_f32_16x16x32_bf16 v[42:45], v[182:185], v[224:227], v[42:45]
	v_mfma_f32_16x16x32_bf16 v[28:31], v[174:177], v[232:235], v[28:31]
	v_mfma_f32_16x16x32_bf16 v[24:27], v[182:185], v[232:235], v[24:27]
	v_mfma_f32_16x16x32_bf16 v[12:15], v[174:177], v[240:243], v[12:15]
	v_mfma_f32_16x16x32_bf16 v[8:11], v[182:185], v[240:243], v[8:11]
	v_mfma_f32_16x16x32_bf16 v[54:57], v[196:199], v[212:215], v[54:57]
	v_mfma_f32_16x16x32_bf16 v[50:53], v[204:207], v[212:215], v[50:53]
	v_mfma_f32_16x16x32_bf16 v[38:41], v[196:199], v[220:223], v[38:41]
	v_mfma_f32_16x16x32_bf16 v[34:37], v[204:207], v[220:223], v[34:37]
	v_mfma_f32_16x16x32_bf16 v[20:23], v[196:199], v[228:231], v[20:23]
	v_mfma_f32_16x16x32_bf16 v[16:19], v[204:207], v[228:231], v[16:19]
	v_mfma_f32_16x16x32_bf16 v[4:7], v[196:199], v[236:239], v[4:7]
	v_mfma_f32_16x16x32_bf16 v[0:3], v[204:207], v[236:239], v[0:3]
	v_mfma_f32_16x16x32_bf16 v[54:57], v[200:203], v[216:219], v[54:57]
	v_mfma_f32_16x16x32_bf16 v[50:53], v[208:211], v[216:219], v[50:53]
	v_mfma_f32_16x16x32_bf16 v[38:41], v[200:203], v[224:227], v[38:41]
	v_mfma_f32_16x16x32_bf16 v[34:37], v[208:211], v[224:227], v[34:37]
	v_mfma_f32_16x16x32_bf16 v[20:23], v[200:203], v[232:235], v[20:23]
	v_mfma_f32_16x16x32_bf16 v[16:19], v[208:211], v[232:235], v[16:19]
	v_mfma_f32_16x16x32_bf16 v[4:7], v[200:203], v[240:243], v[4:7]
	v_mfma_f32_16x16x32_bf16 v[0:3], v[208:211], v[240:243], v[0:3]
	s_barrier
	s_add_i32 vcc_hi, vcc_hi, 2
	s_add_u32 s97, s97, 0x100
	s_addc_u32 vcc_lo, vcc_lo, 0
	s_add_u32 s48, s48, 0x100
	s_addc_u32 s49, s49, 0
	s_cmp_gt_u32 vcc_hi, 13
	s_cbranch_scc0 .LBB0_444
	s_and_b64 vcc, exec, s[4:5]
	s_cbranch_vccz .LBB0_447
	s_barrier

; #define PG8_STAGE(bufoff, gbase, voff) do { _Pragma("unroll") for (int _i = 0; _i < 2; ++_i) \
;         __builtin_amdgcn_global_load_lds((const unsigned*)((const char*)(gbase) + (voff)[_i]), (PG8_LAS unsigned*)(lds + (bufoff) + ldsw + _i * 8192), 16, 0, 0); } while (0)
; #define PG8_LDA(dst, b, h) do { _Pragma("unroll") for (int m = 0; m < 4; ++m) _Pragma("unroll") for (int k = 0; k < 2; ++k) dst[m][k] = *(const PG8_LAS bf16x8*)(lds + PG8_SA(b, h) + aoff + m * 2048 + k * 1024); } while (0)
; #define PG8_LDB(dst, b, h) do { _Pragma("unroll") for (int n = 0; n < 2; ++n) _Pragma("unroll") for (int k = 0; k < 2; ++k) dst[n][k] = *(const PG8_LAS bf16x8*)(lds + PG8_SB(b, h) + boff + n * 2048 + k * 1024); } while (0)
; #define PG8_MMA(ai, bj, At, Bt) do { __builtin_amdgcn_s_setprio(1); _Pragma("unroll") for (int m = 0; m < 4; ++m) _Pragma("unroll") for (int n = 0; n < 2; ++n) _Pragma("unroll") for (int k = 0; k < 2; ++k) \
;         acc[ai][bj][m][n] = __builtin_amdgcn_mfma_f32_16x16x32_bf16(Bt[n][k], At[m][k], acc[ai][bj][m][n], 0, 0, 0); __builtin_amdgcn_s_setprio(0); } while (0)
; #define PG8_WAIT_V(n) asm volatile("s_waitcnt vmcnt(" #n ")" ::: "memory")
; #define PG8_BAR __builtin_amdgcn_s_barrier()
; template <class Epi, class Sched, bool ALIGN_EPI = false, bool SP2 = false>
; __device__ __forceinline__ void gemm_phase(PG8_LAS unsigned char* lds, const Gemm g, const Sched& S, const Epi& E) {
;     ...
;         for (int t = 0; t < nt; t += 2) {
;             const bool last = (t == nt - 2);
;             const char* a1 = cA + (size_t)(t + 1) * kstep;
;             const char* a2 = last ? nA : cA + (size_t)(t + 2) * kstep; const char* b2 = last ? nB : cB + (size_t)(t + 2) * kstep;
;             const char* a3 = a2 + kstep; const char* b3 = b2 + kstep;
;             if (last && has_next) S.a_ready(nxt);
;             if constexpr (SP2) {
;             PG8_LDB(B0, 0, 0); PG8_LDB(B1, 0, 1); PG8_SCHED; PG8_LDA(At, 0, 0); PG8_STAGE(PG8_SA(1, 1), a1 + hstep, voffA);
;             PG8_WAIT_V(8); PG8_WAIT_L(0); PG8_BAR; PG8_MMA(0, 0, At, B0); PG8_MMA(0, 1, At, B1); PG8_BAR; PG8_SCHED;
;             PG8_LDA(At, 0, 1); PG8_STAGE(PG8_SB(0, 0), b2, voffB); PG8_STAGE(PG8_SB(0, 1), b2 + hstep, voffB); PG8_STAGE(PG8_SA(0, 0), a2, voffA);
;             PG8_WAIT_V(8); PG8_WAIT_L(0); PG8_BAR; PG8_MMA(1, 0, At, B0); PG8_MMA(1, 1, At, B1); PG8_BAR; PG8_SCHED;
.LBB0_546:
	s_add_i32 s48, s46, 2
	s_add_u32 s49, s44, 0x80
	s_addc_u32 s47, s45, 0
	s_add_i32 s61, 0, 0x10000
	s_cmp_eq_u32 s87, s46
	s_cselect_b32 s47, s43, s47
	s_cselect_b32 s46, s42, s49
	v_add_u32_e32 v149, s61, v146
	s_cselect_b32 s93, s77, s9
	s_cselect_b32 s92, s76, s0
	s_add_i32 s49, 0, 0x14000
	ds_read_b128 v[142:145], v149
	ds_read_b128 v[150:153], v149 offset:1024
	ds_read_b128 v[154:157], v149 offset:2048
	ds_read_b128 v[158:161], v149 offset:3072
	v_add_u32_e32 v149, s49, v146
	ds_read_b128 v[170:173], v149
	ds_read_b128 v[174:177], v149 offset:1024
	ds_read_b128 v[178:181], v149 offset:2048
	ds_read_b128 v[182:185], v149 offset:3072
	s_add_i32 m0, s78, 0xc000
	ds_read_b128 v[196:199], v148
	ds_read_b128 v[200:203], v148 offset:1024
	ds_read_b128 v[204:207], v148 offset:2048
	ds_read_b128 v[208:211], v148 offset:3072
	ds_read_b128 v[212:215], v148 offset:4096
	ds_read_b128 v[216:219], v148 offset:5120
	ds_read_b128 v[220:223], v148 offset:6144
	ds_read_b128 v[224:227], v148 offset:7168
	global_load_lds_dwordx4 v140, s[44:45]
	s_add_i32 m0, s78, 0xe000
	s_nop 0
	global_load_lds_dwordx4 v138, s[44:45]
	s_waitcnt vmcnt(8) lgkmcnt(0)
	s_barrier
	v_mfma_f32_16x16x32_bf16 v[126:129], v[142:145], v[196:199], v[126:129]
	v_mfma_f32_16x16x32_bf16 v[122:125], v[154:157], v[196:199], v[122:125]
	v_mfma_f32_16x16x32_bf16 v[110:113], v[142:145], v[204:207], v[110:113]
	v_mfma_f32_16x16x32_bf16 v[106:109], v[154:157], v[204:207], v[106:109]
	v_mfma_f32_16x16x32_bf16 v[94:97], v[142:145], v[212:215], v[94:97]
	v_mfma_f32_16x16x32_bf16 v[90:93], v[154:157], v[212:215], v[90:93]
	v_mfma_f32_16x16x32_bf16 v[78:81], v[142:145], v[220:223], v[78:81]
	v_mfma_f32_16x16x32_bf16 v[74:77], v[154:157], v[220:223], v[74:77]
	v_mfma_f32_16x16x32_bf16 v[126:129], v[150:153], v[200:203], v[126:129]
	v_mfma_f32_16x16x32_bf16 v[122:125], v[158:161], v[200:203], v[122:125]
	v_mfma_f32_16x16x32_bf16 v[110:113], v[150:153], v[208:211], v[110:113]
	v_mfma_f32_16x16x32_bf16 v[106:109], v[158:161], v[208:211], v[106:109]
	v_mfma_f32_16x16x32_bf16 v[94:97], v[150:153], v[216:219], v[94:97]
	v_mfma_f32_16x16x32_bf16 v[90:93], v[158:161], v[216:219], v[90:93]
	v_mfma_f32_16x16x32_bf16 v[78:81], v[150:153], v[224:227], v[78:81]
	v_mfma_f32_16x16x32_bf16 v[74:77], v[158:161], v[224:227], v[74:77]
	v_mfma_f32_16x16x32_bf16 v[118:121], v[170:173], v[196:199], v[118:121]
	v_mfma_f32_16x16x32_bf16 v[114:117], v[178:181], v[196:199], v[114:117]
	v_mfma_f32_16x16x32_bf16 v[102:105], v[170:173], v[204:207], v[102:105]
	v_mfma_f32_16x16x32_bf16 v[98:101], v[178:181], v[204:207], v[98:101]
	v_mfma_f32_16x16x32_bf16 v[86:89], v[170:173], v[212:215], v[86:89]
	v_mfma_f32_16x16x32_bf16 v[82:85], v[178:181], v[212:215], v[82:85]
	v_mfma_f32_16x16x32_bf16 v[70:73], v[170:173], v[220:223], v[70:73]
	v_mfma_f32_16x16x32_bf16 v[66:69], v[178:181], v[220:223], v[66:69]
	v_mfma_f32_16x16x32_bf16 v[118:121], v[174:177], v[200:203], v[118:121]
	v_mfma_f32_16x16x32_bf16 v[114:117], v[182:185], v[200:203], v[114:117]
	v_mfma_f32_16x16x32_bf16 v[102:105], v[174:177], v[208:211], v[102:105]
	v_mfma_f32_16x16x32_bf16 v[98:101], v[182:185], v[208:211], v[98:101]
	v_mfma_f32_16x16x32_bf16 v[86:89], v[174:177], v[216:219], v[86:89]
	v_mfma_f32_16x16x32_bf16 v[82:85], v[182:185], v[216:219], v[82:85]
	v_mfma_f32_16x16x32_bf16 v[70:73], v[174:177], v[224:227], v[70:73]
	v_mfma_f32_16x16x32_bf16 v[66:69], v[182:185], v[224:227], v[66:69]
	s_barrier
	s_add_i32 s61, s61, s51
	v_lshl_add_u64 v[228:229], s[92:93], 0, v[132:133]
	s_mov_b32 m0, s61
	ds_read_b128 v[196:199], v148 offset:16384
	ds_read_b128 v[200:203], v148 offset:17408
	ds_read_b128 v[204:207], v148 offset:18432
	ds_read_b128 v[208:211], v148 offset:19456
	ds_read_b128 v[212:215], v148 offset:20480
	ds_read_b128 v[216:219], v148 offset:21504
	ds_read_b128 v[220:223], v148 offset:22528
	ds_read_b128 v[224:227], v148 offset:23552
	global_load_lds_dwordx4 v[228:229], off
	s_add_i32 m0, s61, 0x2000
	v_lshl_add_u64 v[230:231], s[92:93], 0, v[136:137]
	s_add_u32 s92, s92, s8
	s_addc_u32 s93, s93, 0
	s_add_i32 s49, s49, s51
	global_load_lds_dwordx4 v[230:231], off
	v_lshl_add_u64 v[232:233], s[92:93], 0, v[132:133]
	s_mov_b32 m0, s49
	v_lshl_add_u64 v[234:235], s[92:93], 0, v[136:137]
	global_load_lds_dwordx4 v[232:233], off
	s_add_i32 m0, s49, 0x2000
	v_lshl_add_u64 v[236:237], s[46:47], 0, v[130:131]
	global_load_lds_dwordx4 v[234:235], off
	s_mov_b32 m0, s78
	v_lshl_add_u64 v[238:239], s[46:47], 0, v[134:135]
	global_load_lds_dwordx4 v[236:237], off
	s_mov_b32 m0, s79
	s_nop 0
	global_load_lds_dwordx4 v[238:239], off
	s_waitcnt vmcnt(8) lgkmcnt(0)
	s_barrier
; #define PG8_STAGE(bufoff, gbase, voff) do { _Pragma("unroll") for (int _i = 0; _i < 2; ++_i) \
;         __builtin_amdgcn_global_load_lds((const unsigned*)((const char*)(gbase) + (voff)[_i]), (PG8_LAS unsigned*)(lds + (bufoff) + ldsw + _i * 8192), 16, 0, 0); } while (0)
; #define PG8_LDA(dst, b, h) do { _Pragma("unroll") for (int m = 0; m < 4; ++m) _Pragma("unroll") for (int k = 0; k < 2; ++k) dst[m][k] = *(const PG8_LAS bf16x8*)(lds + PG8_SA(b, h) + aoff + m * 2048 + k * 1024); } while (0)
; #define PG8_LDB(dst, b, h) do { _Pragma("unroll") for (int n = 0; n < 2; ++n) _Pragma("unroll") for (int k = 0; k < 2; ++k) dst[n][k] = *(const PG8_LAS bf16x8*)(lds + PG8_SB(b, h) + boff + n * 2048 + k * 1024); } while (0)
; #define PG8_MMA(ai, bj, At, Bt) do { __builtin_amdgcn_s_setprio(1); _Pragma("unroll") for (int m = 0; m < 4; ++m) _Pragma("unroll") for (int n = 0; n < 2; ++n) _Pragma("unroll") for (int k = 0; k < 2; ++k) \
;         acc[ai][bj][m][n] = __builtin_amdgcn_mfma_f32_16x16x32_bf16(Bt[n][k], At[m][k], acc[ai][bj][m][n], 0, 0, 0); __builtin_amdgcn_s_setprio(0); } while (0)
; #define PG8_WAIT_V(n) asm volatile("s_waitcnt vmcnt(" #n ")" ::: "memory")
; #define PG8_WAIT_L(n) asm volatile("s_waitcnt lgkmcnt(" #n ")" ::: "memory")
; #define PG8_BAR __builtin_amdgcn_s_barrier()
; #define PG8_SCHED __builtin_amdgcn_sched_barrier(0)
; template <class Epi, class Sched, bool ALIGN_EPI = false, bool SP2 = false>
; __device__ __forceinline__ void gemm_phase(PG8_LAS unsigned char* lds, const Gemm g, const Sched& S, const Epi& E) {
;     ...
;             PG8_WAIT_V(8); PG8_WAIT_L(0); PG8_BAR; PG8_MMA(1, 0, At, B0); PG8_MMA(1, 1, At, B1); PG8_BAR; PG8_SCHED;
;             PG8_LDB(B0, 1, 0); PG8_LDB(B1, 1, 1); PG8_SCHED; PG8_LDA(At, 1, 0); PG8_STAGE(PG8_SA(0, 1), a2 + hstep, voffA);
;             PG8_WAIT_V(8); PG8_WAIT_L(0); PG8_BAR; PG8_MMA(0, 0, At, B0); PG8_MMA(0, 1, At, B1); PG8_BAR; PG8_SCHED;
	v_mfma_f32_16x16x32_bf16 v[62:65], v[142:145], v[196:199], v[62:65]
	v_mfma_f32_16x16x32_bf16 v[58:61], v[154:157], v[196:199], v[58:61]
	v_mfma_f32_16x16x32_bf16 v[46:49], v[142:145], v[204:207], v[46:49]
	v_mfma_f32_16x16x32_bf16 v[42:45], v[154:157], v[204:207], v[42:45]
	v_mfma_f32_16x16x32_bf16 v[28:31], v[142:145], v[212:215], v[28:31]
	v_mfma_f32_16x16x32_bf16 v[24:27], v[154:157], v[212:215], v[24:27]
	v_mfma_f32_16x16x32_bf16 v[12:15], v[142:145], v[220:223], v[12:15]
	v_mfma_f32_16x16x32_bf16 v[8:11], v[154:157], v[220:223], v[8:11]
	v_mfma_f32_16x16x32_bf16 v[62:65], v[150:153], v[200:203], v[62:65]
	v_mfma_f32_16x16x32_bf16 v[58:61], v[158:161], v[200:203], v[58:61]
	v_mfma_f32_16x16x32_bf16 v[46:49], v[150:153], v[208:211], v[46:49]
	v_mfma_f32_16x16x32_bf16 v[42:45], v[158:161], v[208:211], v[42:45]
	v_mfma_f32_16x16x32_bf16 v[28:31], v[150:153], v[216:219], v[28:31]
	v_mfma_f32_16x16x32_bf16 v[24:27], v[158:161], v[216:219], v[24:27]
	v_mfma_f32_16x16x32_bf16 v[12:15], v[150:153], v[224:227], v[12:15]
	v_mfma_f32_16x16x32_bf16 v[8:11], v[158:161], v[224:227], v[8:11]
	v_mfma_f32_16x16x32_bf16 v[54:57], v[170:173], v[196:199], v[54:57]
	v_mfma_f32_16x16x32_bf16 v[50:53], v[178:181], v[196:199], v[50:53]
	v_mfma_f32_16x16x32_bf16 v[38:41], v[170:173], v[204:207], v[38:41]
	v_mfma_f32_16x16x32_bf16 v[34:37], v[178:181], v[204:207], v[34:37]
	v_mfma_f32_16x16x32_bf16 v[20:23], v[170:173], v[212:215], v[20:23]
	v_mfma_f32_16x16x32_bf16 v[16:19], v[178:181], v[212:215], v[16:19]
	v_mfma_f32_16x16x32_bf16 v[4:7], v[170:173], v[220:223], v[4:7]
	v_mfma_f32_16x16x32_bf16 v[0:3], v[178:181], v[220:223], v[0:3]
	v_mfma_f32_16x16x32_bf16 v[54:57], v[174:177], v[200:203], v[54:57]
	v_mfma_f32_16x16x32_bf16 v[50:53], v[182:185], v[200:203], v[50:53]
	v_mfma_f32_16x16x32_bf16 v[38:41], v[174:177], v[208:211], v[38:41]
	v_mfma_f32_16x16x32_bf16 v[34:37], v[182:185], v[208:211], v[34:37]
	v_mfma_f32_16x16x32_bf16 v[20:23], v[174:177], v[216:219], v[20:23]
	v_mfma_f32_16x16x32_bf16 v[16:19], v[182:185], v[216:219], v[16:19]
	v_mfma_f32_16x16x32_bf16 v[4:7], v[174:177], v[224:227], v[4:7]
	v_mfma_f32_16x16x32_bf16 v[0:3], v[182:185], v[224:227], v[0:3]
	s_barrier
	s_add_i32 s49, 0, 0x18000
	v_add_u32_e32 v149, s49, v146
	s_add_i32 s61, 0, 0x1c000
	ds_read_b128 v[142:145], v149
	ds_read_b128 v[150:153], v149 offset:1024
	ds_read_b128 v[154:157], v149 offset:2048
	ds_read_b128 v[158:161], v149 offset:3072
	v_add_u32_e32 v149, s61, v146
	ds_read_b128 v[170:173], v149
	ds_read_b128 v[174:177], v149 offset:1024
	ds_read_b128 v[178:181], v149 offset:2048
	ds_read_b128 v[182:185], v149 offset:3072
	s_add_u32 s46, s46, s8
	s_addc_u32 s47, s47, 0
	s_mov_b32 m0, s80
	ds_read_b128 v[196:199], v148 offset:32768
	ds_read_b128 v[200:203], v148 offset:33792
	ds_read_b128 v[204:207], v148 offset:34816
	ds_read_b128 v[208:211], v148 offset:35840
	ds_read_b128 v[212:215], v148 offset:36864
	ds_read_b128 v[216:219], v148 offset:37888
	ds_read_b128 v[220:223], v148 offset:38912
	ds_read_b128 v[224:227], v148 offset:39936
	global_load_lds_dwordx4 v130, s[46:47]
	s_mov_b32 m0, s81
	s_nop 0
	global_load_lds_dwordx4 v134, s[46:47]
	s_waitcnt vmcnt(8) lgkmcnt(0)
	s_barrier
	v_mfma_f32_16x16x32_bf16 v[126:129], v[142:145], v[196:199], v[126:129]
	v_mfma_f32_16x16x32_bf16 v[122:125], v[154:157], v[196:199], v[122:125]
	v_mfma_f32_16x16x32_bf16 v[110:113], v[142:145], v[204:207], v[110:113]
	v_mfma_f32_16x16x32_bf16 v[106:109], v[154:157], v[204:207], v[106:109]
	v_mfma_f32_16x16x32_bf16 v[94:97], v[142:145], v[212:215], v[94:97]
	v_mfma_f32_16x16x32_bf16 v[90:93], v[154:157], v[212:215], v[90:93]
	v_mfma_f32_16x16x32_bf16 v[78:81], v[142:145], v[220:223], v[78:81]
	v_mfma_f32_16x16x32_bf16 v[74:77], v[154:157], v[220:223], v[74:77]
	v_mfma_f32_16x16x32_bf16 v[126:129], v[150:153], v[200:203], v[126:129]
	v_mfma_f32_16x16x32_bf16 v[122:125], v[158:161], v[200:203], v[122:125]
	v_mfma_f32_16x16x32_bf16 v[110:113], v[150:153], v[208:211], v[110:113]
	v_mfma_f32_16x16x32_bf16 v[106:109], v[158:161], v[208:211], v[106:109]
	v_mfma_f32_16x16x32_bf16 v[94:97], v[150:153], v[216:219], v[94:97]
	v_mfma_f32_16x16x32_bf16 v[90:93], v[158:161], v[216:219], v[90:93]
	v_mfma_f32_16x16x32_bf16 v[78:81], v[150:153], v[224:227], v[78:81]
	v_mfma_f32_16x16x32_bf16 v[74:77], v[158:161], v[224:227], v[74:77]
	v_mfma_f32_16x16x32_bf16 v[118:121], v[170:173], v[196:199], v[118:121]
	v_mfma_f32_16x16x32_bf16 v[114:117], v[178:181], v[196:199], v[114:117]
	v_mfma_f32_16x16x32_bf16 v[102:105], v[170:173], v[204:207], v[102:105]
	v_mfma_f32_16x16x32_bf16 v[98:101], v[178:181], v[204:207], v[98:101]
	v_mfma_f32_16x16x32_bf16 v[86:89], v[170:173], v[212:215], v[86:89]
	v_mfma_f32_16x16x32_bf16 v[82:85], v[178:181], v[212:215], v[82:85]
	v_mfma_f32_16x16x32_bf16 v[70:73], v[170:173], v[220:223], v[70:73]
	v_mfma_f32_16x16x32_bf16 v[66:69], v[178:181], v[220:223], v[66:69]
	v_mfma_f32_16x16x32_bf16 v[118:121], v[174:177], v[200:203], v[118:121]
	v_mfma_f32_16x16x32_bf16 v[114:117], v[182:185], v[200:203], v[114:117]
	v_mfma_f32_16x16x32_bf16 v[102:105], v[174:177], v[208:211], v[102:105]
	v_mfma_f32_16x16x32_bf16 v[98:101], v[182:185], v[208:211], v[98:101]
	v_mfma_f32_16x16x32_bf16 v[86:89], v[174:177], v[216:219], v[86:89]
	v_mfma_f32_16x16x32_bf16 v[82:85], v[182:185], v[216:219], v[82:85]
	v_mfma_f32_16x16x32_bf16 v[70:73], v[174:177], v[224:227], v[70:73]
	v_mfma_f32_16x16x32_bf16 v[66:69], v[182:185], v[224:227], v[66:69]
	s_barrier
; #define PG8_STAGE(bufoff, gbase, voff) do { _Pragma("unroll") for (int _i = 0; _i < 2; ++_i) \
;         __builtin_amdgcn_global_load_lds((const unsigned*)((const char*)(gbase) + (voff)[_i]), (PG8_LAS unsigned*)(lds + (bufoff) + ldsw + _i * 8192), 16, 0, 0); } while (0)
; #define PG8_LDA(dst, b, h) do { _Pragma("unroll") for (int m = 0; m < 4; ++m) _Pragma("unroll") for (int k = 0; k < 2; ++k) dst[m][k] = *(const PG8_LAS bf16x8*)(lds + PG8_SA(b, h) + aoff + m * 2048 + k * 1024); } while (0)
; #define PG8_MMA(ai, bj, At, Bt) do { __builtin_amdgcn_s_setprio(1); _Pragma("unroll") for (int m = 0; m < 4; ++m) _Pragma("unroll") for (int n = 0; n < 2; ++n) _Pragma("unroll") for (int k = 0; k < 2; ++k) \
;         acc[ai][bj][m][n] = __builtin_amdgcn_mfma_f32_16x16x32_bf16(Bt[n][k], At[m][k], acc[ai][bj][m][n], 0, 0, 0); __builtin_amdgcn_s_setprio(0); } while (0)
; #define PG8_WAIT_V(n) asm volatile("s_waitcnt vmcnt(" #n ")" ::: "memory")
; #define PG8_WAIT_L(n) asm volatile("s_waitcnt lgkmcnt(" #n ")" ::: "memory")
; #define PG8_BAR __builtin_amdgcn_s_barrier()
; #define PG8_SCHED __builtin_amdgcn_sched_barrier(0)
; template <class Epi, class Sched, bool ALIGN_EPI = false, bool SP2 = false>
; __device__ __forceinline__ void gemm_phase(PG8_LAS unsigned char* lds, const Gemm g, const Sched& S, const Epi& E) {
;     ...
;             PG8_LDA(At, 1, 1); PG8_STAGE(PG8_SB(1, 0), b3, voffB); PG8_STAGE(PG8_SB(1, 1), b3 + hstep, voffB); PG8_STAGE(PG8_SA(1, 0), a3, voffA);
;             PG8_WAIT_V(8); PG8_WAIT_L(0); PG8_BAR; PG8_MMA(1, 0, At, B0); PG8_MMA(1, 1, At, B1); PG8_BAR; PG8_SCHED;
	s_add_i32 s46, s49, s51
	v_lshl_add_u64 v[228:229], v[228:229], 0, s[34:35]
	s_mov_b32 m0, s46
	ds_read_b128 v[196:199], v148 offset:49152
	ds_read_b128 v[200:203], v148 offset:50176
	ds_read_b128 v[204:207], v148 offset:51200
	ds_read_b128 v[208:211], v148 offset:52224
	ds_read_b128 v[212:215], v148 offset:53248
	ds_read_b128 v[216:219], v148 offset:54272
	ds_read_b128 v[220:223], v148 offset:55296
	ds_read_b128 v[224:227], v148 offset:56320
	global_load_lds_dwordx4 v[228:229], off
	v_lshl_add_u64 v[228:229], v[230:231], 0, s[34:35]
	s_add_i32 m0, s46, 0x2000
	s_add_i32 s46, s61, s51
	global_load_lds_dwordx4 v[228:229], off
	v_lshl_add_u64 v[228:229], v[232:233], 0, s[34:35]
	s_mov_b32 m0, s46
	s_nop 0
	global_load_lds_dwordx4 v[228:229], off
	v_lshl_add_u64 v[228:229], v[234:235], 0, s[34:35]
	s_add_i32 m0, s46, 0x2000
	s_nop 0
	global_load_lds_dwordx4 v[228:229], off
	v_lshl_add_u64 v[228:229], v[236:237], 0, s[34:35]
	s_mov_b32 m0, s83
	s_nop 0
	global_load_lds_dwordx4 v[228:229], off
	v_lshl_add_u64 v[228:229], v[238:239], 0, s[34:35]
	s_mov_b32 m0, s84
	s_nop 0
	global_load_lds_dwordx4 v[228:229], off
	s_waitcnt vmcnt(8) lgkmcnt(0)
	s_barrier
	v_mfma_f32_16x16x32_bf16 v[62:65], v[142:145], v[196:199], v[62:65]
	v_mfma_f32_16x16x32_bf16 v[58:61], v[154:157], v[196:199], v[58:61]
	v_mfma_f32_16x16x32_bf16 v[46:49], v[142:145], v[204:207], v[46:49]
	v_mfma_f32_16x16x32_bf16 v[42:45], v[154:157], v[204:207], v[42:45]
	v_mfma_f32_16x16x32_bf16 v[28:31], v[142:145], v[212:215], v[28:31]
	v_mfma_f32_16x16x32_bf16 v[24:27], v[154:157], v[212:215], v[24:27]
	v_mfma_f32_16x16x32_bf16 v[12:15], v[142:145], v[220:223], v[12:15]
	v_mfma_f32_16x16x32_bf16 v[8:11], v[154:157], v[220:223], v[8:11]
	v_mfma_f32_16x16x32_bf16 v[62:65], v[150:153], v[200:203], v[62:65]
	v_mfma_f32_16x16x32_bf16 v[58:61], v[158:161], v[200:203], v[58:61]
	v_mfma_f32_16x16x32_bf16 v[46:49], v[150:153], v[208:211], v[46:49]
	v_mfma_f32_16x16x32_bf16 v[42:45], v[158:161], v[208:211], v[42:45]
	v_mfma_f32_16x16x32_bf16 v[28:31], v[150:153], v[216:219], v[28:31]
	v_mfma_f32_16x16x32_bf16 v[24:27], v[158:161], v[216:219], v[24:27]
	v_mfma_f32_16x16x32_bf16 v[12:15], v[150:153], v[224:227], v[12:15]
	v_mfma_f32_16x16x32_bf16 v[8:11], v[158:161], v[224:227], v[8:11]
	v_mfma_f32_16x16x32_bf16 v[54:57], v[170:173], v[196:199], v[54:57]
	v_mfma_f32_16x16x32_bf16 v[50:53], v[178:181], v[196:199], v[50:53]
	v_mfma_f32_16x16x32_bf16 v[38:41], v[170:173], v[204:207], v[38:41]
	v_mfma_f32_16x16x32_bf16 v[34:37], v[178:181], v[204:207], v[34:37]
	v_mfma_f32_16x16x32_bf16 v[20:23], v[170:173], v[212:215], v[20:23]
	v_mfma_f32_16x16x32_bf16 v[16:19], v[178:181], v[212:215], v[16:19]
	v_mfma_f32_16x16x32_bf16 v[4:7], v[170:173], v[220:223], v[4:7]
	v_mfma_f32_16x16x32_bf16 v[0:3], v[178:181], v[220:223], v[0:3]
	v_mfma_f32_16x16x32_bf16 v[54:57], v[174:177], v[200:203], v[54:57]
	v_mfma_f32_16x16x32_bf16 v[50:53], v[182:185], v[200:203], v[50:53]
	v_mfma_f32_16x16x32_bf16 v[38:41], v[174:177], v[208:211], v[38:41]
	v_mfma_f32_16x16x32_bf16 v[34:37], v[182:185], v[208:211], v[34:37]
	v_mfma_f32_16x16x32_bf16 v[20:23], v[174:177], v[216:219], v[20:23]
	v_mfma_f32_16x16x32_bf16 v[16:19], v[182:185], v[216:219], v[16:19]
	v_mfma_f32_16x16x32_bf16 v[4:7], v[174:177], v[224:227], v[4:7]
	v_mfma_f32_16x16x32_bf16 v[0:3], v[182:185], v[224:227], v[0:3]
	s_barrier
	s_add_u32 s0, s0, 0x100
	s_addc_u32 s9, s9, 0
	s_add_u32 s44, s44, 0x100
	s_addc_u32 s45, s45, 0
	s_cmp_ge_u32 s48, s85
	s_mov_b32 s46, s48
	s_cbranch_scc0 .LBB0_546
	s_and_b64 vcc, exec, s[40:41]
	s_cbranch_vccz .LBB0_549
	s_barrier

; #define PG8_STAGE(bufoff, gbase, voff) do { _Pragma("unroll") for (int _i = 0; _i < 2; ++_i) \
;         __builtin_amdgcn_global_load_lds((const unsigned*)((const char*)(gbase) + (voff)[_i]), (PG8_LAS unsigned*)(lds + (bufoff) + ldsw + _i * 8192), 16, 0, 0); } while (0)
; #define PG8_LDA(dst, b, h) do { _Pragma("unroll") for (int m = 0; m < 4; ++m) _Pragma("unroll") for (int k = 0; k < 2; ++k) dst[m][k] = *(const PG8_LAS bf16x8*)(lds + PG8_SA(b, h) + aoff + m * 2048 + k * 1024); } while (0)
; #define PG8_LDB(dst, b, h) do { _Pragma("unroll") for (int n = 0; n < 2; ++n) _Pragma("unroll") for (int k = 0; k < 2; ++k) dst[n][k] = *(const PG8_LAS bf16x8*)(lds + PG8_SB(b, h) + boff + n * 2048 + k * 1024); } while (0)
; #define PG8_MMA(ai, bj, At, Bt) do { __builtin_amdgcn_s_setprio(1); _Pragma("unroll") for (int m = 0; m < 4; ++m) _Pragma("unroll") for (int n = 0; n < 2; ++n) _Pragma("unroll") for (int k = 0; k < 2; ++k) \
;         acc[ai][bj][m][n] = __builtin_amdgcn_mfma_f32_16x16x32_bf16(Bt[n][k], At[m][k], acc[ai][bj][m][n], 0, 0, 0); __builtin_amdgcn_s_setprio(0); } while (0)
; #define PG8_WAIT_V(n) asm volatile("s_waitcnt vmcnt(" #n ")" ::: "memory")
; #define PG8_BAR __builtin_amdgcn_s_barrier()
; template <class Epi, class Sched, bool ALIGN_EPI = false, bool SP2 = false>
; __device__ __forceinline__ void gemm_phase(PG8_LAS unsigned char* lds, const Gemm g, const Sched& S, const Epi& E) {
;     ...
;         for (int t = 0; t < nt; t += 2) {
;             const bool last = (t == nt - 2);
;             const char* a1 = cA + (size_t)(t + 1) * kstep;
;             const char* a2 = last ? nA : cA + (size_t)(t + 2) * kstep; const char* b2 = last ? nB : cB + (size_t)(t + 2) * kstep;
;             const char* a3 = a2 + kstep; const char* b3 = b2 + kstep;
;             if (last && has_next) S.a_ready(nxt);
;             if constexpr (SP2) {
;             PG8_LDB(B0, 0, 0); PG8_LDB(B1, 0, 1); PG8_SCHED; PG8_LDA(At, 0, 0); PG8_STAGE(PG8_SA(1, 1), a1 + hstep, voffA);
;             PG8_WAIT_V(8); PG8_WAIT_L(0); PG8_BAR; PG8_MMA(0, 0, At, B0); PG8_MMA(0, 1, At, B1); PG8_BAR; PG8_SCHED;
;             PG8_LDA(At, 0, 1); PG8_STAGE(PG8_SB(0, 0), b2, voffB); PG8_STAGE(PG8_SB(0, 1), b2 + hstep, voffB); PG8_STAGE(PG8_SA(0, 0), a2, voffA);
;             PG8_WAIT_V(8); PG8_WAIT_L(0); PG8_BAR; PG8_MMA(1, 0, At, B0); PG8_MMA(1, 1, At, B1); PG8_BAR; PG8_SCHED;
.LBB0_580:
	s_add_u32 s48, s46, 0xfffc0080
	s_addc_u32 s49, s47, -1
	s_add_i32 s82, 0, 0x10000
	s_cmp_eq_u32 s81, 12
	s_cselect_b32 s51, s9, s49
	s_cselect_b32 s50, s66, s48
	v_add_u32_e32 v151, s82, v145
	s_cselect_b32 s49, s7, s80
	s_cselect_b32 s48, s67, s79
	s_add_i32 s84, 0, 0x14000
	ds_read_b128 v[170:173], v151
	ds_read_b128 v[174:177], v151 offset:1024
	ds_read_b128 v[178:181], v151 offset:2048
	ds_read_b128 v[182:185], v151 offset:3072
	v_add_u32_e32 v151, s84, v145
	ds_read_b128 v[196:199], v151
	ds_read_b128 v[200:203], v151 offset:1024
	ds_read_b128 v[204:207], v151 offset:2048
	ds_read_b128 v[208:211], v151 offset:3072
	s_add_i32 m0, s71, 0xc000
	ds_read_b128 v[212:215], v149
	ds_read_b128 v[216:219], v149 offset:1024
	ds_read_b128 v[220:223], v149 offset:2048
	ds_read_b128 v[224:227], v149 offset:3072
	ds_read_b128 v[228:231], v149 offset:4096
	ds_read_b128 v[232:235], v149 offset:5120
	ds_read_b128 v[236:239], v149 offset:6144
	ds_read_b128 v[240:243], v149 offset:7168
	global_load_lds_dwordx4 v142, s[46:47]
	s_add_i32 m0, s71, 0xe000
	s_nop 0
	global_load_lds_dwordx4 v140, s[46:47]
	s_waitcnt vmcnt(8) lgkmcnt(0)
	s_barrier
	v_mfma_f32_16x16x32_bf16 v[126:129], v[170:173], v[212:215], v[126:129]
	v_mfma_f32_16x16x32_bf16 v[122:125], v[178:181], v[212:215], v[122:125]
	v_mfma_f32_16x16x32_bf16 v[110:113], v[170:173], v[220:223], v[110:113]
	v_mfma_f32_16x16x32_bf16 v[106:109], v[178:181], v[220:223], v[106:109]
	v_mfma_f32_16x16x32_bf16 v[94:97], v[170:173], v[228:231], v[94:97]
	v_mfma_f32_16x16x32_bf16 v[90:93], v[178:181], v[228:231], v[90:93]
	v_mfma_f32_16x16x32_bf16 v[78:81], v[170:173], v[236:239], v[78:81]
	v_mfma_f32_16x16x32_bf16 v[74:77], v[178:181], v[236:239], v[74:77]
	v_mfma_f32_16x16x32_bf16 v[126:129], v[174:177], v[216:219], v[126:129]
	v_mfma_f32_16x16x32_bf16 v[122:125], v[182:185], v[216:219], v[122:125]
	v_mfma_f32_16x16x32_bf16 v[110:113], v[174:177], v[224:227], v[110:113]
	v_mfma_f32_16x16x32_bf16 v[106:109], v[182:185], v[224:227], v[106:109]
	v_mfma_f32_16x16x32_bf16 v[94:97], v[174:177], v[232:235], v[94:97]
	v_mfma_f32_16x16x32_bf16 v[90:93], v[182:185], v[232:235], v[90:93]
	v_mfma_f32_16x16x32_bf16 v[78:81], v[174:177], v[240:243], v[78:81]
	v_mfma_f32_16x16x32_bf16 v[74:77], v[182:185], v[240:243], v[74:77]
	v_mfma_f32_16x16x32_bf16 v[118:121], v[196:199], v[212:215], v[118:121]
	v_mfma_f32_16x16x32_bf16 v[114:117], v[204:207], v[212:215], v[114:117]
	v_mfma_f32_16x16x32_bf16 v[102:105], v[196:199], v[220:223], v[102:105]
	v_mfma_f32_16x16x32_bf16 v[98:101], v[204:207], v[220:223], v[98:101]
	v_mfma_f32_16x16x32_bf16 v[86:89], v[196:199], v[228:231], v[86:89]
	v_mfma_f32_16x16x32_bf16 v[82:85], v[204:207], v[228:231], v[82:85]
	v_mfma_f32_16x16x32_bf16 v[70:73], v[196:199], v[236:239], v[70:73]
	v_mfma_f32_16x16x32_bf16 v[66:69], v[204:207], v[236:239], v[66:69]
	v_mfma_f32_16x16x32_bf16 v[118:121], v[200:203], v[216:219], v[118:121]
	v_mfma_f32_16x16x32_bf16 v[114:117], v[208:211], v[216:219], v[114:117]
	v_mfma_f32_16x16x32_bf16 v[102:105], v[200:203], v[224:227], v[102:105]
	v_mfma_f32_16x16x32_bf16 v[98:101], v[208:211], v[224:227], v[98:101]
	v_mfma_f32_16x16x32_bf16 v[86:89], v[200:203], v[232:235], v[86:89]
	v_mfma_f32_16x16x32_bf16 v[82:85], v[208:211], v[232:235], v[82:85]
	v_mfma_f32_16x16x32_bf16 v[70:73], v[200:203], v[240:243], v[70:73]
	v_mfma_f32_16x16x32_bf16 v[66:69], v[208:211], v[240:243], v[66:69]
	s_barrier
	s_add_i32 s82, s82, s69
	v_lshl_add_u64 v[160:161], s[48:49], 0, v[134:135]
	s_mov_b32 m0, s82
	ds_read_b128 v[212:215], v149 offset:16384
	ds_read_b128 v[216:219], v149 offset:17408
	ds_read_b128 v[220:223], v149 offset:18432
	ds_read_b128 v[224:227], v149 offset:19456
	ds_read_b128 v[228:231], v149 offset:20480
	ds_read_b128 v[232:235], v149 offset:21504
	ds_read_b128 v[236:239], v149 offset:22528
	ds_read_b128 v[240:243], v149 offset:23552
	global_load_lds_dwordx4 v[160:161], off
	s_add_i32 m0, s82, 0x2000
	s_add_u32 s82, s48, 0x40000
	v_lshl_add_u64 v[244:245], s[48:49], 0, v[130:131]
	s_addc_u32 s83, s49, 0
	s_add_i32 s84, s84, s69
	global_load_lds_dwordx4 v[244:245], off
	s_mov_b32 m0, s84
	v_lshl_add_u64 v[248:249], s[50:51], 0, v[132:133]
	global_load_lds_dwordx4 v134, s[82:83]
	s_add_i32 m0, s84, 0x2000
	s_nop 0
	global_load_lds_dwordx4 v130, s[82:83]
	v_lshl_add_u64 v[246:247], s[50:51], 0, v[136:137]
	s_mov_b32 m0, s71
	s_nop 0
	global_load_lds_dwordx4 v[246:247], off
	s_mov_b32 m0, s72
	s_nop 0
	global_load_lds_dwordx4 v[248:249], off
	s_waitcnt vmcnt(8) lgkmcnt(0)
	s_barrier
; #define PG8_STAGE(bufoff, gbase, voff) do { _Pragma("unroll") for (int _i = 0; _i < 2; ++_i) \
;         __builtin_amdgcn_global_load_lds((const unsigned*)((const char*)(gbase) + (voff)[_i]), (PG8_LAS unsigned*)(lds + (bufoff) + ldsw + _i * 8192), 16, 0, 0); } while (0)
; #define PG8_LDA(dst, b, h) do { _Pragma("unroll") for (int m = 0; m < 4; ++m) _Pragma("unroll") for (int k = 0; k < 2; ++k) dst[m][k] = *(const PG8_LAS bf16x8*)(lds + PG8_SA(b, h) + aoff + m * 2048 + k * 1024); } while (0)
; #define PG8_LDB(dst, b, h) do { _Pragma("unroll") for (int n = 0; n < 2; ++n) _Pragma("unroll") for (int k = 0; k < 2; ++k) dst[n][k] = *(const PG8_LAS bf16x8*)(lds + PG8_SB(b, h) + boff + n * 2048 + k * 1024); } while (0)
; #define PG8_MMA(ai, bj, At, Bt) do { __builtin_amdgcn_s_setprio(1); _Pragma("unroll") for (int m = 0; m < 4; ++m) _Pragma("unroll") for (int n = 0; n < 2; ++n) _Pragma("unroll") for (int k = 0; k < 2; ++k) \
;         acc[ai][bj][m][n] = __builtin_amdgcn_mfma_f32_16x16x32_bf16(Bt[n][k], At[m][k], acc[ai][bj][m][n], 0, 0, 0); __builtin_amdgcn_s_setprio(0); } while (0)
; #define PG8_WAIT_V(n) asm volatile("s_waitcnt vmcnt(" #n ")" ::: "memory")
; #define PG8_WAIT_L(n) asm volatile("s_waitcnt lgkmcnt(" #n ")" ::: "memory")
; #define PG8_BAR __builtin_amdgcn_s_barrier()
; #define PG8_SCHED __builtin_amdgcn_sched_barrier(0)
; template <class Epi, class Sched, bool ALIGN_EPI = false, bool SP2 = false>
; __device__ __forceinline__ void gemm_phase(PG8_LAS unsigned char* lds, const Gemm g, const Sched& S, const Epi& E) {
;     ...
;             PG8_WAIT_V(8); PG8_WAIT_L(0); PG8_BAR; PG8_MMA(1, 0, At, B0); PG8_MMA(1, 1, At, B1); PG8_BAR; PG8_SCHED;
;             PG8_LDB(B0, 1, 0); PG8_LDB(B1, 1, 1); PG8_SCHED; PG8_LDA(At, 1, 0); PG8_STAGE(PG8_SA(0, 1), a2 + hstep, voffA);
;             PG8_WAIT_V(8); PG8_WAIT_L(0); PG8_BAR; PG8_MMA(0, 0, At, B0); PG8_MMA(0, 1, At, B1); PG8_BAR; PG8_SCHED;
	v_mfma_f32_16x16x32_bf16 v[62:65], v[170:173], v[212:215], v[62:65]
	v_mfma_f32_16x16x32_bf16 v[58:61], v[178:181], v[212:215], v[58:61]
	v_mfma_f32_16x16x32_bf16 v[46:49], v[170:173], v[220:223], v[46:49]
	v_mfma_f32_16x16x32_bf16 v[42:45], v[178:181], v[220:223], v[42:45]
	v_mfma_f32_16x16x32_bf16 v[28:31], v[170:173], v[228:231], v[28:31]
	v_mfma_f32_16x16x32_bf16 v[24:27], v[178:181], v[228:231], v[24:27]
	v_mfma_f32_16x16x32_bf16 v[12:15], v[170:173], v[236:239], v[12:15]
	v_mfma_f32_16x16x32_bf16 v[8:11], v[178:181], v[236:239], v[8:11]
	v_mfma_f32_16x16x32_bf16 v[62:65], v[174:177], v[216:219], v[62:65]
	v_mfma_f32_16x16x32_bf16 v[58:61], v[182:185], v[216:219], v[58:61]
	v_mfma_f32_16x16x32_bf16 v[46:49], v[174:177], v[224:227], v[46:49]
	v_mfma_f32_16x16x32_bf16 v[42:45], v[182:185], v[224:227], v[42:45]
	v_mfma_f32_16x16x32_bf16 v[28:31], v[174:177], v[232:235], v[28:31]
	v_mfma_f32_16x16x32_bf16 v[24:27], v[182:185], v[232:235], v[24:27]
	v_mfma_f32_16x16x32_bf16 v[12:15], v[174:177], v[240:243], v[12:15]
	v_mfma_f32_16x16x32_bf16 v[8:11], v[182:185], v[240:243], v[8:11]
	v_mfma_f32_16x16x32_bf16 v[54:57], v[196:199], v[212:215], v[54:57]
	v_mfma_f32_16x16x32_bf16 v[50:53], v[204:207], v[212:215], v[50:53]
	v_mfma_f32_16x16x32_bf16 v[38:41], v[196:199], v[220:223], v[38:41]
	v_mfma_f32_16x16x32_bf16 v[34:37], v[204:207], v[220:223], v[34:37]
	v_mfma_f32_16x16x32_bf16 v[20:23], v[196:199], v[228:231], v[20:23]
	v_mfma_f32_16x16x32_bf16 v[16:19], v[204:207], v[228:231], v[16:19]
	v_mfma_f32_16x16x32_bf16 v[4:7], v[196:199], v[236:239], v[4:7]
	v_mfma_f32_16x16x32_bf16 v[0:3], v[204:207], v[236:239], v[0:3]
	v_mfma_f32_16x16x32_bf16 v[54:57], v[200:203], v[216:219], v[54:57]
	v_mfma_f32_16x16x32_bf16 v[50:53], v[208:211], v[216:219], v[50:53]
	v_mfma_f32_16x16x32_bf16 v[38:41], v[200:203], v[224:227], v[38:41]
	v_mfma_f32_16x16x32_bf16 v[34:37], v[208:211], v[224:227], v[34:37]
	v_mfma_f32_16x16x32_bf16 v[20:23], v[200:203], v[232:235], v[20:23]
	v_mfma_f32_16x16x32_bf16 v[16:19], v[208:211], v[232:235], v[16:19]
	v_mfma_f32_16x16x32_bf16 v[4:7], v[200:203], v[240:243], v[4:7]
	v_mfma_f32_16x16x32_bf16 v[0:3], v[208:211], v[240:243], v[0:3]
	s_barrier
	s_add_i32 s82, 0, 0x18000
	v_add_u32_e32 v151, s82, v145
	s_add_i32 s83, 0, 0x1c000
	ds_read_b128 v[170:173], v151
	ds_read_b128 v[174:177], v151 offset:1024
	ds_read_b128 v[178:181], v151 offset:2048
	ds_read_b128 v[182:185], v151 offset:3072
	v_add_u32_e32 v151, s83, v145
	ds_read_b128 v[196:199], v151
	ds_read_b128 v[200:203], v151 offset:1024
	ds_read_b128 v[204:207], v151 offset:2048
	ds_read_b128 v[208:211], v151 offset:3072
	s_add_u32 s50, s50, 0x40000
	s_addc_u32 s51, s51, 0
	s_mov_b32 m0, s73
	ds_read_b128 v[212:215], v149 offset:32768
	ds_read_b128 v[216:219], v149 offset:33792
	ds_read_b128 v[220:223], v149 offset:34816
	ds_read_b128 v[224:227], v149 offset:35840
	ds_read_b128 v[228:231], v149 offset:36864
	ds_read_b128 v[232:235], v149 offset:37888
	ds_read_b128 v[236:239], v149 offset:38912
	ds_read_b128 v[240:243], v149 offset:39936
	global_load_lds_dwordx4 v136, s[50:51]
	s_mov_b32 m0, s76
	s_nop 0
	global_load_lds_dwordx4 v132, s[50:51]
	s_waitcnt vmcnt(8) lgkmcnt(0)
	s_barrier
	v_mfma_f32_16x16x32_bf16 v[126:129], v[170:173], v[212:215], v[126:129]
	v_mfma_f32_16x16x32_bf16 v[122:125], v[178:181], v[212:215], v[122:125]
	v_mfma_f32_16x16x32_bf16 v[110:113], v[170:173], v[220:223], v[110:113]
	v_mfma_f32_16x16x32_bf16 v[106:109], v[178:181], v[220:223], v[106:109]
	v_mfma_f32_16x16x32_bf16 v[94:97], v[170:173], v[228:231], v[94:97]
	v_mfma_f32_16x16x32_bf16 v[90:93], v[178:181], v[228:231], v[90:93]
	v_mfma_f32_16x16x32_bf16 v[78:81], v[170:173], v[236:239], v[78:81]
	v_mfma_f32_16x16x32_bf16 v[74:77], v[178:181], v[236:239], v[74:77]
	v_mfma_f32_16x16x32_bf16 v[126:129], v[174:177], v[216:219], v[126:129]
	v_mfma_f32_16x16x32_bf16 v[122:125], v[182:185], v[216:219], v[122:125]
	v_mfma_f32_16x16x32_bf16 v[110:113], v[174:177], v[224:227], v[110:113]
	v_mfma_f32_16x16x32_bf16 v[106:109], v[182:185], v[224:227], v[106:109]
	v_mfma_f32_16x16x32_bf16 v[94:97], v[174:177], v[232:235], v[94:97]
	v_mfma_f32_16x16x32_bf16 v[90:93], v[182:185], v[232:235], v[90:93]
	v_mfma_f32_16x16x32_bf16 v[78:81], v[174:177], v[240:243], v[78:81]
	v_mfma_f32_16x16x32_bf16 v[74:77], v[182:185], v[240:243], v[74:77]
	v_mfma_f32_16x16x32_bf16 v[118:121], v[196:199], v[212:215], v[118:121]
	v_mfma_f32_16x16x32_bf16 v[114:117], v[204:207], v[212:215], v[114:117]
	v_mfma_f32_16x16x32_bf16 v[102:105], v[196:199], v[220:223], v[102:105]
	v_mfma_f32_16x16x32_bf16 v[98:101], v[204:207], v[220:223], v[98:101]
	v_mfma_f32_16x16x32_bf16 v[86:89], v[196:199], v[228:231], v[86:89]
	v_mfma_f32_16x16x32_bf16 v[82:85], v[204:207], v[228:231], v[82:85]
	v_mfma_f32_16x16x32_bf16 v[70:73], v[196:199], v[236:239], v[70:73]
	v_mfma_f32_16x16x32_bf16 v[66:69], v[204:207], v[236:239], v[66:69]
	v_mfma_f32_16x16x32_bf16 v[118:121], v[200:203], v[216:219], v[118:121]
	v_mfma_f32_16x16x32_bf16 v[114:117], v[208:211], v[216:219], v[114:117]
	v_mfma_f32_16x16x32_bf16 v[102:105], v[200:203], v[224:227], v[102:105]
	v_mfma_f32_16x16x32_bf16 v[98:101], v[208:211], v[224:227], v[98:101]
	v_mfma_f32_16x16x32_bf16 v[86:89], v[200:203], v[232:235], v[86:89]
	v_mfma_f32_16x16x32_bf16 v[82:85], v[208:211], v[232:235], v[82:85]
	v_mfma_f32_16x16x32_bf16 v[70:73], v[200:203], v[240:243], v[70:73]
	v_mfma_f32_16x16x32_bf16 v[66:69], v[208:211], v[240:243], v[66:69]
	s_barrier
; #define PG8_STAGE(bufoff, gbase, voff) do { _Pragma("unroll") for (int _i = 0; _i < 2; ++_i) \
;         __builtin_amdgcn_global_load_lds((const unsigned*)((const char*)(gbase) + (voff)[_i]), (PG8_LAS unsigned*)(lds + (bufoff) + ldsw + _i * 8192), 16, 0, 0); } while (0)
; #define PG8_LDA(dst, b, h) do { _Pragma("unroll") for (int m = 0; m < 4; ++m) _Pragma("unroll") for (int k = 0; k < 2; ++k) dst[m][k] = *(const PG8_LAS bf16x8*)(lds + PG8_SA(b, h) + aoff + m * 2048 + k * 1024); } while (0)
; #define PG8_MMA(ai, bj, At, Bt) do { __builtin_amdgcn_s_setprio(1); _Pragma("unroll") for (int m = 0; m < 4; ++m) _Pragma("unroll") for (int n = 0; n < 2; ++n) _Pragma("unroll") for (int k = 0; k < 2; ++k) \
;         acc[ai][bj][m][n] = __builtin_amdgcn_mfma_f32_16x16x32_bf16(Bt[n][k], At[m][k], acc[ai][bj][m][n], 0, 0, 0); __builtin_amdgcn_s_setprio(0); } while (0)
; #define PG8_WAIT_V(n) asm volatile("s_waitcnt vmcnt(" #n ")" ::: "memory")
; #define PG8_WAIT_L(n) asm volatile("s_waitcnt lgkmcnt(" #n ")" ::: "memory")
; #define PG8_BAR __builtin_amdgcn_s_barrier()
; #define PG8_SCHED __builtin_amdgcn_sched_barrier(0)
; template <class Epi, class Sched, bool ALIGN_EPI = false, bool SP2 = false>
; __device__ __forceinline__ void gemm_phase(PG8_LAS unsigned char* lds, const Gemm g, const Sched& S, const Epi& E) {
;     ...
;             PG8_LDA(At, 1, 1); PG8_STAGE(PG8_SB(1, 0), b3, voffB); PG8_STAGE(PG8_SB(1, 1), b3 + hstep, voffB); PG8_STAGE(PG8_SA(1, 0), a3, voffA);
;             PG8_WAIT_V(8); PG8_WAIT_L(0); PG8_BAR; PG8_MMA(1, 0, At, B0); PG8_MMA(1, 1, At, B1); PG8_BAR; PG8_SCHED;
	s_add_i32 s50, s82, s69
	v_lshl_add_u64 v[160:161], v[160:161], 0, s[34:35]
	s_mov_b32 m0, s50
	ds_read_b128 v[212:215], v149 offset:49152
	ds_read_b128 v[216:219], v149 offset:50176
	ds_read_b128 v[220:223], v149 offset:51200
	ds_read_b128 v[224:227], v149 offset:52224
	ds_read_b128 v[228:231], v149 offset:53248
	ds_read_b128 v[232:235], v149 offset:54272
	ds_read_b128 v[236:239], v149 offset:55296
	ds_read_b128 v[240:243], v149 offset:56320
	global_load_lds_dwordx4 v[160:161], off
	s_add_i32 m0, s50, 0x2000
	s_add_u32 s48, s48, 0x40080
	v_lshl_add_u64 v[160:161], v[244:245], 0, s[34:35]
	s_addc_u32 s49, s49, 0
	s_add_i32 s50, s83, s69
	global_load_lds_dwordx4 v[160:161], off
	s_mov_b32 m0, s50
	s_nop 0
	global_load_lds_dwordx4 v134, s[48:49]
	s_add_i32 m0, s50, 0x2000
	s_nop 0
	global_load_lds_dwordx4 v130, s[48:49]
	v_lshl_add_u64 v[160:161], v[246:247], 0, s[34:35]
	s_mov_b32 m0, s77
	s_nop 0
	global_load_lds_dwordx4 v[160:161], off
	v_lshl_add_u64 v[160:161], v[248:249], 0, s[34:35]
	s_mov_b32 m0, s78
	s_nop 0
	global_load_lds_dwordx4 v[160:161], off
	s_waitcnt vmcnt(8) lgkmcnt(0)
	s_barrier
	v_mfma_f32_16x16x32_bf16 v[62:65], v[170:173], v[212:215], v[62:65]
	v_mfma_f32_16x16x32_bf16 v[58:61], v[178:181], v[212:215], v[58:61]
	v_mfma_f32_16x16x32_bf16 v[46:49], v[170:173], v[220:223], v[46:49]
	v_mfma_f32_16x16x32_bf16 v[42:45], v[178:181], v[220:223], v[42:45]
	v_mfma_f32_16x16x32_bf16 v[28:31], v[170:173], v[228:231], v[28:31]
	v_mfma_f32_16x16x32_bf16 v[24:27], v[178:181], v[228:231], v[24:27]
	v_mfma_f32_16x16x32_bf16 v[12:15], v[170:173], v[236:239], v[12:15]
	v_mfma_f32_16x16x32_bf16 v[8:11], v[178:181], v[236:239], v[8:11]
	v_mfma_f32_16x16x32_bf16 v[62:65], v[174:177], v[216:219], v[62:65]
	v_mfma_f32_16x16x32_bf16 v[58:61], v[182:185], v[216:219], v[58:61]
	v_mfma_f32_16x16x32_bf16 v[46:49], v[174:177], v[224:227], v[46:49]
	v_mfma_f32_16x16x32_bf16 v[42:45], v[182:185], v[224:227], v[42:45]
	v_mfma_f32_16x16x32_bf16 v[28:31], v[174:177], v[232:235], v[28:31]
	v_mfma_f32_16x16x32_bf16 v[24:27], v[182:185], v[232:235], v[24:27]
	v_mfma_f32_16x16x32_bf16 v[12:15], v[174:177], v[240:243], v[12:15]
	v_mfma_f32_16x16x32_bf16 v[8:11], v[182:185], v[240:243], v[8:11]
	v_mfma_f32_16x16x32_bf16 v[54:57], v[196:199], v[212:215], v[54:57]
	v_mfma_f32_16x16x32_bf16 v[50:53], v[204:207], v[212:215], v[50:53]
	v_mfma_f32_16x16x32_bf16 v[38:41], v[196:199], v[220:223], v[38:41]
	v_mfma_f32_16x16x32_bf16 v[34:37], v[204:207], v[220:223], v[34:37]
	v_mfma_f32_16x16x32_bf16 v[20:23], v[196:199], v[228:231], v[20:23]
	v_mfma_f32_16x16x32_bf16 v[16:19], v[204:207], v[228:231], v[16:19]
	v_mfma_f32_16x16x32_bf16 v[4:7], v[196:199], v[236:239], v[4:7]
	v_mfma_f32_16x16x32_bf16 v[0:3], v[204:207], v[236:239], v[0:3]
	v_mfma_f32_16x16x32_bf16 v[54:57], v[200:203], v[216:219], v[54:57]
	v_mfma_f32_16x16x32_bf16 v[50:53], v[208:211], v[216:219], v[50:53]
	v_mfma_f32_16x16x32_bf16 v[38:41], v[200:203], v[224:227], v[38:41]
	v_mfma_f32_16x16x32_bf16 v[34:37], v[208:211], v[224:227], v[34:37]
	v_mfma_f32_16x16x32_bf16 v[20:23], v[200:203], v[232:235], v[20:23]
	v_mfma_f32_16x16x32_bf16 v[16:19], v[208:211], v[232:235], v[16:19]
	v_mfma_f32_16x16x32_bf16 v[4:7], v[200:203], v[240:243], v[4:7]
	v_mfma_f32_16x16x32_bf16 v[0:3], v[208:211], v[240:243], v[0:3]
	s_barrier
	s_add_i32 s81, s81, 2
	s_add_u32 s79, s79, 0x100
	s_addc_u32 s80, s80, 0
	s_add_u32 s46, s46, 0x100
	s_addc_u32 s47, s47, 0
	s_cmp_gt_u32 s81, 13
	s_cbranch_scc0 .LBB0_580
	s_and_b64 vcc, exec, s[4:5]
	s_cbranch_vccz .LBB0_583
	s_barrier
